# P4 fused gates: xb A-tile read once for the three sigmoid-gate GEMMs (48-step K loop, A double buffer + B ring), bf16-packed gates as baseline, three branch GEMM passes with gated accumulate; trampoli
# speedup vs baseline: 1.1518x; 1.0274x over previous
.Ltr_222:
	s_branch .LBB0_222

.LBB0_918:
	s_lshl_b64 s[54:55], s[38:39], 11
	s_add_u32 s100, s0, s54
	s_addc_u32 s101, s1, s55
	s_add_u32 s52, s100, 0x200000
	s_addc_u32 s53, s101, 0
	s_add_u32 s54, s100, 0x400000
	s_addc_u32 s55, s101, 0
	s_mov_b64 s[98:99], s[42:43]
	v_mov_b32_e32 v251, v199
	v_lshrrev_b32_e32 v0, 3, v251
	v_and_b32_e32 v248, 7, v251
	v_bfe_u32 v249, v251, 4, 3
	v_xor_b32_e32 v248, v248, v249
	v_lshlrev_b32_e32 v248, 4, v248
	v_lshl_or_b32 v244, v0, 11, v248
	v_add_u32_e32 v245, 0x10000, v244
	v_add_u32_e32 v246, 0x20000, v244
	v_add_u32_e32 v247, 0x30000, v244
	v_lshlrev_b32_e32 v0, 4, v251
	s_nop 0
	v_readfirstlane_b32 s30, v0
	v_and_b32_e32 v248, 31, v251
	v_bfe_u32 v250, v251, 5, 1
	v_bfe_u32 v249, v251, 1, 3
	v_xor_b32_e32 v250, v250, v249
	v_lshlrev_b32_e32 v250, 4, v250
	v_lshlrev_b32_e32 v0, 7, v248
	v_bfe_u32 v248, v251, 7, 1
	v_bfe_u32 v249, v251, 6, 1
	v_lshl_or_b32 v248, v248, 13, v0
	v_lshl_or_b32 v249, v249, 13, v0
	s_barrier
	s_add_u32 m0, s30, 0x0
	v_mov_b32_e32 v2, 0
	global_load_lds_dwordx4 v244, s[98:99]
	s_add_u32 m0, s30, 0x1000
	v_mov_b32_e32 v3, 0
	global_load_lds_dwordx4 v245, s[98:99]
	s_add_u32 m0, s30, 0x2000
	v_mov_b32_e32 v4, 0
	global_load_lds_dwordx4 v246, s[98:99]
	s_add_u32 m0, s30, 0x3000
	v_mov_b32_e32 v5, 0
	global_load_lds_dwordx4 v247, s[98:99]
	s_add_u32 s98, s98, 0x80
	s_addc_u32 s99, s99, 0
	s_add_u32 m0, s30, 0x8000
	v_mov_b32_e32 v6, 0
	global_load_lds_dwordx4 v244, s[100:101]
	s_add_u32 m0, s30, 0x9000
	v_mov_b32_e32 v7, 0
	global_load_lds_dwordx4 v245, s[100:101]
	s_add_u32 m0, s30, 0xa000
	v_mov_b32_e32 v8, 0
	global_load_lds_dwordx4 v246, s[100:101]
	s_add_u32 m0, s30, 0xb000
	v_mov_b32_e32 v9, 0
	global_load_lds_dwordx4 v247, s[100:101]
	s_add_u32 s100, s100, 0x80
	s_addc_u32 s101, s101, 0
	s_add_u32 m0, s30, 0x4000
	v_mov_b32_e32 v10, 0
	global_load_lds_dwordx4 v244, s[98:99]
	s_add_u32 m0, s30, 0x5000
	v_mov_b32_e32 v11, 0
	global_load_lds_dwordx4 v245, s[98:99]
	s_add_u32 m0, s30, 0x6000
	v_mov_b32_e32 v12, 0
	global_load_lds_dwordx4 v246, s[98:99]
	s_add_u32 m0, s30, 0x7000
	v_mov_b32_e32 v13, 0
	global_load_lds_dwordx4 v247, s[98:99]
	s_add_u32 s98, s98, 0x80
	s_addc_u32 s99, s99, 0
	s_add_u32 m0, s30, 0xc000
	v_mov_b32_e32 v14, 0
	global_load_lds_dwordx4 v244, s[52:53]
	s_add_u32 m0, s30, 0xd000
	v_mov_b32_e32 v15, 0
	global_load_lds_dwordx4 v245, s[52:53]
	s_add_u32 m0, s30, 0xe000
	v_mov_b32_e32 v16, 0
	global_load_lds_dwordx4 v246, s[52:53]
	s_add_u32 m0, s30, 0xf000
	v_mov_b32_e32 v17, 0
	global_load_lds_dwordx4 v247, s[52:53]
	s_add_u32 s52, s52, 0x80
	s_addc_u32 s53, s53, 0
	v_mov_b32_e32 v18, 0
	v_mov_b32_e32 v19, 0
	v_mov_b32_e32 v20, 0
	v_mov_b32_e32 v21, 0
	v_mov_b32_e32 v22, 0
	v_mov_b32_e32 v23, 0
	v_mov_b32_e32 v24, 0
	v_mov_b32_e32 v25, 0
	v_mov_b32_e32 v26, 0
	v_mov_b32_e32 v27, 0
	v_mov_b32_e32 v28, 0
	v_mov_b32_e32 v29, 0
	v_mov_b32_e32 v30, 0
	v_mov_b32_e32 v31, 0
	v_mov_b32_e32 v32, 0
	v_mov_b32_e32 v33, 0
	v_mov_b32_e32 v34, 0
	v_mov_b32_e32 v35, 0
	v_mov_b32_e32 v36, 0
	v_mov_b32_e32 v37, 0
	v_mov_b32_e32 v38, 0
	v_mov_b32_e32 v39, 0
	v_mov_b32_e32 v40, 0
	v_mov_b32_e32 v41, 0
	v_mov_b32_e32 v42, 0
	v_mov_b32_e32 v43, 0
	v_mov_b32_e32 v44, 0
	v_mov_b32_e32 v45, 0
	v_mov_b32_e32 v46, 0
	v_mov_b32_e32 v47, 0
	v_mov_b32_e32 v48, 0
	v_mov_b32_e32 v49, 0
	v_mov_b32_e32 v50, 0
	v_mov_b32_e32 v51, 0
	v_mov_b32_e32 v52, 0
	v_mov_b32_e32 v53, 0
	v_mov_b32_e32 v54, 0
	v_mov_b32_e32 v55, 0
	v_mov_b32_e32 v56, 0
	v_mov_b32_e32 v57, 0
	v_mov_b32_e32 v58, 0
	v_mov_b32_e32 v59, 0
	v_mov_b32_e32 v60, 0
	v_mov_b32_e32 v61, 0
	v_mov_b32_e32 v62, 0
	v_mov_b32_e32 v63, 0
	v_mov_b32_e32 v64, 0
	v_mov_b32_e32 v65, 0
	v_mov_b32_e32 v66, 0
	v_mov_b32_e32 v67, 0
	v_mov_b32_e32 v68, 0
	v_mov_b32_e32 v69, 0
	v_mov_b32_e32 v70, 0
	v_mov_b32_e32 v71, 0
	v_mov_b32_e32 v72, 0
	v_mov_b32_e32 v73, 0
	v_mov_b32_e32 v74, 0
	v_mov_b32_e32 v75, 0
	v_mov_b32_e32 v76, 0
	v_mov_b32_e32 v77, 0
	v_mov_b32_e32 v78, 0
	v_mov_b32_e32 v79, 0
	v_mov_b32_e32 v80, 0
	v_mov_b32_e32 v81, 0
	v_mov_b32_e32 v82, 0
	v_mov_b32_e32 v83, 0
	v_mov_b32_e32 v84, 0
	v_mov_b32_e32 v85, 0
	v_mov_b32_e32 v86, 0
	v_mov_b32_e32 v87, 0
	v_mov_b32_e32 v88, 0
	v_mov_b32_e32 v89, 0
	v_mov_b32_e32 v90, 0
	v_mov_b32_e32 v91, 0
	v_mov_b32_e32 v92, 0
	v_mov_b32_e32 v93, 0
	v_mov_b32_e32 v94, 0
	v_mov_b32_e32 v95, 0
	v_mov_b32_e32 v96, 0
	v_mov_b32_e32 v97, 0
	v_mov_b32_e32 v98, 0
	v_mov_b32_e32 v99, 0
	v_mov_b32_e32 v100, 0
	v_mov_b32_e32 v101, 0
	v_mov_b32_e32 v102, 0
	v_mov_b32_e32 v103, 0
	v_mov_b32_e32 v104, 0
	v_mov_b32_e32 v105, 0
	v_mov_b32_e32 v106, 0
	v_mov_b32_e32 v107, 0
	v_mov_b32_e32 v108, 0
	v_mov_b32_e32 v109, 0
	v_mov_b32_e32 v110, 0
	v_mov_b32_e32 v111, 0
	v_mov_b32_e32 v112, 0
	v_mov_b32_e32 v113, 0
	v_mov_b32_e32 v114, 0
	v_mov_b32_e32 v115, 0
	v_mov_b32_e32 v116, 0
	v_mov_b32_e32 v117, 0
	v_mov_b32_e32 v118, 0
	v_mov_b32_e32 v119, 0
	v_mov_b32_e32 v120, 0
	v_mov_b32_e32 v121, 0
	v_mov_b32_e32 v122, 0
	v_mov_b32_e32 v123, 0
	v_mov_b32_e32 v124, 0
	v_mov_b32_e32 v125, 0
	v_mov_b32_e32 v126, 0
	v_mov_b32_e32 v127, 0
	v_mov_b32_e32 v128, 0
	v_mov_b32_e32 v129, 0
	v_mov_b32_e32 v130, 0
	v_mov_b32_e32 v131, 0
	v_mov_b32_e32 v132, 0
	v_mov_b32_e32 v133, 0
	v_mov_b32_e32 v134, 0
	v_mov_b32_e32 v135, 0
	v_mov_b32_e32 v136, 0
	v_mov_b32_e32 v137, 0
	v_mov_b32_e32 v138, 0
	v_mov_b32_e32 v139, 0
	v_mov_b32_e32 v140, 0
	v_mov_b32_e32 v141, 0
	v_mov_b32_e32 v142, 0
	v_mov_b32_e32 v143, 0
	v_mov_b32_e32 v144, 0
	v_mov_b32_e32 v145, 0
	v_mov_b32_e32 v146, 0
	v_mov_b32_e32 v147, 0
	v_mov_b32_e32 v148, 0
	v_mov_b32_e32 v149, 0
	v_mov_b32_e32 v150, 0
	v_mov_b32_e32 v151, 0
	v_mov_b32_e32 v152, 0
	v_mov_b32_e32 v153, 0
	v_mov_b32_e32 v154, 0
	v_mov_b32_e32 v155, 0
	v_mov_b32_e32 v156, 0
	v_mov_b32_e32 v157, 0
	v_mov_b32_e32 v158, 0
	v_mov_b32_e32 v159, 0
	v_mov_b32_e32 v160, 0
	v_mov_b32_e32 v161, 0
	v_mov_b32_e32 v162, 0
	v_mov_b32_e32 v163, 0
	v_mov_b32_e32 v164, 0
	v_mov_b32_e32 v165, 0
	v_mov_b32_e32 v166, 0
	v_mov_b32_e32 v167, 0
	v_mov_b32_e32 v168, 0
	v_mov_b32_e32 v169, 0
	v_mov_b32_e32 v170, 0
	v_mov_b32_e32 v171, 0
	v_mov_b32_e32 v172, 0
	v_mov_b32_e32 v173, 0
	v_mov_b32_e32 v174, 0
	v_mov_b32_e32 v175, 0
	v_mov_b32_e32 v176, 0
	v_mov_b32_e32 v177, 0
	v_mov_b32_e32 v178, 0
	v_mov_b32_e32 v179, 0
	v_mov_b32_e32 v180, 0
	v_mov_b32_e32 v181, 0
	v_mov_b32_e32 v182, 0
	v_mov_b32_e32 v183, 0
	v_mov_b32_e32 v184, 0
	v_mov_b32_e32 v185, 0
	v_mov_b32_e32 v186, 0
	v_mov_b32_e32 v187, 0
	v_mov_b32_e32 v188, 0
	v_mov_b32_e32 v189, 0
	v_mov_b32_e32 v190, 0
	v_mov_b32_e32 v191, 0
	v_mov_b32_e32 v192, 0
	v_mov_b32_e32 v193, 0
	s_waitcnt vmcnt(8)
	s_barrier
	v_add_u32_e32 v224, v250, v248
	v_add_u32_e32 v236, v250, v249
	ds_read_b128 v[220:223], v224
	ds_read_b128 v[224:227], v224 offset:4096
	ds_read_b128 v[232:235], v236 offset:32768
	ds_read_b128 v[236:239], v236 offset:36864
	s_mov_b32 s51, 7
.Lp4f_gloop:
	s_waitcnt lgkmcnt(0)
	v_mfma_f32_32x32x16_bf16 v[50:65], v[232:235], v[220:223], v[50:65]
	v_xor_b32_e32 v240, 0x20, v250
	v_add_u32_e32 v228, v240, v248
	v_add_u32_e32 v240, v240, v249
	v_mfma_f32_32x32x16_bf16 v[34:49], v[236:239], v[220:223], v[34:49]
	ds_read_b128 v[220:223], v228
	ds_read_b128 v[228:231], v228 offset:4096
	v_mfma_f32_32x32x16_bf16 v[18:33], v[232:235], v[224:227], v[18:33]
	ds_read_b128 v[232:235], v240 offset:32768
	ds_read_b128 v[240:243], v240 offset:36864
	v_mfma_f32_32x32x16_bf16 v[2:17], v[236:239], v[224:227], v[2:17]
	s_waitcnt lgkmcnt(0)
	v_mfma_f32_32x32x16_bf16 v[50:65], v[232:235], v[220:223], v[50:65]
	v_xor_b32_e32 v236, 0x40, v250
	v_add_u32_e32 v224, v236, v248
	v_add_u32_e32 v236, v236, v249
	v_mfma_f32_32x32x16_bf16 v[34:49], v[240:243], v[220:223], v[34:49]
	ds_read_b128 v[220:223], v224
	ds_read_b128 v[224:227], v224 offset:4096
	v_mfma_f32_32x32x16_bf16 v[18:33], v[232:235], v[228:231], v[18:33]
	ds_read_b128 v[232:235], v236 offset:32768
	ds_read_b128 v[236:239], v236 offset:36864
	v_mfma_f32_32x32x16_bf16 v[2:17], v[240:243], v[228:231], v[2:17]
	s_waitcnt lgkmcnt(0)
	v_mfma_f32_32x32x16_bf16 v[50:65], v[232:235], v[220:223], v[50:65]
	v_xor_b32_e32 v240, 0x60, v250
	v_add_u32_e32 v228, v240, v248
	v_add_u32_e32 v240, v240, v249
	v_mfma_f32_32x32x16_bf16 v[34:49], v[236:239], v[220:223], v[34:49]
	ds_read_b128 v[220:223], v228
	ds_read_b128 v[228:231], v228 offset:4096
	v_mfma_f32_32x32x16_bf16 v[18:33], v[232:235], v[224:227], v[18:33]
	ds_read_b128 v[232:235], v240 offset:32768
	ds_read_b128 v[240:243], v240 offset:36864
	v_mfma_f32_32x32x16_bf16 v[2:17], v[236:239], v[224:227], v[2:17]
	s_waitcnt vmcnt(0) lgkmcnt(0)
	s_barrier
	s_waitcnt lgkmcnt(0)
	v_mfma_f32_32x32x16_bf16 v[50:65], v[232:235], v[220:223], v[50:65]
	v_mov_b32_e32 v236, v250
	v_add_u32_e32 v224, v236, v248
	v_add_u32_e32 v236, v236, v249
	v_mfma_f32_32x32x16_bf16 v[34:49], v[240:243], v[220:223], v[34:49]
	ds_read_b128 v[220:223], v224
	ds_read_b128 v[224:227], v224 offset:4096
	s_add_u32 m0, s30, 0x8000
	s_nop 0
	global_load_lds_dwordx4 v244, s[54:55]
	s_add_u32 m0, s30, 0x9000
	s_nop 0
	global_load_lds_dwordx4 v245, s[54:55]
	v_mfma_f32_32x32x16_bf16 v[18:33], v[232:235], v[228:231], v[18:33]
	ds_read_b128 v[232:235], v236 offset:49152
	ds_read_b128 v[236:239], v236 offset:53248
	s_add_u32 m0, s30, 0xa000
	s_nop 0
	global_load_lds_dwordx4 v246, s[54:55]
	s_add_u32 m0, s30, 0xb000
	s_nop 0
	global_load_lds_dwordx4 v247, s[54:55]
	v_mfma_f32_32x32x16_bf16 v[2:17], v[240:243], v[228:231], v[2:17]
	s_add_u32 s54, s54, 0x80
	s_addc_u32 s55, s55, 0
	s_waitcnt lgkmcnt(0)
	v_mfma_f32_32x32x16_bf16 v[114:129], v[232:235], v[220:223], v[114:129]
	v_xor_b32_e32 v240, 0x20, v250
	v_add_u32_e32 v228, v240, v248
	v_add_u32_e32 v240, v240, v249
	v_mfma_f32_32x32x16_bf16 v[98:113], v[236:239], v[220:223], v[98:113]
	ds_read_b128 v[220:223], v228
	ds_read_b128 v[228:231], v228 offset:4096
	v_mfma_f32_32x32x16_bf16 v[82:97], v[232:235], v[224:227], v[82:97]
	ds_read_b128 v[232:235], v240 offset:49152
	ds_read_b128 v[240:243], v240 offset:53248
	v_mfma_f32_32x32x16_bf16 v[66:81], v[236:239], v[224:227], v[66:81]
	s_waitcnt lgkmcnt(0)
	v_mfma_f32_32x32x16_bf16 v[114:129], v[232:235], v[220:223], v[114:129]
	v_xor_b32_e32 v236, 0x40, v250
	v_add_u32_e32 v224, v236, v248
	v_add_u32_e32 v236, v236, v249
	v_mfma_f32_32x32x16_bf16 v[98:113], v[240:243], v[220:223], v[98:113]
	ds_read_b128 v[220:223], v224
	ds_read_b128 v[224:227], v224 offset:4096
	v_mfma_f32_32x32x16_bf16 v[82:97], v[232:235], v[228:231], v[82:97]
	ds_read_b128 v[232:235], v236 offset:49152
	ds_read_b128 v[236:239], v236 offset:53248
	v_mfma_f32_32x32x16_bf16 v[66:81], v[240:243], v[228:231], v[66:81]
	s_waitcnt lgkmcnt(0)
	v_mfma_f32_32x32x16_bf16 v[114:129], v[232:235], v[220:223], v[114:129]
	v_xor_b32_e32 v240, 0x60, v250
	v_add_u32_e32 v228, v240, v248
	v_add_u32_e32 v240, v240, v249
	v_mfma_f32_32x32x16_bf16 v[98:113], v[236:239], v[220:223], v[98:113]
	ds_read_b128 v[220:223], v228
	ds_read_b128 v[228:231], v228 offset:4096
	v_mfma_f32_32x32x16_bf16 v[82:97], v[232:235], v[224:227], v[82:97]
	ds_read_b128 v[232:235], v240 offset:49152
	ds_read_b128 v[240:243], v240 offset:53248
	v_mfma_f32_32x32x16_bf16 v[66:81], v[236:239], v[224:227], v[66:81]
	s_waitcnt vmcnt(0) lgkmcnt(0)
	s_barrier
	s_waitcnt lgkmcnt(0)
	v_mfma_f32_32x32x16_bf16 v[114:129], v[232:235], v[220:223], v[114:129]
	v_mov_b32_e32 v236, v250
	v_add_u32_e32 v224, v236, v248
	v_add_u32_e32 v236, v236, v249
	v_mfma_f32_32x32x16_bf16 v[98:113], v[240:243], v[220:223], v[98:113]
	ds_read_b128 v[220:223], v224
	ds_read_b128 v[224:227], v224 offset:4096
	s_add_u32 m0, s30, 0xc000
	s_nop 0
	global_load_lds_dwordx4 v244, s[100:101]
	s_add_u32 m0, s30, 0xd000
	s_nop 0
	global_load_lds_dwordx4 v245, s[100:101]
	v_mfma_f32_32x32x16_bf16 v[82:97], v[232:235], v[228:231], v[82:97]
	ds_read_b128 v[232:235], v236 offset:32768
	ds_read_b128 v[236:239], v236 offset:36864
	s_add_u32 m0, s30, 0xe000
	s_nop 0
	global_load_lds_dwordx4 v246, s[100:101]
	s_add_u32 m0, s30, 0xf000
	s_nop 0
	global_load_lds_dwordx4 v247, s[100:101]
	v_mfma_f32_32x32x16_bf16 v[66:81], v[240:243], v[228:231], v[66:81]
	s_add_u32 s100, s100, 0x80
	s_addc_u32 s101, s101, 0
	s_waitcnt lgkmcnt(0)
	v_mfma_f32_32x32x16_bf16 v[178:193], v[232:235], v[220:223], v[178:193]
	v_xor_b32_e32 v240, 0x20, v250
	v_add_u32_e32 v228, v240, v248
	v_add_u32_e32 v240, v240, v249
	v_mfma_f32_32x32x16_bf16 v[162:177], v[236:239], v[220:223], v[162:177]
	ds_read_b128 v[220:223], v228
	ds_read_b128 v[228:231], v228 offset:4096
	v_mfma_f32_32x32x16_bf16 v[146:161], v[232:235], v[224:227], v[146:161]
	ds_read_b128 v[232:235], v240 offset:32768
	ds_read_b128 v[240:243], v240 offset:36864
	v_mfma_f32_32x32x16_bf16 v[130:145], v[236:239], v[224:227], v[130:145]
	s_waitcnt lgkmcnt(0)
	v_mfma_f32_32x32x16_bf16 v[178:193], v[232:235], v[220:223], v[178:193]
	v_xor_b32_e32 v236, 0x40, v250
	v_add_u32_e32 v224, v236, v248
	v_add_u32_e32 v236, v236, v249
	v_mfma_f32_32x32x16_bf16 v[162:177], v[240:243], v[220:223], v[162:177]
	ds_read_b128 v[220:223], v224
	ds_read_b128 v[224:227], v224 offset:4096
	v_mfma_f32_32x32x16_bf16 v[146:161], v[232:235], v[228:231], v[146:161]
	ds_read_b128 v[232:235], v236 offset:32768
	ds_read_b128 v[236:239], v236 offset:36864
	v_mfma_f32_32x32x16_bf16 v[130:145], v[240:243], v[228:231], v[130:145]
	s_waitcnt lgkmcnt(0)
	v_mfma_f32_32x32x16_bf16 v[178:193], v[232:235], v[220:223], v[178:193]
	v_xor_b32_e32 v240, 0x60, v250
	v_add_u32_e32 v228, v240, v248
	v_add_u32_e32 v240, v240, v249
	v_mfma_f32_32x32x16_bf16 v[162:177], v[236:239], v[220:223], v[162:177]
	ds_read_b128 v[220:223], v228
	ds_read_b128 v[228:231], v228 offset:4096
	v_mfma_f32_32x32x16_bf16 v[146:161], v[232:235], v[224:227], v[146:161]
	ds_read_b128 v[232:235], v240 offset:32768
	ds_read_b128 v[240:243], v240 offset:36864
	v_mfma_f32_32x32x16_bf16 v[130:145], v[236:239], v[224:227], v[130:145]
	s_waitcnt vmcnt(0) lgkmcnt(0)
	s_barrier
	s_waitcnt lgkmcnt(0)
	v_mfma_f32_32x32x16_bf16 v[178:193], v[232:235], v[220:223], v[178:193]
	v_mov_b32_e32 v236, v250
	v_add_u32_e32 v224, v236, v248
	v_add_u32_e32 v236, v236, v249
	v_mfma_f32_32x32x16_bf16 v[162:177], v[240:243], v[220:223], v[162:177]
	ds_read_b128 v[220:223], v224 offset:16384
	ds_read_b128 v[224:227], v224 offset:20480
	s_add_u32 m0, s30, 0x8000
	s_nop 0
	global_load_lds_dwordx4 v244, s[52:53]
	s_add_u32 m0, s30, 0x9000
	s_nop 0
	global_load_lds_dwordx4 v245, s[52:53]
	v_mfma_f32_32x32x16_bf16 v[146:161], v[232:235], v[228:231], v[146:161]
	ds_read_b128 v[232:235], v236 offset:49152
	ds_read_b128 v[236:239], v236 offset:53248
	s_add_u32 m0, s30, 0xa000
	s_nop 0
	global_load_lds_dwordx4 v246, s[52:53]
	s_add_u32 m0, s30, 0xb000
	s_nop 0
	global_load_lds_dwordx4 v247, s[52:53]
	v_mfma_f32_32x32x16_bf16 v[130:145], v[240:243], v[228:231], v[130:145]
	s_add_u32 m0, s30, 0x0
	s_nop 0
	global_load_lds_dwordx4 v244, s[98:99]
	s_add_u32 m0, s30, 0x1000
	s_nop 0
	global_load_lds_dwordx4 v245, s[98:99]
	s_add_u32 m0, s30, 0x2000
	s_nop 0
	global_load_lds_dwordx4 v246, s[98:99]
	s_add_u32 m0, s30, 0x3000
	s_nop 0
	global_load_lds_dwordx4 v247, s[98:99]
	s_add_u32 s52, s52, 0x80
	s_addc_u32 s53, s53, 0
	s_add_u32 s98, s98, 0x80
	s_addc_u32 s99, s99, 0
	s_waitcnt lgkmcnt(0)
	v_mfma_f32_32x32x16_bf16 v[50:65], v[232:235], v[220:223], v[50:65]
	v_xor_b32_e32 v240, 0x20, v250
	v_add_u32_e32 v228, v240, v248
	v_add_u32_e32 v240, v240, v249
	v_mfma_f32_32x32x16_bf16 v[34:49], v[236:239], v[220:223], v[34:49]
	ds_read_b128 v[220:223], v228 offset:16384
	ds_read_b128 v[228:231], v228 offset:20480
	v_mfma_f32_32x32x16_bf16 v[18:33], v[232:235], v[224:227], v[18:33]
	ds_read_b128 v[232:235], v240 offset:49152
	ds_read_b128 v[240:243], v240 offset:53248
	v_mfma_f32_32x32x16_bf16 v[2:17], v[236:239], v[224:227], v[2:17]
	s_waitcnt lgkmcnt(0)
	v_mfma_f32_32x32x16_bf16 v[50:65], v[232:235], v[220:223], v[50:65]
	v_xor_b32_e32 v236, 0x40, v250
	v_add_u32_e32 v224, v236, v248
	v_add_u32_e32 v236, v236, v249
	v_mfma_f32_32x32x16_bf16 v[34:49], v[240:243], v[220:223], v[34:49]
	ds_read_b128 v[220:223], v224 offset:16384
	ds_read_b128 v[224:227], v224 offset:20480
	v_mfma_f32_32x32x16_bf16 v[18:33], v[232:235], v[228:231], v[18:33]
	ds_read_b128 v[232:235], v236 offset:49152
	ds_read_b128 v[236:239], v236 offset:53248
	v_mfma_f32_32x32x16_bf16 v[2:17], v[240:243], v[228:231], v[2:17]
	s_waitcnt lgkmcnt(0)
	v_mfma_f32_32x32x16_bf16 v[50:65], v[232:235], v[220:223], v[50:65]
	v_xor_b32_e32 v240, 0x60, v250
	v_add_u32_e32 v228, v240, v248
	v_add_u32_e32 v240, v240, v249
	v_mfma_f32_32x32x16_bf16 v[34:49], v[236:239], v[220:223], v[34:49]
	ds_read_b128 v[220:223], v228 offset:16384
	ds_read_b128 v[228:231], v228 offset:20480
	v_mfma_f32_32x32x16_bf16 v[18:33], v[232:235], v[224:227], v[18:33]
	ds_read_b128 v[232:235], v240 offset:49152
	ds_read_b128 v[240:243], v240 offset:53248
	v_mfma_f32_32x32x16_bf16 v[2:17], v[236:239], v[224:227], v[2:17]
	s_waitcnt vmcnt(0) lgkmcnt(0)
	s_barrier
	s_waitcnt lgkmcnt(0)
	v_mfma_f32_32x32x16_bf16 v[50:65], v[232:235], v[220:223], v[50:65]
	v_mov_b32_e32 v236, v250
	v_add_u32_e32 v224, v236, v248
	v_add_u32_e32 v236, v236, v249
	v_mfma_f32_32x32x16_bf16 v[34:49], v[240:243], v[220:223], v[34:49]
	ds_read_b128 v[220:223], v224 offset:16384
	ds_read_b128 v[224:227], v224 offset:20480
	s_add_u32 m0, s30, 0xc000
	s_nop 0
	global_load_lds_dwordx4 v244, s[54:55]
	s_add_u32 m0, s30, 0xd000
	s_nop 0
	global_load_lds_dwordx4 v245, s[54:55]
	v_mfma_f32_32x32x16_bf16 v[18:33], v[232:235], v[228:231], v[18:33]
	ds_read_b128 v[232:235], v236 offset:32768
	ds_read_b128 v[236:239], v236 offset:36864
	s_add_u32 m0, s30, 0xe000
	s_nop 0
	global_load_lds_dwordx4 v246, s[54:55]
	s_add_u32 m0, s30, 0xf000
	s_nop 0
	global_load_lds_dwordx4 v247, s[54:55]
	v_mfma_f32_32x32x16_bf16 v[2:17], v[240:243], v[228:231], v[2:17]
	s_add_u32 s54, s54, 0x80
	s_addc_u32 s55, s55, 0
	s_waitcnt lgkmcnt(0)
	v_mfma_f32_32x32x16_bf16 v[114:129], v[232:235], v[220:223], v[114:129]
	v_xor_b32_e32 v240, 0x20, v250
	v_add_u32_e32 v228, v240, v248
	v_add_u32_e32 v240, v240, v249
	v_mfma_f32_32x32x16_bf16 v[98:113], v[236:239], v[220:223], v[98:113]
	ds_read_b128 v[220:223], v228 offset:16384
	ds_read_b128 v[228:231], v228 offset:20480
	v_mfma_f32_32x32x16_bf16 v[82:97], v[232:235], v[224:227], v[82:97]
	ds_read_b128 v[232:235], v240 offset:32768
	ds_read_b128 v[240:243], v240 offset:36864
	v_mfma_f32_32x32x16_bf16 v[66:81], v[236:239], v[224:227], v[66:81]
	s_waitcnt lgkmcnt(0)
	v_mfma_f32_32x32x16_bf16 v[114:129], v[232:235], v[220:223], v[114:129]
	v_xor_b32_e32 v236, 0x40, v250
	v_add_u32_e32 v224, v236, v248
	v_add_u32_e32 v236, v236, v249
	v_mfma_f32_32x32x16_bf16 v[98:113], v[240:243], v[220:223], v[98:113]
	ds_read_b128 v[220:223], v224 offset:16384
	ds_read_b128 v[224:227], v224 offset:20480
	v_mfma_f32_32x32x16_bf16 v[82:97], v[232:235], v[228:231], v[82:97]
	ds_read_b128 v[232:235], v236 offset:32768
	ds_read_b128 v[236:239], v236 offset:36864
	v_mfma_f32_32x32x16_bf16 v[66:81], v[240:243], v[228:231], v[66:81]
	s_waitcnt lgkmcnt(0)
	v_mfma_f32_32x32x16_bf16 v[114:129], v[232:235], v[220:223], v[114:129]
	v_xor_b32_e32 v240, 0x60, v250
	v_add_u32_e32 v228, v240, v248
	v_add_u32_e32 v240, v240, v249
	v_mfma_f32_32x32x16_bf16 v[98:113], v[236:239], v[220:223], v[98:113]
	ds_read_b128 v[220:223], v228 offset:16384
	ds_read_b128 v[228:231], v228 offset:20480
	v_mfma_f32_32x32x16_bf16 v[82:97], v[232:235], v[224:227], v[82:97]
	ds_read_b128 v[232:235], v240 offset:32768
	ds_read_b128 v[240:243], v240 offset:36864
	v_mfma_f32_32x32x16_bf16 v[66:81], v[236:239], v[224:227], v[66:81]
	s_waitcnt vmcnt(0) lgkmcnt(0)
	s_barrier
	s_waitcnt lgkmcnt(0)
	v_mfma_f32_32x32x16_bf16 v[114:129], v[232:235], v[220:223], v[114:129]
	v_mov_b32_e32 v236, v250
	v_add_u32_e32 v224, v236, v248
	v_add_u32_e32 v236, v236, v249
	v_mfma_f32_32x32x16_bf16 v[98:113], v[240:243], v[220:223], v[98:113]
	ds_read_b128 v[220:223], v224 offset:16384
	ds_read_b128 v[224:227], v224 offset:20480
	s_add_u32 m0, s30, 0x8000
	s_nop 0
	global_load_lds_dwordx4 v244, s[100:101]
	s_add_u32 m0, s30, 0x9000
	s_nop 0
	global_load_lds_dwordx4 v245, s[100:101]
	v_mfma_f32_32x32x16_bf16 v[82:97], v[232:235], v[228:231], v[82:97]
	ds_read_b128 v[232:235], v236 offset:49152
	ds_read_b128 v[236:239], v236 offset:53248
	s_add_u32 m0, s30, 0xa000
	s_nop 0
	global_load_lds_dwordx4 v246, s[100:101]
	s_add_u32 m0, s30, 0xb000
	s_nop 0
	global_load_lds_dwordx4 v247, s[100:101]
	v_mfma_f32_32x32x16_bf16 v[66:81], v[240:243], v[228:231], v[66:81]
	s_add_u32 s100, s100, 0x80
	s_addc_u32 s101, s101, 0
	s_waitcnt lgkmcnt(0)
	v_mfma_f32_32x32x16_bf16 v[178:193], v[232:235], v[220:223], v[178:193]
	v_xor_b32_e32 v240, 0x20, v250
	v_add_u32_e32 v228, v240, v248
	v_add_u32_e32 v240, v240, v249
	v_mfma_f32_32x32x16_bf16 v[162:177], v[236:239], v[220:223], v[162:177]
	ds_read_b128 v[220:223], v228 offset:16384
	ds_read_b128 v[228:231], v228 offset:20480
	v_mfma_f32_32x32x16_bf16 v[146:161], v[232:235], v[224:227], v[146:161]
	ds_read_b128 v[232:235], v240 offset:49152
	ds_read_b128 v[240:243], v240 offset:53248
	v_mfma_f32_32x32x16_bf16 v[130:145], v[236:239], v[224:227], v[130:145]
	s_waitcnt lgkmcnt(0)
	v_mfma_f32_32x32x16_bf16 v[178:193], v[232:235], v[220:223], v[178:193]
	v_xor_b32_e32 v236, 0x40, v250
	v_add_u32_e32 v224, v236, v248
	v_add_u32_e32 v236, v236, v249
	v_mfma_f32_32x32x16_bf16 v[162:177], v[240:243], v[220:223], v[162:177]
	ds_read_b128 v[220:223], v224 offset:16384
	ds_read_b128 v[224:227], v224 offset:20480
	v_mfma_f32_32x32x16_bf16 v[146:161], v[232:235], v[228:231], v[146:161]
	ds_read_b128 v[232:235], v236 offset:49152
	ds_read_b128 v[236:239], v236 offset:53248
	v_mfma_f32_32x32x16_bf16 v[130:145], v[240:243], v[228:231], v[130:145]
	s_waitcnt lgkmcnt(0)
	v_mfma_f32_32x32x16_bf16 v[178:193], v[232:235], v[220:223], v[178:193]
	v_xor_b32_e32 v240, 0x60, v250
	v_add_u32_e32 v228, v240, v248
	v_add_u32_e32 v240, v240, v249
	v_mfma_f32_32x32x16_bf16 v[162:177], v[236:239], v[220:223], v[162:177]
	ds_read_b128 v[220:223], v228 offset:16384
	ds_read_b128 v[228:231], v228 offset:20480
	v_mfma_f32_32x32x16_bf16 v[146:161], v[232:235], v[224:227], v[146:161]
	ds_read_b128 v[232:235], v240 offset:49152
	ds_read_b128 v[240:243], v240 offset:53248
	v_mfma_f32_32x32x16_bf16 v[130:145], v[236:239], v[224:227], v[130:145]
	s_waitcnt vmcnt(0) lgkmcnt(0)
	s_barrier
	s_waitcnt lgkmcnt(0)
	v_mfma_f32_32x32x16_bf16 v[178:193], v[232:235], v[220:223], v[178:193]
	v_mov_b32_e32 v236, v250
	v_add_u32_e32 v224, v236, v248
	v_add_u32_e32 v236, v236, v249
	v_mfma_f32_32x32x16_bf16 v[162:177], v[240:243], v[220:223], v[162:177]
	ds_read_b128 v[220:223], v224
	ds_read_b128 v[224:227], v224 offset:4096
	s_add_u32 m0, s30, 0xc000
	s_nop 0
	global_load_lds_dwordx4 v244, s[52:53]
	s_add_u32 m0, s30, 0xd000
	s_nop 0
	global_load_lds_dwordx4 v245, s[52:53]
	v_mfma_f32_32x32x16_bf16 v[146:161], v[232:235], v[228:231], v[146:161]
	ds_read_b128 v[232:235], v236 offset:32768
	ds_read_b128 v[236:239], v236 offset:36864
	s_add_u32 m0, s30, 0xe000
	s_nop 0
	global_load_lds_dwordx4 v246, s[52:53]
	s_add_u32 m0, s30, 0xf000
	s_nop 0
	global_load_lds_dwordx4 v247, s[52:53]
	v_mfma_f32_32x32x16_bf16 v[130:145], v[240:243], v[228:231], v[130:145]
	s_add_u32 m0, s30, 0x4000
	s_nop 0
	global_load_lds_dwordx4 v244, s[98:99]
	s_add_u32 m0, s30, 0x5000
	s_nop 0
	global_load_lds_dwordx4 v245, s[98:99]
	s_add_u32 m0, s30, 0x6000
	s_nop 0
	global_load_lds_dwordx4 v246, s[98:99]
	s_add_u32 m0, s30, 0x7000
	s_nop 0
	global_load_lds_dwordx4 v247, s[98:99]
	s_add_u32 s52, s52, 0x80
	s_addc_u32 s53, s53, 0
	s_add_u32 s98, s98, 0x80
	s_addc_u32 s99, s99, 0
	s_sub_u32 s51, s51, 1
	s_cmp_lg_u32 s51, 0
	s_cbranch_scc1 .Lp4f_gloop
	s_waitcnt lgkmcnt(0)
	v_mfma_f32_32x32x16_bf16 v[50:65], v[232:235], v[220:223], v[50:65]
	v_xor_b32_e32 v240, 0x20, v250
	v_add_u32_e32 v228, v240, v248
	v_add_u32_e32 v240, v240, v249
	v_mfma_f32_32x32x16_bf16 v[34:49], v[236:239], v[220:223], v[34:49]
	ds_read_b128 v[220:223], v228
	ds_read_b128 v[228:231], v228 offset:4096
	v_mfma_f32_32x32x16_bf16 v[18:33], v[232:235], v[224:227], v[18:33]
	ds_read_b128 v[232:235], v240 offset:32768
	ds_read_b128 v[240:243], v240 offset:36864
	v_mfma_f32_32x32x16_bf16 v[2:17], v[236:239], v[224:227], v[2:17]
	s_waitcnt lgkmcnt(0)
	v_mfma_f32_32x32x16_bf16 v[50:65], v[232:235], v[220:223], v[50:65]
	v_xor_b32_e32 v236, 0x40, v250
	v_add_u32_e32 v224, v236, v248
	v_add_u32_e32 v236, v236, v249
	v_mfma_f32_32x32x16_bf16 v[34:49], v[240:243], v[220:223], v[34:49]
	ds_read_b128 v[220:223], v224
	ds_read_b128 v[224:227], v224 offset:4096
	v_mfma_f32_32x32x16_bf16 v[18:33], v[232:235], v[228:231], v[18:33]
	ds_read_b128 v[232:235], v236 offset:32768
	ds_read_b128 v[236:239], v236 offset:36864
	v_mfma_f32_32x32x16_bf16 v[2:17], v[240:243], v[228:231], v[2:17]
	s_waitcnt lgkmcnt(0)
	v_mfma_f32_32x32x16_bf16 v[50:65], v[232:235], v[220:223], v[50:65]
	v_xor_b32_e32 v240, 0x60, v250
	v_add_u32_e32 v228, v240, v248
	v_add_u32_e32 v240, v240, v249
	v_mfma_f32_32x32x16_bf16 v[34:49], v[236:239], v[220:223], v[34:49]
	ds_read_b128 v[220:223], v228
	ds_read_b128 v[228:231], v228 offset:4096
	v_mfma_f32_32x32x16_bf16 v[18:33], v[232:235], v[224:227], v[18:33]
	ds_read_b128 v[232:235], v240 offset:32768
	ds_read_b128 v[240:243], v240 offset:36864
	v_mfma_f32_32x32x16_bf16 v[2:17], v[236:239], v[224:227], v[2:17]
	s_waitcnt vmcnt(0) lgkmcnt(0)
	s_barrier
	s_waitcnt lgkmcnt(0)
	v_mfma_f32_32x32x16_bf16 v[50:65], v[232:235], v[220:223], v[50:65]
	v_mov_b32_e32 v236, v250
	v_add_u32_e32 v224, v236, v248
	v_add_u32_e32 v236, v236, v249
	v_mfma_f32_32x32x16_bf16 v[34:49], v[240:243], v[220:223], v[34:49]
	ds_read_b128 v[220:223], v224
	ds_read_b128 v[224:227], v224 offset:4096
	s_add_u32 m0, s30, 0x8000
	s_nop 0
	global_load_lds_dwordx4 v244, s[54:55]
	s_add_u32 m0, s30, 0x9000
	s_nop 0
	global_load_lds_dwordx4 v245, s[54:55]
	v_mfma_f32_32x32x16_bf16 v[18:33], v[232:235], v[228:231], v[18:33]
	ds_read_b128 v[232:235], v236 offset:49152
	ds_read_b128 v[236:239], v236 offset:53248
	s_add_u32 m0, s30, 0xa000
	s_nop 0
	global_load_lds_dwordx4 v246, s[54:55]
	s_add_u32 m0, s30, 0xb000
	s_nop 0
	global_load_lds_dwordx4 v247, s[54:55]
	v_mfma_f32_32x32x16_bf16 v[2:17], v[240:243], v[228:231], v[2:17]
	s_add_u32 s54, s54, 0x80
	s_addc_u32 s55, s55, 0
	s_waitcnt lgkmcnt(0)
	v_mfma_f32_32x32x16_bf16 v[114:129], v[232:235], v[220:223], v[114:129]
	v_xor_b32_e32 v240, 0x20, v250
	v_add_u32_e32 v228, v240, v248
	v_add_u32_e32 v240, v240, v249
	v_mfma_f32_32x32x16_bf16 v[98:113], v[236:239], v[220:223], v[98:113]
	ds_read_b128 v[220:223], v228
	ds_read_b128 v[228:231], v228 offset:4096
	v_mfma_f32_32x32x16_bf16 v[82:97], v[232:235], v[224:227], v[82:97]
	ds_read_b128 v[232:235], v240 offset:49152
	ds_read_b128 v[240:243], v240 offset:53248
	v_mfma_f32_32x32x16_bf16 v[66:81], v[236:239], v[224:227], v[66:81]
	s_waitcnt lgkmcnt(0)
	v_mfma_f32_32x32x16_bf16 v[114:129], v[232:235], v[220:223], v[114:129]
	v_xor_b32_e32 v236, 0x40, v250
	v_add_u32_e32 v224, v236, v248
	v_add_u32_e32 v236, v236, v249
	v_mfma_f32_32x32x16_bf16 v[98:113], v[240:243], v[220:223], v[98:113]
	ds_read_b128 v[220:223], v224
	ds_read_b128 v[224:227], v224 offset:4096
	v_mfma_f32_32x32x16_bf16 v[82:97], v[232:235], v[228:231], v[82:97]
	ds_read_b128 v[232:235], v236 offset:49152
	ds_read_b128 v[236:239], v236 offset:53248
	v_mfma_f32_32x32x16_bf16 v[66:81], v[240:243], v[228:231], v[66:81]
	s_waitcnt lgkmcnt(0)
	v_mfma_f32_32x32x16_bf16 v[114:129], v[232:235], v[220:223], v[114:129]
	v_xor_b32_e32 v240, 0x60, v250
	v_add_u32_e32 v228, v240, v248
	v_add_u32_e32 v240, v240, v249
	v_mfma_f32_32x32x16_bf16 v[98:113], v[236:239], v[220:223], v[98:113]
	ds_read_b128 v[220:223], v228
	ds_read_b128 v[228:231], v228 offset:4096
	v_mfma_f32_32x32x16_bf16 v[82:97], v[232:235], v[224:227], v[82:97]
	ds_read_b128 v[232:235], v240 offset:49152
	ds_read_b128 v[240:243], v240 offset:53248
	v_mfma_f32_32x32x16_bf16 v[66:81], v[236:239], v[224:227], v[66:81]
	s_waitcnt vmcnt(0) lgkmcnt(0)
	s_barrier
	s_waitcnt lgkmcnt(0)
	v_mfma_f32_32x32x16_bf16 v[114:129], v[232:235], v[220:223], v[114:129]
	v_mov_b32_e32 v236, v250
	v_add_u32_e32 v224, v236, v248
	v_add_u32_e32 v236, v236, v249
	v_mfma_f32_32x32x16_bf16 v[98:113], v[240:243], v[220:223], v[98:113]
	ds_read_b128 v[220:223], v224
	ds_read_b128 v[224:227], v224 offset:4096
	s_add_u32 m0, s30, 0xc000
	s_nop 0
	global_load_lds_dwordx4 v244, s[100:101]
	s_add_u32 m0, s30, 0xd000
	s_nop 0
	global_load_lds_dwordx4 v245, s[100:101]
	v_mfma_f32_32x32x16_bf16 v[82:97], v[232:235], v[228:231], v[82:97]
	ds_read_b128 v[232:235], v236 offset:32768
	ds_read_b128 v[236:239], v236 offset:36864
	s_add_u32 m0, s30, 0xe000
	s_nop 0
	global_load_lds_dwordx4 v246, s[100:101]
	s_add_u32 m0, s30, 0xf000
	s_nop 0
	global_load_lds_dwordx4 v247, s[100:101]
	v_mfma_f32_32x32x16_bf16 v[66:81], v[240:243], v[228:231], v[66:81]
	s_add_u32 s100, s100, 0x80
	s_addc_u32 s101, s101, 0
	s_waitcnt lgkmcnt(0)
	v_mfma_f32_32x32x16_bf16 v[178:193], v[232:235], v[220:223], v[178:193]
	v_xor_b32_e32 v240, 0x20, v250
	v_add_u32_e32 v228, v240, v248
	v_add_u32_e32 v240, v240, v249
	v_mfma_f32_32x32x16_bf16 v[162:177], v[236:239], v[220:223], v[162:177]
	ds_read_b128 v[220:223], v228
	ds_read_b128 v[228:231], v228 offset:4096
	v_mfma_f32_32x32x16_bf16 v[146:161], v[232:235], v[224:227], v[146:161]
	ds_read_b128 v[232:235], v240 offset:32768
	ds_read_b128 v[240:243], v240 offset:36864
	v_mfma_f32_32x32x16_bf16 v[130:145], v[236:239], v[224:227], v[130:145]
	s_waitcnt lgkmcnt(0)
	v_mfma_f32_32x32x16_bf16 v[178:193], v[232:235], v[220:223], v[178:193]
	v_xor_b32_e32 v236, 0x40, v250
	v_add_u32_e32 v224, v236, v248
	v_add_u32_e32 v236, v236, v249
	v_mfma_f32_32x32x16_bf16 v[162:177], v[240:243], v[220:223], v[162:177]
	ds_read_b128 v[220:223], v224
	ds_read_b128 v[224:227], v224 offset:4096
	v_mfma_f32_32x32x16_bf16 v[146:161], v[232:235], v[228:231], v[146:161]
	ds_read_b128 v[232:235], v236 offset:32768
	ds_read_b128 v[236:239], v236 offset:36864
	v_mfma_f32_32x32x16_bf16 v[130:145], v[240:243], v[228:231], v[130:145]
	s_waitcnt lgkmcnt(0)
	v_mfma_f32_32x32x16_bf16 v[178:193], v[232:235], v[220:223], v[178:193]
	v_xor_b32_e32 v240, 0x60, v250
	v_add_u32_e32 v228, v240, v248
	v_add_u32_e32 v240, v240, v249
	v_mfma_f32_32x32x16_bf16 v[162:177], v[236:239], v[220:223], v[162:177]
	ds_read_b128 v[220:223], v228
	ds_read_b128 v[228:231], v228 offset:4096
	v_mfma_f32_32x32x16_bf16 v[146:161], v[232:235], v[224:227], v[146:161]
	ds_read_b128 v[232:235], v240 offset:32768
	ds_read_b128 v[240:243], v240 offset:36864
	v_mfma_f32_32x32x16_bf16 v[130:145], v[236:239], v[224:227], v[130:145]
	s_waitcnt vmcnt(0) lgkmcnt(0)
	s_barrier
	s_waitcnt lgkmcnt(0)
	v_mfma_f32_32x32x16_bf16 v[178:193], v[232:235], v[220:223], v[178:193]
	v_mov_b32_e32 v236, v250
	v_add_u32_e32 v224, v236, v248
	v_add_u32_e32 v236, v236, v249
	v_mfma_f32_32x32x16_bf16 v[162:177], v[240:243], v[220:223], v[162:177]
	ds_read_b128 v[220:223], v224 offset:16384
	ds_read_b128 v[224:227], v224 offset:20480
	s_add_u32 m0, s30, 0x8000
	s_nop 0
	global_load_lds_dwordx4 v244, s[52:53]
	s_add_u32 m0, s30, 0x9000
	s_nop 0
	global_load_lds_dwordx4 v245, s[52:53]
	v_mfma_f32_32x32x16_bf16 v[146:161], v[232:235], v[228:231], v[146:161]
	ds_read_b128 v[232:235], v236 offset:49152
	ds_read_b128 v[236:239], v236 offset:53248
	s_add_u32 m0, s30, 0xa000
	s_nop 0
	global_load_lds_dwordx4 v246, s[52:53]
	s_add_u32 m0, s30, 0xb000
	s_nop 0
	global_load_lds_dwordx4 v247, s[52:53]
	v_mfma_f32_32x32x16_bf16 v[130:145], v[240:243], v[228:231], v[130:145]
	s_add_u32 s52, s52, 0x80
	s_addc_u32 s53, s53, 0
	s_waitcnt lgkmcnt(0)
	v_mfma_f32_32x32x16_bf16 v[50:65], v[232:235], v[220:223], v[50:65]
	v_xor_b32_e32 v240, 0x20, v250
	v_add_u32_e32 v228, v240, v248
	v_add_u32_e32 v240, v240, v249
	v_mfma_f32_32x32x16_bf16 v[34:49], v[236:239], v[220:223], v[34:49]
	ds_read_b128 v[220:223], v228 offset:16384
	ds_read_b128 v[228:231], v228 offset:20480
	v_mfma_f32_32x32x16_bf16 v[18:33], v[232:235], v[224:227], v[18:33]
	ds_read_b128 v[232:235], v240 offset:49152
	ds_read_b128 v[240:243], v240 offset:53248
	v_mfma_f32_32x32x16_bf16 v[2:17], v[236:239], v[224:227], v[2:17]
	s_waitcnt lgkmcnt(0)
	v_mfma_f32_32x32x16_bf16 v[50:65], v[232:235], v[220:223], v[50:65]
	v_xor_b32_e32 v236, 0x40, v250
	v_add_u32_e32 v224, v236, v248
	v_add_u32_e32 v236, v236, v249
	v_mfma_f32_32x32x16_bf16 v[34:49], v[240:243], v[220:223], v[34:49]
	ds_read_b128 v[220:223], v224 offset:16384
	ds_read_b128 v[224:227], v224 offset:20480
	v_mfma_f32_32x32x16_bf16 v[18:33], v[232:235], v[228:231], v[18:33]
	ds_read_b128 v[232:235], v236 offset:49152
	ds_read_b128 v[236:239], v236 offset:53248
	v_mfma_f32_32x32x16_bf16 v[2:17], v[240:243], v[228:231], v[2:17]
	s_waitcnt lgkmcnt(0)
	v_mfma_f32_32x32x16_bf16 v[50:65], v[232:235], v[220:223], v[50:65]
	v_xor_b32_e32 v240, 0x60, v250
	v_add_u32_e32 v228, v240, v248
	v_add_u32_e32 v240, v240, v249
	v_mfma_f32_32x32x16_bf16 v[34:49], v[236:239], v[220:223], v[34:49]
	ds_read_b128 v[220:223], v228 offset:16384
	ds_read_b128 v[228:231], v228 offset:20480
	v_mfma_f32_32x32x16_bf16 v[18:33], v[232:235], v[224:227], v[18:33]
	ds_read_b128 v[232:235], v240 offset:49152
	ds_read_b128 v[240:243], v240 offset:53248
	v_mfma_f32_32x32x16_bf16 v[2:17], v[236:239], v[224:227], v[2:17]
	s_waitcnt vmcnt(0) lgkmcnt(0)
	s_barrier
	s_waitcnt lgkmcnt(0)
	v_mfma_f32_32x32x16_bf16 v[50:65], v[232:235], v[220:223], v[50:65]
	v_mov_b32_e32 v236, v250
	v_add_u32_e32 v224, v236, v248
	v_add_u32_e32 v236, v236, v249
	v_mfma_f32_32x32x16_bf16 v[34:49], v[240:243], v[220:223], v[34:49]
	ds_read_b128 v[220:223], v224 offset:16384
	ds_read_b128 v[224:227], v224 offset:20480
	s_add_u32 m0, s30, 0xc000
	s_nop 0
	global_load_lds_dwordx4 v244, s[54:55]
	s_add_u32 m0, s30, 0xd000
	s_nop 0
	global_load_lds_dwordx4 v245, s[54:55]
	v_mfma_f32_32x32x16_bf16 v[18:33], v[232:235], v[228:231], v[18:33]
	ds_read_b128 v[232:235], v236 offset:32768
	ds_read_b128 v[236:239], v236 offset:36864
	s_add_u32 m0, s30, 0xe000
	s_nop 0
	global_load_lds_dwordx4 v246, s[54:55]
	s_add_u32 m0, s30, 0xf000
	s_nop 0
	global_load_lds_dwordx4 v247, s[54:55]
	v_mfma_f32_32x32x16_bf16 v[2:17], v[240:243], v[228:231], v[2:17]
	s_add_u32 s54, s54, 0x80
	s_addc_u32 s55, s55, 0
	s_waitcnt lgkmcnt(0)
	v_mfma_f32_32x32x16_bf16 v[114:129], v[232:235], v[220:223], v[114:129]
	v_xor_b32_e32 v240, 0x20, v250
	v_add_u32_e32 v228, v240, v248
	v_add_u32_e32 v240, v240, v249
	v_mfma_f32_32x32x16_bf16 v[98:113], v[236:239], v[220:223], v[98:113]
	ds_read_b128 v[220:223], v228 offset:16384
	ds_read_b128 v[228:231], v228 offset:20480
	v_mfma_f32_32x32x16_bf16 v[82:97], v[232:235], v[224:227], v[82:97]
	ds_read_b128 v[232:235], v240 offset:32768
	ds_read_b128 v[240:243], v240 offset:36864
	v_mfma_f32_32x32x16_bf16 v[66:81], v[236:239], v[224:227], v[66:81]
	s_waitcnt lgkmcnt(0)
	v_mfma_f32_32x32x16_bf16 v[114:129], v[232:235], v[220:223], v[114:129]
	v_xor_b32_e32 v236, 0x40, v250
	v_add_u32_e32 v224, v236, v248
	v_add_u32_e32 v236, v236, v249
	v_mfma_f32_32x32x16_bf16 v[98:113], v[240:243], v[220:223], v[98:113]
	ds_read_b128 v[220:223], v224 offset:16384
	ds_read_b128 v[224:227], v224 offset:20480
	v_mfma_f32_32x32x16_bf16 v[82:97], v[232:235], v[228:231], v[82:97]
	ds_read_b128 v[232:235], v236 offset:32768
	ds_read_b128 v[236:239], v236 offset:36864
	v_mfma_f32_32x32x16_bf16 v[66:81], v[240:243], v[228:231], v[66:81]
	s_waitcnt lgkmcnt(0)
	v_mfma_f32_32x32x16_bf16 v[114:129], v[232:235], v[220:223], v[114:129]
	v_xor_b32_e32 v240, 0x60, v250
	v_add_u32_e32 v228, v240, v248
	v_add_u32_e32 v240, v240, v249
	v_mfma_f32_32x32x16_bf16 v[98:113], v[236:239], v[220:223], v[98:113]
	ds_read_b128 v[220:223], v228 offset:16384
	ds_read_b128 v[228:231], v228 offset:20480
	v_mfma_f32_32x32x16_bf16 v[82:97], v[232:235], v[224:227], v[82:97]
	ds_read_b128 v[232:235], v240 offset:32768
	ds_read_b128 v[240:243], v240 offset:36864
	v_mfma_f32_32x32x16_bf16 v[66:81], v[236:239], v[224:227], v[66:81]
	s_waitcnt vmcnt(0) lgkmcnt(0)
	s_barrier
	s_waitcnt lgkmcnt(0)
	v_mfma_f32_32x32x16_bf16 v[114:129], v[232:235], v[220:223], v[114:129]
	v_mov_b32_e32 v236, v250
	v_add_u32_e32 v224, v236, v248
	v_add_u32_e32 v236, v236, v249
	v_mfma_f32_32x32x16_bf16 v[98:113], v[240:243], v[220:223], v[98:113]
	ds_read_b128 v[220:223], v224 offset:16384
	ds_read_b128 v[224:227], v224 offset:20480
	v_mfma_f32_32x32x16_bf16 v[82:97], v[232:235], v[228:231], v[82:97]
	ds_read_b128 v[232:235], v236 offset:49152
	ds_read_b128 v[236:239], v236 offset:53248
	v_mfma_f32_32x32x16_bf16 v[66:81], v[240:243], v[228:231], v[66:81]
	s_waitcnt lgkmcnt(0)
	v_mfma_f32_32x32x16_bf16 v[178:193], v[232:235], v[220:223], v[178:193]
	v_xor_b32_e32 v240, 0x20, v250
	v_add_u32_e32 v228, v240, v248
	v_add_u32_e32 v240, v240, v249
	v_mfma_f32_32x32x16_bf16 v[162:177], v[236:239], v[220:223], v[162:177]
	ds_read_b128 v[220:223], v228 offset:16384
	ds_read_b128 v[228:231], v228 offset:20480
	v_mfma_f32_32x32x16_bf16 v[146:161], v[232:235], v[224:227], v[146:161]
	ds_read_b128 v[232:235], v240 offset:49152
	ds_read_b128 v[240:243], v240 offset:53248
	v_mfma_f32_32x32x16_bf16 v[130:145], v[236:239], v[224:227], v[130:145]
	s_waitcnt lgkmcnt(0)
	v_mfma_f32_32x32x16_bf16 v[178:193], v[232:235], v[220:223], v[178:193]
	v_xor_b32_e32 v236, 0x40, v250
	v_add_u32_e32 v224, v236, v248
	v_add_u32_e32 v236, v236, v249
	v_mfma_f32_32x32x16_bf16 v[162:177], v[240:243], v[220:223], v[162:177]
	ds_read_b128 v[220:223], v224 offset:16384
	ds_read_b128 v[224:227], v224 offset:20480
	v_mfma_f32_32x32x16_bf16 v[146:161], v[232:235], v[228:231], v[146:161]
	ds_read_b128 v[232:235], v236 offset:49152
	ds_read_b128 v[236:239], v236 offset:53248
	v_mfma_f32_32x32x16_bf16 v[130:145], v[240:243], v[228:231], v[130:145]
	s_waitcnt lgkmcnt(0)
	v_mfma_f32_32x32x16_bf16 v[178:193], v[232:235], v[220:223], v[178:193]
	v_xor_b32_e32 v240, 0x60, v250
	v_add_u32_e32 v228, v240, v248
	v_add_u32_e32 v240, v240, v249
	v_mfma_f32_32x32x16_bf16 v[162:177], v[236:239], v[220:223], v[162:177]
	ds_read_b128 v[220:223], v228 offset:16384
	ds_read_b128 v[228:231], v228 offset:20480
	v_mfma_f32_32x32x16_bf16 v[146:161], v[232:235], v[224:227], v[146:161]
	ds_read_b128 v[232:235], v240 offset:49152
	ds_read_b128 v[240:243], v240 offset:53248
	v_mfma_f32_32x32x16_bf16 v[130:145], v[236:239], v[224:227], v[130:145]
	s_waitcnt lgkmcnt(0)
	v_mfma_f32_32x32x16_bf16 v[178:193], v[232:235], v[220:223], v[178:193]
	v_mfma_f32_32x32x16_bf16 v[162:177], v[240:243], v[220:223], v[162:177]
	v_mfma_f32_32x32x16_bf16 v[146:161], v[232:235], v[228:231], v[146:161]
	v_mfma_f32_32x32x16_bf16 v[130:145], v[240:243], v[228:231], v[130:145]
	s_nop 15
	v_mul_f32_e32 v230, 0xbfb8aa3b, v192
	v_mul_f32_e32 v231, 0xbfb8aa3b, v193
	v_exp_f32_e32 v230, v230
	v_exp_f32_e32 v231, v231
	s_nop 0
	v_add_f32_e32 v230, 1.0, v230
	v_add_f32_e32 v231, 1.0, v231
	v_div_scale_f32 v220, s[66:67], v230, v230, 1.0
	v_rcp_f32_e32 v221, v220
	s_nop 0
	v_fma_f32 v222, -v220, v221, 1.0
	v_fmac_f32_e32 v221, v222, v221
	v_div_scale_f32 v223, vcc, 1.0, v230, 1.0
	v_mul_f32_e32 v224, v223, v221
	v_fma_f32 v222, -v220, v224, v223
	v_fmac_f32_e32 v224, v222, v221
	v_fma_f32 v220, -v220, v224, v223
	v_div_fmas_f32 v220, v220, v221, v224
	v_div_fixup_f32 v192, v220, v230, 1.0
	v_div_scale_f32 v225, s[66:67], v231, v231, 1.0
	v_rcp_f32_e32 v226, v225
	s_nop 0
	v_fma_f32 v227, -v225, v226, 1.0
	v_fmac_f32_e32 v226, v227, v226
	v_div_scale_f32 v228, vcc, 1.0, v231, 1.0
	v_mul_f32_e32 v229, v228, v226
	v_fma_f32 v227, -v225, v229, v228
	v_fmac_f32_e32 v229, v227, v226
	v_fma_f32 v225, -v225, v229, v228
	v_div_fmas_f32 v225, v225, v226, v229
	v_div_fixup_f32 v193, v225, v231, 1.0
	v_cvt_pk_bf16_f32 v193, v192, v193
	v_mul_f32_e32 v230, 0xbfb8aa3b, v190
	v_mul_f32_e32 v231, 0xbfb8aa3b, v191
	v_exp_f32_e32 v230, v230
	v_exp_f32_e32 v231, v231
	s_nop 0
	v_add_f32_e32 v230, 1.0, v230
	v_add_f32_e32 v231, 1.0, v231
	v_div_scale_f32 v220, s[66:67], v230, v230, 1.0
	v_rcp_f32_e32 v221, v220
	s_nop 0
	v_fma_f32 v222, -v220, v221, 1.0
	v_fmac_f32_e32 v221, v222, v221
	v_div_scale_f32 v223, vcc, 1.0, v230, 1.0
	v_mul_f32_e32 v224, v223, v221
	v_fma_f32 v222, -v220, v224, v223
	v_fmac_f32_e32 v224, v222, v221
	v_fma_f32 v220, -v220, v224, v223
	v_div_fmas_f32 v220, v220, v221, v224
	v_div_fixup_f32 v190, v220, v230, 1.0
	v_div_scale_f32 v225, s[66:67], v231, v231, 1.0
	v_rcp_f32_e32 v226, v225
	s_nop 0
	v_fma_f32 v227, -v225, v226, 1.0
	v_fmac_f32_e32 v226, v227, v226
	v_div_scale_f32 v228, vcc, 1.0, v231, 1.0
	v_mul_f32_e32 v229, v228, v226
	v_fma_f32 v227, -v225, v229, v228
	v_fmac_f32_e32 v229, v227, v226
	v_fma_f32 v225, -v225, v229, v228
	v_div_fmas_f32 v225, v225, v226, v229
	v_div_fixup_f32 v191, v225, v231, 1.0
	v_cvt_pk_bf16_f32 v192, v190, v191
	v_mul_f32_e32 v230, 0xbfb8aa3b, v188
	v_mul_f32_e32 v231, 0xbfb8aa3b, v189
	v_exp_f32_e32 v230, v230
	v_exp_f32_e32 v231, v231
	s_nop 0
	v_add_f32_e32 v230, 1.0, v230
	v_add_f32_e32 v231, 1.0, v231
	v_div_scale_f32 v220, s[66:67], v230, v230, 1.0
	v_rcp_f32_e32 v221, v220
	s_nop 0
	v_fma_f32 v222, -v220, v221, 1.0
	v_fmac_f32_e32 v221, v222, v221
	v_div_scale_f32 v223, vcc, 1.0, v230, 1.0
	v_mul_f32_e32 v224, v223, v221
	v_fma_f32 v222, -v220, v224, v223
	v_fmac_f32_e32 v224, v222, v221
	v_fma_f32 v220, -v220, v224, v223
	v_div_fmas_f32 v220, v220, v221, v224
	v_div_fixup_f32 v188, v220, v230, 1.0
	v_div_scale_f32 v225, s[66:67], v231, v231, 1.0
	v_rcp_f32_e32 v226, v225
	s_nop 0
	v_fma_f32 v227, -v225, v226, 1.0
	v_fmac_f32_e32 v226, v227, v226
	v_div_scale_f32 v228, vcc, 1.0, v231, 1.0
	v_mul_f32_e32 v229, v228, v226
	v_fma_f32 v227, -v225, v229, v228
	v_fmac_f32_e32 v229, v227, v226
	v_fma_f32 v225, -v225, v229, v228
	v_div_fmas_f32 v225, v225, v226, v229
	v_div_fixup_f32 v189, v225, v231, 1.0
	v_cvt_pk_bf16_f32 v191, v188, v189
	v_mul_f32_e32 v230, 0xbfb8aa3b, v186
	v_mul_f32_e32 v231, 0xbfb8aa3b, v187
	v_exp_f32_e32 v230, v230
	v_exp_f32_e32 v231, v231
	s_nop 0
	v_add_f32_e32 v230, 1.0, v230
	v_add_f32_e32 v231, 1.0, v231
	v_div_scale_f32 v220, s[66:67], v230, v230, 1.0
	v_rcp_f32_e32 v221, v220
	s_nop 0
	v_fma_f32 v222, -v220, v221, 1.0
	v_fmac_f32_e32 v221, v222, v221
	v_div_scale_f32 v223, vcc, 1.0, v230, 1.0
	v_mul_f32_e32 v224, v223, v221
	v_fma_f32 v222, -v220, v224, v223
	v_fmac_f32_e32 v224, v222, v221
	v_fma_f32 v220, -v220, v224, v223
	v_div_fmas_f32 v220, v220, v221, v224
	v_div_fixup_f32 v186, v220, v230, 1.0
	v_div_scale_f32 v225, s[66:67], v231, v231, 1.0
	v_rcp_f32_e32 v226, v225
	s_nop 0
	v_fma_f32 v227, -v225, v226, 1.0
	v_fmac_f32_e32 v226, v227, v226
	v_div_scale_f32 v228, vcc, 1.0, v231, 1.0
	v_mul_f32_e32 v229, v228, v226
	v_fma_f32 v227, -v225, v229, v228
	v_fmac_f32_e32 v229, v227, v226
	v_fma_f32 v225, -v225, v229, v228
	v_div_fmas_f32 v225, v225, v226, v229
	v_div_fixup_f32 v187, v225, v231, 1.0
	v_cvt_pk_bf16_f32 v190, v186, v187
	v_mul_f32_e32 v230, 0xbfb8aa3b, v184
	v_mul_f32_e32 v231, 0xbfb8aa3b, v185
	v_exp_f32_e32 v230, v230
	v_exp_f32_e32 v231, v231
	s_nop 0
	v_add_f32_e32 v230, 1.0, v230
	v_add_f32_e32 v231, 1.0, v231
	v_div_scale_f32 v220, s[66:67], v230, v230, 1.0
	v_rcp_f32_e32 v221, v220
	s_nop 0
	v_fma_f32 v222, -v220, v221, 1.0
	v_fmac_f32_e32 v221, v222, v221
	v_div_scale_f32 v223, vcc, 1.0, v230, 1.0
	v_mul_f32_e32 v224, v223, v221
	v_fma_f32 v222, -v220, v224, v223
	v_fmac_f32_e32 v224, v222, v221
	v_fma_f32 v220, -v220, v224, v223
	v_div_fmas_f32 v220, v220, v221, v224
	v_div_fixup_f32 v184, v220, v230, 1.0
	v_div_scale_f32 v225, s[66:67], v231, v231, 1.0
	v_rcp_f32_e32 v226, v225
	s_nop 0
	v_fma_f32 v227, -v225, v226, 1.0
	v_fmac_f32_e32 v226, v227, v226
	v_div_scale_f32 v228, vcc, 1.0, v231, 1.0
	v_mul_f32_e32 v229, v228, v226
	v_fma_f32 v227, -v225, v229, v228
	v_fmac_f32_e32 v229, v227, v226
	v_fma_f32 v225, -v225, v229, v228
	v_div_fmas_f32 v225, v225, v226, v229
	v_div_fixup_f32 v185, v225, v231, 1.0
	v_cvt_pk_bf16_f32 v189, v184, v185
	v_mul_f32_e32 v230, 0xbfb8aa3b, v182
	v_mul_f32_e32 v231, 0xbfb8aa3b, v183
	v_exp_f32_e32 v230, v230
	v_exp_f32_e32 v231, v231
	s_nop 0
	v_add_f32_e32 v230, 1.0, v230
	v_add_f32_e32 v231, 1.0, v231
	v_div_scale_f32 v220, s[66:67], v230, v230, 1.0
	v_rcp_f32_e32 v221, v220
	s_nop 0
	v_fma_f32 v222, -v220, v221, 1.0
	v_fmac_f32_e32 v221, v222, v221
	v_div_scale_f32 v223, vcc, 1.0, v230, 1.0
	v_mul_f32_e32 v224, v223, v221
	v_fma_f32 v222, -v220, v224, v223
	v_fmac_f32_e32 v224, v222, v221
	v_fma_f32 v220, -v220, v224, v223
	v_div_fmas_f32 v220, v220, v221, v224
	v_div_fixup_f32 v182, v220, v230, 1.0
	v_div_scale_f32 v225, s[66:67], v231, v231, 1.0
	v_rcp_f32_e32 v226, v225
	s_nop 0
	v_fma_f32 v227, -v225, v226, 1.0
	v_fmac_f32_e32 v226, v227, v226
	v_div_scale_f32 v228, vcc, 1.0, v231, 1.0
	v_mul_f32_e32 v229, v228, v226
	v_fma_f32 v227, -v225, v229, v228
	v_fmac_f32_e32 v229, v227, v226
	v_fma_f32 v225, -v225, v229, v228
	v_div_fmas_f32 v225, v225, v226, v229
	v_div_fixup_f32 v183, v225, v231, 1.0
	v_cvt_pk_bf16_f32 v188, v182, v183
	v_mul_f32_e32 v230, 0xbfb8aa3b, v180
	v_mul_f32_e32 v231, 0xbfb8aa3b, v181
	v_exp_f32_e32 v230, v230
	v_exp_f32_e32 v231, v231
	s_nop 0
	v_add_f32_e32 v230, 1.0, v230
	v_add_f32_e32 v231, 1.0, v231
	v_div_scale_f32 v220, s[66:67], v230, v230, 1.0
	v_rcp_f32_e32 v221, v220
	s_nop 0
	v_fma_f32 v222, -v220, v221, 1.0
	v_fmac_f32_e32 v221, v222, v221
	v_div_scale_f32 v223, vcc, 1.0, v230, 1.0
	v_mul_f32_e32 v224, v223, v221
	v_fma_f32 v222, -v220, v224, v223
	v_fmac_f32_e32 v224, v222, v221
	v_fma_f32 v220, -v220, v224, v223
	v_div_fmas_f32 v220, v220, v221, v224
	v_div_fixup_f32 v180, v220, v230, 1.0
	v_div_scale_f32 v225, s[66:67], v231, v231, 1.0
	v_rcp_f32_e32 v226, v225
	s_nop 0
	v_fma_f32 v227, -v225, v226, 1.0
	v_fmac_f32_e32 v226, v227, v226
	v_div_scale_f32 v228, vcc, 1.0, v231, 1.0
	v_mul_f32_e32 v229, v228, v226
	v_fma_f32 v227, -v225, v229, v228
	v_fmac_f32_e32 v229, v227, v226
	v_fma_f32 v225, -v225, v229, v228
	v_div_fmas_f32 v225, v225, v226, v229
	v_div_fixup_f32 v181, v225, v231, 1.0
	v_cvt_pk_bf16_f32 v187, v180, v181
	v_mul_f32_e32 v230, 0xbfb8aa3b, v178
	v_mul_f32_e32 v231, 0xbfb8aa3b, v179
	v_exp_f32_e32 v230, v230
	v_exp_f32_e32 v231, v231
	s_nop 0
	v_add_f32_e32 v230, 1.0, v230
	v_add_f32_e32 v231, 1.0, v231
	v_div_scale_f32 v220, s[66:67], v230, v230, 1.0
	v_rcp_f32_e32 v221, v220
	s_nop 0
	v_fma_f32 v222, -v220, v221, 1.0
	v_fmac_f32_e32 v221, v222, v221
	v_div_scale_f32 v223, vcc, 1.0, v230, 1.0
	v_mul_f32_e32 v224, v223, v221
	v_fma_f32 v222, -v220, v224, v223
	v_fmac_f32_e32 v224, v222, v221
	v_fma_f32 v220, -v220, v224, v223
	v_div_fmas_f32 v220, v220, v221, v224
	v_div_fixup_f32 v178, v220, v230, 1.0
	v_div_scale_f32 v225, s[66:67], v231, v231, 1.0
	v_rcp_f32_e32 v226, v225
	s_nop 0
	v_fma_f32 v227, -v225, v226, 1.0
	v_fmac_f32_e32 v226, v227, v226
	v_div_scale_f32 v228, vcc, 1.0, v231, 1.0
	v_mul_f32_e32 v229, v228, v226
	v_fma_f32 v227, -v225, v229, v228
	v_fmac_f32_e32 v229, v227, v226
	v_fma_f32 v225, -v225, v229, v228
	v_div_fmas_f32 v225, v225, v226, v229
	v_div_fixup_f32 v179, v225, v231, 1.0
	v_cvt_pk_bf16_f32 v186, v178, v179
	v_mul_f32_e32 v230, 0xbfb8aa3b, v176
	v_mul_f32_e32 v231, 0xbfb8aa3b, v177
	v_exp_f32_e32 v230, v230
	v_exp_f32_e32 v231, v231
	s_nop 0
	v_add_f32_e32 v230, 1.0, v230
	v_add_f32_e32 v231, 1.0, v231
	v_div_scale_f32 v220, s[66:67], v230, v230, 1.0
	v_rcp_f32_e32 v221, v220
	s_nop 0
	v_fma_f32 v222, -v220, v221, 1.0
	v_fmac_f32_e32 v221, v222, v221
	v_div_scale_f32 v223, vcc, 1.0, v230, 1.0
	v_mul_f32_e32 v224, v223, v221
	v_fma_f32 v222, -v220, v224, v223
	v_fmac_f32_e32 v224, v222, v221
	v_fma_f32 v220, -v220, v224, v223
	v_div_fmas_f32 v220, v220, v221, v224
	v_div_fixup_f32 v176, v220, v230, 1.0
	v_div_scale_f32 v225, s[66:67], v231, v231, 1.0
	v_rcp_f32_e32 v226, v225
	s_nop 0
	v_fma_f32 v227, -v225, v226, 1.0
	v_fmac_f32_e32 v226, v227, v226
	v_div_scale_f32 v228, vcc, 1.0, v231, 1.0
	v_mul_f32_e32 v229, v228, v226
	v_fma_f32 v227, -v225, v229, v228
	v_fmac_f32_e32 v229, v227, v226
	v_fma_f32 v225, -v225, v229, v228
	v_div_fmas_f32 v225, v225, v226, v229
	v_div_fixup_f32 v177, v225, v231, 1.0
	v_cvt_pk_bf16_f32 v185, v176, v177
	v_mul_f32_e32 v230, 0xbfb8aa3b, v174
	v_mul_f32_e32 v231, 0xbfb8aa3b, v175
	v_exp_f32_e32 v230, v230
	v_exp_f32_e32 v231, v231
	s_nop 0
	v_add_f32_e32 v230, 1.0, v230
	v_add_f32_e32 v231, 1.0, v231
	v_div_scale_f32 v220, s[66:67], v230, v230, 1.0
	v_rcp_f32_e32 v221, v220
	s_nop 0
	v_fma_f32 v222, -v220, v221, 1.0
	v_fmac_f32_e32 v221, v222, v221
	v_div_scale_f32 v223, vcc, 1.0, v230, 1.0
	v_mul_f32_e32 v224, v223, v221
	v_fma_f32 v222, -v220, v224, v223
	v_fmac_f32_e32 v224, v222, v221
	v_fma_f32 v220, -v220, v224, v223
	v_div_fmas_f32 v220, v220, v221, v224
	v_div_fixup_f32 v174, v220, v230, 1.0
	v_div_scale_f32 v225, s[66:67], v231, v231, 1.0
	v_rcp_f32_e32 v226, v225
	s_nop 0
	v_fma_f32 v227, -v225, v226, 1.0
	v_fmac_f32_e32 v226, v227, v226
	v_div_scale_f32 v228, vcc, 1.0, v231, 1.0
	v_mul_f32_e32 v229, v228, v226
	v_fma_f32 v227, -v225, v229, v228
	v_fmac_f32_e32 v229, v227, v226
	v_fma_f32 v225, -v225, v229, v228
	v_div_fmas_f32 v225, v225, v226, v229
	v_div_fixup_f32 v175, v225, v231, 1.0
	v_cvt_pk_bf16_f32 v184, v174, v175
	v_mul_f32_e32 v230, 0xbfb8aa3b, v172
	v_mul_f32_e32 v231, 0xbfb8aa3b, v173
	v_exp_f32_e32 v230, v230
	v_exp_f32_e32 v231, v231
	s_nop 0
	v_add_f32_e32 v230, 1.0, v230
	v_add_f32_e32 v231, 1.0, v231
	v_div_scale_f32 v220, s[66:67], v230, v230, 1.0
	v_rcp_f32_e32 v221, v220
	s_nop 0
	v_fma_f32 v222, -v220, v221, 1.0
	v_fmac_f32_e32 v221, v222, v221
	v_div_scale_f32 v223, vcc, 1.0, v230, 1.0
	v_mul_f32_e32 v224, v223, v221
	v_fma_f32 v222, -v220, v224, v223
	v_fmac_f32_e32 v224, v222, v221
	v_fma_f32 v220, -v220, v224, v223
	v_div_fmas_f32 v220, v220, v221, v224
	v_div_fixup_f32 v172, v220, v230, 1.0
	v_div_scale_f32 v225, s[66:67], v231, v231, 1.0
	v_rcp_f32_e32 v226, v225
	s_nop 0
	v_fma_f32 v227, -v225, v226, 1.0
	v_fmac_f32_e32 v226, v227, v226
	v_div_scale_f32 v228, vcc, 1.0, v231, 1.0
	v_mul_f32_e32 v229, v228, v226
	v_fma_f32 v227, -v225, v229, v228
	v_fmac_f32_e32 v229, v227, v226
	v_fma_f32 v225, -v225, v229, v228
	v_div_fmas_f32 v225, v225, v226, v229
	v_div_fixup_f32 v173, v225, v231, 1.0
	v_cvt_pk_bf16_f32 v183, v172, v173
	v_mul_f32_e32 v230, 0xbfb8aa3b, v170
	v_mul_f32_e32 v231, 0xbfb8aa3b, v171
	v_exp_f32_e32 v230, v230
	v_exp_f32_e32 v231, v231
	s_nop 0
	v_add_f32_e32 v230, 1.0, v230
	v_add_f32_e32 v231, 1.0, v231
	v_div_scale_f32 v220, s[66:67], v230, v230, 1.0
	v_rcp_f32_e32 v221, v220
	s_nop 0
	v_fma_f32 v222, -v220, v221, 1.0
	v_fmac_f32_e32 v221, v222, v221
	v_div_scale_f32 v223, vcc, 1.0, v230, 1.0
	v_mul_f32_e32 v224, v223, v221
	v_fma_f32 v222, -v220, v224, v223
	v_fmac_f32_e32 v224, v222, v221
	v_fma_f32 v220, -v220, v224, v223
	v_div_fmas_f32 v220, v220, v221, v224
	v_div_fixup_f32 v170, v220, v230, 1.0
	v_div_scale_f32 v225, s[66:67], v231, v231, 1.0
	v_rcp_f32_e32 v226, v225
	s_nop 0
	v_fma_f32 v227, -v225, v226, 1.0
	v_fmac_f32_e32 v226, v227, v226
	v_div_scale_f32 v228, vcc, 1.0, v231, 1.0
	v_mul_f32_e32 v229, v228, v226
	v_fma_f32 v227, -v225, v229, v228
	v_fmac_f32_e32 v229, v227, v226
	v_fma_f32 v225, -v225, v229, v228
	v_div_fmas_f32 v225, v225, v226, v229
	v_div_fixup_f32 v171, v225, v231, 1.0
	v_cvt_pk_bf16_f32 v182, v170, v171
	v_mul_f32_e32 v230, 0xbfb8aa3b, v168
	v_mul_f32_e32 v231, 0xbfb8aa3b, v169
	v_exp_f32_e32 v230, v230
	v_exp_f32_e32 v231, v231
	s_nop 0
	v_add_f32_e32 v230, 1.0, v230
	v_add_f32_e32 v231, 1.0, v231
	v_div_scale_f32 v220, s[66:67], v230, v230, 1.0
	v_rcp_f32_e32 v221, v220
	s_nop 0
	v_fma_f32 v222, -v220, v221, 1.0
	v_fmac_f32_e32 v221, v222, v221
	v_div_scale_f32 v223, vcc, 1.0, v230, 1.0
	v_mul_f32_e32 v224, v223, v221
	v_fma_f32 v222, -v220, v224, v223
	v_fmac_f32_e32 v224, v222, v221
	v_fma_f32 v220, -v220, v224, v223
	v_div_fmas_f32 v220, v220, v221, v224
	v_div_fixup_f32 v168, v220, v230, 1.0
	v_div_scale_f32 v225, s[66:67], v231, v231, 1.0
	v_rcp_f32_e32 v226, v225
	s_nop 0
	v_fma_f32 v227, -v225, v226, 1.0
	v_fmac_f32_e32 v226, v227, v226
	v_div_scale_f32 v228, vcc, 1.0, v231, 1.0
	v_mul_f32_e32 v229, v228, v226
	v_fma_f32 v227, -v225, v229, v228
	v_fmac_f32_e32 v229, v227, v226
	v_fma_f32 v225, -v225, v229, v228
	v_div_fmas_f32 v225, v225, v226, v229
	v_div_fixup_f32 v169, v225, v231, 1.0
	v_cvt_pk_bf16_f32 v181, v168, v169
	v_mul_f32_e32 v230, 0xbfb8aa3b, v166
	v_mul_f32_e32 v231, 0xbfb8aa3b, v167
	v_exp_f32_e32 v230, v230
	v_exp_f32_e32 v231, v231
	s_nop 0
	v_add_f32_e32 v230, 1.0, v230
	v_add_f32_e32 v231, 1.0, v231
	v_div_scale_f32 v220, s[66:67], v230, v230, 1.0
	v_rcp_f32_e32 v221, v220
	s_nop 0
	v_fma_f32 v222, -v220, v221, 1.0
	v_fmac_f32_e32 v221, v222, v221
	v_div_scale_f32 v223, vcc, 1.0, v230, 1.0
	v_mul_f32_e32 v224, v223, v221
	v_fma_f32 v222, -v220, v224, v223
	v_fmac_f32_e32 v224, v222, v221
	v_fma_f32 v220, -v220, v224, v223
	v_div_fmas_f32 v220, v220, v221, v224
	v_div_fixup_f32 v166, v220, v230, 1.0
	v_div_scale_f32 v225, s[66:67], v231, v231, 1.0
	v_rcp_f32_e32 v226, v225
	s_nop 0
	v_fma_f32 v227, -v225, v226, 1.0
	v_fmac_f32_e32 v226, v227, v226
	v_div_scale_f32 v228, vcc, 1.0, v231, 1.0
	v_mul_f32_e32 v229, v228, v226
	v_fma_f32 v227, -v225, v229, v228
	v_fmac_f32_e32 v229, v227, v226
	v_fma_f32 v225, -v225, v229, v228
	v_div_fmas_f32 v225, v225, v226, v229
	v_div_fixup_f32 v167, v225, v231, 1.0
	v_cvt_pk_bf16_f32 v180, v166, v167
	v_mul_f32_e32 v230, 0xbfb8aa3b, v164
	v_mul_f32_e32 v231, 0xbfb8aa3b, v165
	v_exp_f32_e32 v230, v230
	v_exp_f32_e32 v231, v231
	s_nop 0
	v_add_f32_e32 v230, 1.0, v230
	v_add_f32_e32 v231, 1.0, v231
	v_div_scale_f32 v220, s[66:67], v230, v230, 1.0
	v_rcp_f32_e32 v221, v220
	s_nop 0
	v_fma_f32 v222, -v220, v221, 1.0
	v_fmac_f32_e32 v221, v222, v221
	v_div_scale_f32 v223, vcc, 1.0, v230, 1.0
	v_mul_f32_e32 v224, v223, v221
	v_fma_f32 v222, -v220, v224, v223
	v_fmac_f32_e32 v224, v222, v221
	v_fma_f32 v220, -v220, v224, v223
	v_div_fmas_f32 v220, v220, v221, v224
	v_div_fixup_f32 v164, v220, v230, 1.0
	v_div_scale_f32 v225, s[66:67], v231, v231, 1.0
	v_rcp_f32_e32 v226, v225
	s_nop 0
	v_fma_f32 v227, -v225, v226, 1.0
	v_fmac_f32_e32 v226, v227, v226
	v_div_scale_f32 v228, vcc, 1.0, v231, 1.0
	v_mul_f32_e32 v229, v228, v226
	v_fma_f32 v227, -v225, v229, v228
	v_fmac_f32_e32 v229, v227, v226
	v_fma_f32 v225, -v225, v229, v228
	v_div_fmas_f32 v225, v225, v226, v229
	v_div_fixup_f32 v165, v225, v231, 1.0
	v_cvt_pk_bf16_f32 v179, v164, v165
	v_mul_f32_e32 v230, 0xbfb8aa3b, v162
	v_mul_f32_e32 v231, 0xbfb8aa3b, v163
	v_exp_f32_e32 v230, v230
	v_exp_f32_e32 v231, v231
	s_nop 0
	v_add_f32_e32 v230, 1.0, v230
	v_add_f32_e32 v231, 1.0, v231
	v_div_scale_f32 v220, s[66:67], v230, v230, 1.0
	v_rcp_f32_e32 v221, v220
	s_nop 0
	v_fma_f32 v222, -v220, v221, 1.0
	v_fmac_f32_e32 v221, v222, v221
	v_div_scale_f32 v223, vcc, 1.0, v230, 1.0
	v_mul_f32_e32 v224, v223, v221
	v_fma_f32 v222, -v220, v224, v223
	v_fmac_f32_e32 v224, v222, v221
	v_fma_f32 v220, -v220, v224, v223
	v_div_fmas_f32 v220, v220, v221, v224
	v_div_fixup_f32 v162, v220, v230, 1.0
	v_div_scale_f32 v225, s[66:67], v231, v231, 1.0
	v_rcp_f32_e32 v226, v225
	s_nop 0
	v_fma_f32 v227, -v225, v226, 1.0
	v_fmac_f32_e32 v226, v227, v226
	v_div_scale_f32 v228, vcc, 1.0, v231, 1.0
	v_mul_f32_e32 v229, v228, v226
	v_fma_f32 v227, -v225, v229, v228
	v_fmac_f32_e32 v229, v227, v226
	v_fma_f32 v225, -v225, v229, v228
	v_div_fmas_f32 v225, v225, v226, v229
	v_div_fixup_f32 v163, v225, v231, 1.0
	v_cvt_pk_bf16_f32 v178, v162, v163
	v_mul_f32_e32 v230, 0xbfb8aa3b, v160
	v_mul_f32_e32 v231, 0xbfb8aa3b, v161
	v_exp_f32_e32 v230, v230
	v_exp_f32_e32 v231, v231
	s_nop 0
	v_add_f32_e32 v230, 1.0, v230
	v_add_f32_e32 v231, 1.0, v231
	v_div_scale_f32 v220, s[66:67], v230, v230, 1.0
	v_rcp_f32_e32 v221, v220
	s_nop 0
	v_fma_f32 v222, -v220, v221, 1.0
	v_fmac_f32_e32 v221, v222, v221
	v_div_scale_f32 v223, vcc, 1.0, v230, 1.0
	v_mul_f32_e32 v224, v223, v221
	v_fma_f32 v222, -v220, v224, v223
	v_fmac_f32_e32 v224, v222, v221
	v_fma_f32 v220, -v220, v224, v223
	v_div_fmas_f32 v220, v220, v221, v224
	v_div_fixup_f32 v160, v220, v230, 1.0
	v_div_scale_f32 v225, s[66:67], v231, v231, 1.0
	v_rcp_f32_e32 v226, v225
	s_nop 0
	v_fma_f32 v227, -v225, v226, 1.0
	v_fmac_f32_e32 v226, v227, v226
	v_div_scale_f32 v228, vcc, 1.0, v231, 1.0
	v_mul_f32_e32 v229, v228, v226
	v_fma_f32 v227, -v225, v229, v228
	v_fmac_f32_e32 v229, v227, v226
	v_fma_f32 v225, -v225, v229, v228
	v_div_fmas_f32 v225, v225, v226, v229
	v_div_fixup_f32 v161, v225, v231, 1.0
	v_cvt_pk_bf16_f32 v177, v160, v161
	v_mul_f32_e32 v230, 0xbfb8aa3b, v158
	v_mul_f32_e32 v231, 0xbfb8aa3b, v159
	v_exp_f32_e32 v230, v230
	v_exp_f32_e32 v231, v231
	s_nop 0
	v_add_f32_e32 v230, 1.0, v230
	v_add_f32_e32 v231, 1.0, v231
	v_div_scale_f32 v220, s[66:67], v230, v230, 1.0
	v_rcp_f32_e32 v221, v220
	s_nop 0
	v_fma_f32 v222, -v220, v221, 1.0
	v_fmac_f32_e32 v221, v222, v221
	v_div_scale_f32 v223, vcc, 1.0, v230, 1.0
	v_mul_f32_e32 v224, v223, v221
	v_fma_f32 v222, -v220, v224, v223
	v_fmac_f32_e32 v224, v222, v221
	v_fma_f32 v220, -v220, v224, v223
	v_div_fmas_f32 v220, v220, v221, v224
	v_div_fixup_f32 v158, v220, v230, 1.0
	v_div_scale_f32 v225, s[66:67], v231, v231, 1.0
	v_rcp_f32_e32 v226, v225
	s_nop 0
	v_fma_f32 v227, -v225, v226, 1.0
	v_fmac_f32_e32 v226, v227, v226
	v_div_scale_f32 v228, vcc, 1.0, v231, 1.0
	v_mul_f32_e32 v229, v228, v226
	v_fma_f32 v227, -v225, v229, v228
	v_fmac_f32_e32 v229, v227, v226
	v_fma_f32 v225, -v225, v229, v228
	v_div_fmas_f32 v225, v225, v226, v229
	v_div_fixup_f32 v159, v225, v231, 1.0
	v_cvt_pk_bf16_f32 v176, v158, v159
	v_mul_f32_e32 v230, 0xbfb8aa3b, v156
	v_mul_f32_e32 v231, 0xbfb8aa3b, v157
	v_exp_f32_e32 v230, v230
	v_exp_f32_e32 v231, v231
	s_nop 0
	v_add_f32_e32 v230, 1.0, v230
	v_add_f32_e32 v231, 1.0, v231
	v_div_scale_f32 v220, s[66:67], v230, v230, 1.0
	v_rcp_f32_e32 v221, v220
	s_nop 0
	v_fma_f32 v222, -v220, v221, 1.0
	v_fmac_f32_e32 v221, v222, v221
	v_div_scale_f32 v223, vcc, 1.0, v230, 1.0
	v_mul_f32_e32 v224, v223, v221
	v_fma_f32 v222, -v220, v224, v223
	v_fmac_f32_e32 v224, v222, v221
	v_fma_f32 v220, -v220, v224, v223
	v_div_fmas_f32 v220, v220, v221, v224
	v_div_fixup_f32 v156, v220, v230, 1.0
	v_div_scale_f32 v225, s[66:67], v231, v231, 1.0
	v_rcp_f32_e32 v226, v225
	s_nop 0
	v_fma_f32 v227, -v225, v226, 1.0
	v_fmac_f32_e32 v226, v227, v226
	v_div_scale_f32 v228, vcc, 1.0, v231, 1.0
	v_mul_f32_e32 v229, v228, v226
	v_fma_f32 v227, -v225, v229, v228
	v_fmac_f32_e32 v229, v227, v226
	v_fma_f32 v225, -v225, v229, v228
	v_div_fmas_f32 v225, v225, v226, v229
	v_div_fixup_f32 v157, v225, v231, 1.0
	v_cvt_pk_bf16_f32 v175, v156, v157
	v_mul_f32_e32 v230, 0xbfb8aa3b, v154
	v_mul_f32_e32 v231, 0xbfb8aa3b, v155
	v_exp_f32_e32 v230, v230
	v_exp_f32_e32 v231, v231
	s_nop 0
	v_add_f32_e32 v230, 1.0, v230
	v_add_f32_e32 v231, 1.0, v231
	v_div_scale_f32 v220, s[66:67], v230, v230, 1.0
	v_rcp_f32_e32 v221, v220
	s_nop 0
	v_fma_f32 v222, -v220, v221, 1.0
	v_fmac_f32_e32 v221, v222, v221
	v_div_scale_f32 v223, vcc, 1.0, v230, 1.0
	v_mul_f32_e32 v224, v223, v221
	v_fma_f32 v222, -v220, v224, v223
	v_fmac_f32_e32 v224, v222, v221
	v_fma_f32 v220, -v220, v224, v223
	v_div_fmas_f32 v220, v220, v221, v224
	v_div_fixup_f32 v154, v220, v230, 1.0
	v_div_scale_f32 v225, s[66:67], v231, v231, 1.0
	v_rcp_f32_e32 v226, v225
	s_nop 0
	v_fma_f32 v227, -v225, v226, 1.0
	v_fmac_f32_e32 v226, v227, v226
	v_div_scale_f32 v228, vcc, 1.0, v231, 1.0
	v_mul_f32_e32 v229, v228, v226
	v_fma_f32 v227, -v225, v229, v228
	v_fmac_f32_e32 v229, v227, v226
	v_fma_f32 v225, -v225, v229, v228
	v_div_fmas_f32 v225, v225, v226, v229
	v_div_fixup_f32 v155, v225, v231, 1.0
	v_cvt_pk_bf16_f32 v174, v154, v155
	v_mul_f32_e32 v230, 0xbfb8aa3b, v152
	v_mul_f32_e32 v231, 0xbfb8aa3b, v153
	v_exp_f32_e32 v230, v230
	v_exp_f32_e32 v231, v231
	s_nop 0
	v_add_f32_e32 v230, 1.0, v230
	v_add_f32_e32 v231, 1.0, v231
	v_div_scale_f32 v220, s[66:67], v230, v230, 1.0
	v_rcp_f32_e32 v221, v220
	s_nop 0
	v_fma_f32 v222, -v220, v221, 1.0
	v_fmac_f32_e32 v221, v222, v221
	v_div_scale_f32 v223, vcc, 1.0, v230, 1.0
	v_mul_f32_e32 v224, v223, v221
	v_fma_f32 v222, -v220, v224, v223
	v_fmac_f32_e32 v224, v222, v221
	v_fma_f32 v220, -v220, v224, v223
	v_div_fmas_f32 v220, v220, v221, v224
	v_div_fixup_f32 v152, v220, v230, 1.0
	v_div_scale_f32 v225, s[66:67], v231, v231, 1.0
	v_rcp_f32_e32 v226, v225
	s_nop 0
	v_fma_f32 v227, -v225, v226, 1.0
	v_fmac_f32_e32 v226, v227, v226
	v_div_scale_f32 v228, vcc, 1.0, v231, 1.0
	v_mul_f32_e32 v229, v228, v226
	v_fma_f32 v227, -v225, v229, v228
	v_fmac_f32_e32 v229, v227, v226
	v_fma_f32 v225, -v225, v229, v228
	v_div_fmas_f32 v225, v225, v226, v229
	v_div_fixup_f32 v153, v225, v231, 1.0
	v_cvt_pk_bf16_f32 v173, v152, v153
	v_mul_f32_e32 v230, 0xbfb8aa3b, v150
	v_mul_f32_e32 v231, 0xbfb8aa3b, v151
	v_exp_f32_e32 v230, v230
	v_exp_f32_e32 v231, v231
	s_nop 0
	v_add_f32_e32 v230, 1.0, v230
	v_add_f32_e32 v231, 1.0, v231
	v_div_scale_f32 v220, s[66:67], v230, v230, 1.0
	v_rcp_f32_e32 v221, v220
	s_nop 0
	v_fma_f32 v222, -v220, v221, 1.0
	v_fmac_f32_e32 v221, v222, v221
	v_div_scale_f32 v223, vcc, 1.0, v230, 1.0
	v_mul_f32_e32 v224, v223, v221
	v_fma_f32 v222, -v220, v224, v223
	v_fmac_f32_e32 v224, v222, v221
	v_fma_f32 v220, -v220, v224, v223
	v_div_fmas_f32 v220, v220, v221, v224
	v_div_fixup_f32 v150, v220, v230, 1.0
	v_div_scale_f32 v225, s[66:67], v231, v231, 1.0
	v_rcp_f32_e32 v226, v225
	s_nop 0
	v_fma_f32 v227, -v225, v226, 1.0
	v_fmac_f32_e32 v226, v227, v226
	v_div_scale_f32 v228, vcc, 1.0, v231, 1.0
	v_mul_f32_e32 v229, v228, v226
	v_fma_f32 v227, -v225, v229, v228
	v_fmac_f32_e32 v229, v227, v226
	v_fma_f32 v225, -v225, v229, v228
	v_div_fmas_f32 v225, v225, v226, v229
	v_div_fixup_f32 v151, v225, v231, 1.0
	v_cvt_pk_bf16_f32 v172, v150, v151
	v_mul_f32_e32 v230, 0xbfb8aa3b, v148
	v_mul_f32_e32 v231, 0xbfb8aa3b, v149
	v_exp_f32_e32 v230, v230
	v_exp_f32_e32 v231, v231
	s_nop 0
	v_add_f32_e32 v230, 1.0, v230
	v_add_f32_e32 v231, 1.0, v231
	v_div_scale_f32 v220, s[66:67], v230, v230, 1.0
	v_rcp_f32_e32 v221, v220
	s_nop 0
	v_fma_f32 v222, -v220, v221, 1.0
	v_fmac_f32_e32 v221, v222, v221
	v_div_scale_f32 v223, vcc, 1.0, v230, 1.0
	v_mul_f32_e32 v224, v223, v221
	v_fma_f32 v222, -v220, v224, v223
	v_fmac_f32_e32 v224, v222, v221
	v_fma_f32 v220, -v220, v224, v223
	v_div_fmas_f32 v220, v220, v221, v224
	v_div_fixup_f32 v148, v220, v230, 1.0
	v_div_scale_f32 v225, s[66:67], v231, v231, 1.0
	v_rcp_f32_e32 v226, v225
	s_nop 0
	v_fma_f32 v227, -v225, v226, 1.0
	v_fmac_f32_e32 v226, v227, v226
	v_div_scale_f32 v228, vcc, 1.0, v231, 1.0
	v_mul_f32_e32 v229, v228, v226
	v_fma_f32 v227, -v225, v229, v228
	v_fmac_f32_e32 v229, v227, v226
	v_fma_f32 v225, -v225, v229, v228
	v_div_fmas_f32 v225, v225, v226, v229
	v_div_fixup_f32 v149, v225, v231, 1.0
	v_cvt_pk_bf16_f32 v171, v148, v149
	v_mul_f32_e32 v230, 0xbfb8aa3b, v146
	v_mul_f32_e32 v231, 0xbfb8aa3b, v147
	v_exp_f32_e32 v230, v230
	v_exp_f32_e32 v231, v231
	s_nop 0
	v_add_f32_e32 v230, 1.0, v230
	v_add_f32_e32 v231, 1.0, v231
	v_div_scale_f32 v220, s[66:67], v230, v230, 1.0
	v_rcp_f32_e32 v221, v220
	s_nop 0
	v_fma_f32 v222, -v220, v221, 1.0
	v_fmac_f32_e32 v221, v222, v221
	v_div_scale_f32 v223, vcc, 1.0, v230, 1.0
	v_mul_f32_e32 v224, v223, v221
	v_fma_f32 v222, -v220, v224, v223
	v_fmac_f32_e32 v224, v222, v221
	v_fma_f32 v220, -v220, v224, v223
	v_div_fmas_f32 v220, v220, v221, v224
	v_div_fixup_f32 v146, v220, v230, 1.0
	v_div_scale_f32 v225, s[66:67], v231, v231, 1.0
	v_rcp_f32_e32 v226, v225
	s_nop 0
	v_fma_f32 v227, -v225, v226, 1.0
	v_fmac_f32_e32 v226, v227, v226
	v_div_scale_f32 v228, vcc, 1.0, v231, 1.0
	v_mul_f32_e32 v229, v228, v226
	v_fma_f32 v227, -v225, v229, v228
	v_fmac_f32_e32 v229, v227, v226
	v_fma_f32 v225, -v225, v229, v228
	v_div_fmas_f32 v225, v225, v226, v229
	v_div_fixup_f32 v147, v225, v231, 1.0
	v_cvt_pk_bf16_f32 v170, v146, v147
	v_mul_f32_e32 v230, 0xbfb8aa3b, v144
	v_mul_f32_e32 v231, 0xbfb8aa3b, v145
	v_exp_f32_e32 v230, v230
	v_exp_f32_e32 v231, v231
	s_nop 0
	v_add_f32_e32 v230, 1.0, v230
	v_add_f32_e32 v231, 1.0, v231
	v_div_scale_f32 v220, s[66:67], v230, v230, 1.0
	v_rcp_f32_e32 v221, v220
	s_nop 0
	v_fma_f32 v222, -v220, v221, 1.0
	v_fmac_f32_e32 v221, v222, v221
	v_div_scale_f32 v223, vcc, 1.0, v230, 1.0
	v_mul_f32_e32 v224, v223, v221
	v_fma_f32 v222, -v220, v224, v223
	v_fmac_f32_e32 v224, v222, v221
	v_fma_f32 v220, -v220, v224, v223
	v_div_fmas_f32 v220, v220, v221, v224
	v_div_fixup_f32 v144, v220, v230, 1.0
	v_div_scale_f32 v225, s[66:67], v231, v231, 1.0
	v_rcp_f32_e32 v226, v225
	s_nop 0
	v_fma_f32 v227, -v225, v226, 1.0
	v_fmac_f32_e32 v226, v227, v226
	v_div_scale_f32 v228, vcc, 1.0, v231, 1.0
	v_mul_f32_e32 v229, v228, v226
	v_fma_f32 v227, -v225, v229, v228
	v_fmac_f32_e32 v229, v227, v226
	v_fma_f32 v225, -v225, v229, v228
	v_div_fmas_f32 v225, v225, v226, v229
	v_div_fixup_f32 v145, v225, v231, 1.0
	v_cvt_pk_bf16_f32 v169, v144, v145
	v_mul_f32_e32 v230, 0xbfb8aa3b, v142
	v_mul_f32_e32 v231, 0xbfb8aa3b, v143
	v_exp_f32_e32 v230, v230
	v_exp_f32_e32 v231, v231
	s_nop 0
	v_add_f32_e32 v230, 1.0, v230
	v_add_f32_e32 v231, 1.0, v231
	v_div_scale_f32 v220, s[66:67], v230, v230, 1.0
	v_rcp_f32_e32 v221, v220
	s_nop 0
	v_fma_f32 v222, -v220, v221, 1.0
	v_fmac_f32_e32 v221, v222, v221
	v_div_scale_f32 v223, vcc, 1.0, v230, 1.0
	v_mul_f32_e32 v224, v223, v221
	v_fma_f32 v222, -v220, v224, v223
	v_fmac_f32_e32 v224, v222, v221
	v_fma_f32 v220, -v220, v224, v223
	v_div_fmas_f32 v220, v220, v221, v224
	v_div_fixup_f32 v142, v220, v230, 1.0
	v_div_scale_f32 v225, s[66:67], v231, v231, 1.0
	v_rcp_f32_e32 v226, v225
	s_nop 0
	v_fma_f32 v227, -v225, v226, 1.0
	v_fmac_f32_e32 v226, v227, v226
	v_div_scale_f32 v228, vcc, 1.0, v231, 1.0
	v_mul_f32_e32 v229, v228, v226
	v_fma_f32 v227, -v225, v229, v228
	v_fmac_f32_e32 v229, v227, v226
	v_fma_f32 v225, -v225, v229, v228
	v_div_fmas_f32 v225, v225, v226, v229
	v_div_fixup_f32 v143, v225, v231, 1.0
	v_cvt_pk_bf16_f32 v168, v142, v143
	v_mul_f32_e32 v230, 0xbfb8aa3b, v140
	v_mul_f32_e32 v231, 0xbfb8aa3b, v141
	v_exp_f32_e32 v230, v230
	v_exp_f32_e32 v231, v231
	s_nop 0
	v_add_f32_e32 v230, 1.0, v230
	v_add_f32_e32 v231, 1.0, v231
	v_div_scale_f32 v220, s[66:67], v230, v230, 1.0
	v_rcp_f32_e32 v221, v220
	s_nop 0
	v_fma_f32 v222, -v220, v221, 1.0
	v_fmac_f32_e32 v221, v222, v221
	v_div_scale_f32 v223, vcc, 1.0, v230, 1.0
	v_mul_f32_e32 v224, v223, v221
	v_fma_f32 v222, -v220, v224, v223
	v_fmac_f32_e32 v224, v222, v221
	v_fma_f32 v220, -v220, v224, v223
	v_div_fmas_f32 v220, v220, v221, v224
	v_div_fixup_f32 v140, v220, v230, 1.0
	v_div_scale_f32 v225, s[66:67], v231, v231, 1.0
	v_rcp_f32_e32 v226, v225
	s_nop 0
	v_fma_f32 v227, -v225, v226, 1.0
	v_fmac_f32_e32 v226, v227, v226
	v_div_scale_f32 v228, vcc, 1.0, v231, 1.0
	v_mul_f32_e32 v229, v228, v226
	v_fma_f32 v227, -v225, v229, v228
	v_fmac_f32_e32 v229, v227, v226
	v_fma_f32 v225, -v225, v229, v228
	v_div_fmas_f32 v225, v225, v226, v229
	v_div_fixup_f32 v141, v225, v231, 1.0
	v_cvt_pk_bf16_f32 v167, v140, v141
	v_mul_f32_e32 v230, 0xbfb8aa3b, v138
	v_mul_f32_e32 v231, 0xbfb8aa3b, v139
	v_exp_f32_e32 v230, v230
	v_exp_f32_e32 v231, v231
	s_nop 0
	v_add_f32_e32 v230, 1.0, v230
	v_add_f32_e32 v231, 1.0, v231
	v_div_scale_f32 v220, s[66:67], v230, v230, 1.0
	v_rcp_f32_e32 v221, v220
	s_nop 0
	v_fma_f32 v222, -v220, v221, 1.0
	v_fmac_f32_e32 v221, v222, v221
	v_div_scale_f32 v223, vcc, 1.0, v230, 1.0
	v_mul_f32_e32 v224, v223, v221
	v_fma_f32 v222, -v220, v224, v223
	v_fmac_f32_e32 v224, v222, v221
	v_fma_f32 v220, -v220, v224, v223
	v_div_fmas_f32 v220, v220, v221, v224
	v_div_fixup_f32 v138, v220, v230, 1.0
	v_div_scale_f32 v225, s[66:67], v231, v231, 1.0
	v_rcp_f32_e32 v226, v225
	s_nop 0
	v_fma_f32 v227, -v225, v226, 1.0
	v_fmac_f32_e32 v226, v227, v226
	v_div_scale_f32 v228, vcc, 1.0, v231, 1.0
	v_mul_f32_e32 v229, v228, v226
	v_fma_f32 v227, -v225, v229, v228
	v_fmac_f32_e32 v229, v227, v226
	v_fma_f32 v225, -v225, v229, v228
	v_div_fmas_f32 v225, v225, v226, v229
	v_div_fixup_f32 v139, v225, v231, 1.0
	v_cvt_pk_bf16_f32 v166, v138, v139
	v_mul_f32_e32 v230, 0xbfb8aa3b, v136
	v_mul_f32_e32 v231, 0xbfb8aa3b, v137
	v_exp_f32_e32 v230, v230
	v_exp_f32_e32 v231, v231
	s_nop 0
	v_add_f32_e32 v230, 1.0, v230
	v_add_f32_e32 v231, 1.0, v231
	v_div_scale_f32 v220, s[66:67], v230, v230, 1.0
	v_rcp_f32_e32 v221, v220
	s_nop 0
	v_fma_f32 v222, -v220, v221, 1.0
	v_fmac_f32_e32 v221, v222, v221
	v_div_scale_f32 v223, vcc, 1.0, v230, 1.0
	v_mul_f32_e32 v224, v223, v221
	v_fma_f32 v222, -v220, v224, v223
	v_fmac_f32_e32 v224, v222, v221
	v_fma_f32 v220, -v220, v224, v223
	v_div_fmas_f32 v220, v220, v221, v224
	v_div_fixup_f32 v136, v220, v230, 1.0
	v_div_scale_f32 v225, s[66:67], v231, v231, 1.0
	v_rcp_f32_e32 v226, v225
	s_nop 0
	v_fma_f32 v227, -v225, v226, 1.0
	v_fmac_f32_e32 v226, v227, v226
	v_div_scale_f32 v228, vcc, 1.0, v231, 1.0
	v_mul_f32_e32 v229, v228, v226
	v_fma_f32 v227, -v225, v229, v228
	v_fmac_f32_e32 v229, v227, v226
	v_fma_f32 v225, -v225, v229, v228
	v_div_fmas_f32 v225, v225, v226, v229
	v_div_fixup_f32 v137, v225, v231, 1.0
	v_cvt_pk_bf16_f32 v165, v136, v137
	v_mul_f32_e32 v230, 0xbfb8aa3b, v134
	v_mul_f32_e32 v231, 0xbfb8aa3b, v135
	v_exp_f32_e32 v230, v230
	v_exp_f32_e32 v231, v231
	s_nop 0
	v_add_f32_e32 v230, 1.0, v230
	v_add_f32_e32 v231, 1.0, v231
	v_div_scale_f32 v220, s[66:67], v230, v230, 1.0
	v_rcp_f32_e32 v221, v220
	s_nop 0
	v_fma_f32 v222, -v220, v221, 1.0
	v_fmac_f32_e32 v221, v222, v221
	v_div_scale_f32 v223, vcc, 1.0, v230, 1.0
	v_mul_f32_e32 v224, v223, v221
	v_fma_f32 v222, -v220, v224, v223
	v_fmac_f32_e32 v224, v222, v221
	v_fma_f32 v220, -v220, v224, v223
	v_div_fmas_f32 v220, v220, v221, v224
	v_div_fixup_f32 v134, v220, v230, 1.0
	v_div_scale_f32 v225, s[66:67], v231, v231, 1.0
	v_rcp_f32_e32 v226, v225
	s_nop 0
	v_fma_f32 v227, -v225, v226, 1.0
	v_fmac_f32_e32 v226, v227, v226
	v_div_scale_f32 v228, vcc, 1.0, v231, 1.0
	v_mul_f32_e32 v229, v228, v226
	v_fma_f32 v227, -v225, v229, v228
	v_fmac_f32_e32 v229, v227, v226
	v_fma_f32 v225, -v225, v229, v228
	v_div_fmas_f32 v225, v225, v226, v229
	v_div_fixup_f32 v135, v225, v231, 1.0
	v_cvt_pk_bf16_f32 v164, v134, v135
	v_mul_f32_e32 v230, 0xbfb8aa3b, v132
	v_mul_f32_e32 v231, 0xbfb8aa3b, v133
	v_exp_f32_e32 v230, v230
	v_exp_f32_e32 v231, v231
	s_nop 0
	v_add_f32_e32 v230, 1.0, v230
	v_add_f32_e32 v231, 1.0, v231
	v_div_scale_f32 v220, s[66:67], v230, v230, 1.0
	v_rcp_f32_e32 v221, v220
	s_nop 0
	v_fma_f32 v222, -v220, v221, 1.0
	v_fmac_f32_e32 v221, v222, v221
	v_div_scale_f32 v223, vcc, 1.0, v230, 1.0
	v_mul_f32_e32 v224, v223, v221
	v_fma_f32 v222, -v220, v224, v223
	v_fmac_f32_e32 v224, v222, v221
	v_fma_f32 v220, -v220, v224, v223
	v_div_fmas_f32 v220, v220, v221, v224
	v_div_fixup_f32 v132, v220, v230, 1.0
	v_div_scale_f32 v225, s[66:67], v231, v231, 1.0
	v_rcp_f32_e32 v226, v225
	s_nop 0
	v_fma_f32 v227, -v225, v226, 1.0
	v_fmac_f32_e32 v226, v227, v226
	v_div_scale_f32 v228, vcc, 1.0, v231, 1.0
	v_mul_f32_e32 v229, v228, v226
	v_fma_f32 v227, -v225, v229, v228
	v_fmac_f32_e32 v229, v227, v226
	v_fma_f32 v225, -v225, v229, v228
	v_div_fmas_f32 v225, v225, v226, v229
	v_div_fixup_f32 v133, v225, v231, 1.0
	v_cvt_pk_bf16_f32 v163, v132, v133
	v_mul_f32_e32 v230, 0xbfb8aa3b, v130
	v_mul_f32_e32 v231, 0xbfb8aa3b, v131
	v_exp_f32_e32 v230, v230
	v_exp_f32_e32 v231, v231
	s_nop 0
	v_add_f32_e32 v230, 1.0, v230
	v_add_f32_e32 v231, 1.0, v231
	v_div_scale_f32 v220, s[66:67], v230, v230, 1.0
	v_rcp_f32_e32 v221, v220
	s_nop 0
	v_fma_f32 v222, -v220, v221, 1.0
	v_fmac_f32_e32 v221, v222, v221
	v_div_scale_f32 v223, vcc, 1.0, v230, 1.0
	v_mul_f32_e32 v224, v223, v221
	v_fma_f32 v222, -v220, v224, v223
	v_fmac_f32_e32 v224, v222, v221
	v_fma_f32 v220, -v220, v224, v223
	v_div_fmas_f32 v220, v220, v221, v224
	v_div_fixup_f32 v130, v220, v230, 1.0
	v_div_scale_f32 v225, s[66:67], v231, v231, 1.0
	v_rcp_f32_e32 v226, v225
	s_nop 0
	v_fma_f32 v227, -v225, v226, 1.0
	v_fmac_f32_e32 v226, v227, v226
	v_div_scale_f32 v228, vcc, 1.0, v231, 1.0
	v_mul_f32_e32 v229, v228, v226
	v_fma_f32 v227, -v225, v229, v228
	v_fmac_f32_e32 v229, v227, v226
	v_fma_f32 v225, -v225, v229, v228
	v_div_fmas_f32 v225, v225, v226, v229
	v_div_fixup_f32 v131, v225, v231, 1.0
	v_cvt_pk_bf16_f32 v162, v130, v131
	v_mul_f32_e32 v230, 0xbfb8aa3b, v128
	v_mul_f32_e32 v231, 0xbfb8aa3b, v129
	v_exp_f32_e32 v230, v230
	v_exp_f32_e32 v231, v231
	s_nop 0
	v_add_f32_e32 v230, 1.0, v230
	v_add_f32_e32 v231, 1.0, v231
	v_div_scale_f32 v220, s[66:67], v230, v230, 1.0
	v_rcp_f32_e32 v221, v220
	s_nop 0
	v_fma_f32 v222, -v220, v221, 1.0
	v_fmac_f32_e32 v221, v222, v221
	v_div_scale_f32 v223, vcc, 1.0, v230, 1.0
	v_mul_f32_e32 v224, v223, v221
	v_fma_f32 v222, -v220, v224, v223
	v_fmac_f32_e32 v224, v222, v221
	v_fma_f32 v220, -v220, v224, v223
	v_div_fmas_f32 v220, v220, v221, v224
	v_div_fixup_f32 v128, v220, v230, 1.0
	v_div_scale_f32 v225, s[66:67], v231, v231, 1.0
	v_rcp_f32_e32 v226, v225
	s_nop 0
	v_fma_f32 v227, -v225, v226, 1.0
	v_fmac_f32_e32 v226, v227, v226
	v_div_scale_f32 v228, vcc, 1.0, v231, 1.0
	v_mul_f32_e32 v229, v228, v226
	v_fma_f32 v227, -v225, v229, v228
	v_fmac_f32_e32 v229, v227, v226
	v_fma_f32 v225, -v225, v229, v228
	v_div_fmas_f32 v225, v225, v226, v229
	v_div_fixup_f32 v129, v225, v231, 1.0
	v_cvt_pk_bf16_f32 v161, v128, v129
	v_mul_f32_e32 v230, 0xbfb8aa3b, v126
	v_mul_f32_e32 v231, 0xbfb8aa3b, v127
	v_exp_f32_e32 v230, v230
	v_exp_f32_e32 v231, v231
	s_nop 0
	v_add_f32_e32 v230, 1.0, v230
	v_add_f32_e32 v231, 1.0, v231
	v_div_scale_f32 v220, s[66:67], v230, v230, 1.0
	v_rcp_f32_e32 v221, v220
	s_nop 0
	v_fma_f32 v222, -v220, v221, 1.0
	v_fmac_f32_e32 v221, v222, v221
	v_div_scale_f32 v223, vcc, 1.0, v230, 1.0
	v_mul_f32_e32 v224, v223, v221
	v_fma_f32 v222, -v220, v224, v223
	v_fmac_f32_e32 v224, v222, v221
	v_fma_f32 v220, -v220, v224, v223
	v_div_fmas_f32 v220, v220, v221, v224
	v_div_fixup_f32 v126, v220, v230, 1.0
	v_div_scale_f32 v225, s[66:67], v231, v231, 1.0
	v_rcp_f32_e32 v226, v225
	s_nop 0
	v_fma_f32 v227, -v225, v226, 1.0
	v_fmac_f32_e32 v226, v227, v226
	v_div_scale_f32 v228, vcc, 1.0, v231, 1.0
	v_mul_f32_e32 v229, v228, v226
	v_fma_f32 v227, -v225, v229, v228
	v_fmac_f32_e32 v229, v227, v226
	v_fma_f32 v225, -v225, v229, v228
	v_div_fmas_f32 v225, v225, v226, v229
	v_div_fixup_f32 v127, v225, v231, 1.0
	v_cvt_pk_bf16_f32 v160, v126, v127
	v_mul_f32_e32 v230, 0xbfb8aa3b, v124
	v_mul_f32_e32 v231, 0xbfb8aa3b, v125
	v_exp_f32_e32 v230, v230
	v_exp_f32_e32 v231, v231
	s_nop 0
	v_add_f32_e32 v230, 1.0, v230
	v_add_f32_e32 v231, 1.0, v231
	v_div_scale_f32 v220, s[66:67], v230, v230, 1.0
	v_rcp_f32_e32 v221, v220
	s_nop 0
	v_fma_f32 v222, -v220, v221, 1.0
	v_fmac_f32_e32 v221, v222, v221
	v_div_scale_f32 v223, vcc, 1.0, v230, 1.0
	v_mul_f32_e32 v224, v223, v221
	v_fma_f32 v222, -v220, v224, v223
	v_fmac_f32_e32 v224, v222, v221
	v_fma_f32 v220, -v220, v224, v223
	v_div_fmas_f32 v220, v220, v221, v224
	v_div_fixup_f32 v124, v220, v230, 1.0
	v_div_scale_f32 v225, s[66:67], v231, v231, 1.0
	v_rcp_f32_e32 v226, v225
	s_nop 0
	v_fma_f32 v227, -v225, v226, 1.0
	v_fmac_f32_e32 v226, v227, v226
	v_div_scale_f32 v228, vcc, 1.0, v231, 1.0
	v_mul_f32_e32 v229, v228, v226
	v_fma_f32 v227, -v225, v229, v228
	v_fmac_f32_e32 v229, v227, v226
	v_fma_f32 v225, -v225, v229, v228
	v_div_fmas_f32 v225, v225, v226, v229
	v_div_fixup_f32 v125, v225, v231, 1.0
	v_cvt_pk_bf16_f32 v159, v124, v125
	v_mul_f32_e32 v230, 0xbfb8aa3b, v122
	v_mul_f32_e32 v231, 0xbfb8aa3b, v123
	v_exp_f32_e32 v230, v230
	v_exp_f32_e32 v231, v231
	s_nop 0
	v_add_f32_e32 v230, 1.0, v230
	v_add_f32_e32 v231, 1.0, v231
	v_div_scale_f32 v220, s[66:67], v230, v230, 1.0
	v_rcp_f32_e32 v221, v220
	s_nop 0
	v_fma_f32 v222, -v220, v221, 1.0
	v_fmac_f32_e32 v221, v222, v221
	v_div_scale_f32 v223, vcc, 1.0, v230, 1.0
	v_mul_f32_e32 v224, v223, v221
	v_fma_f32 v222, -v220, v224, v223
	v_fmac_f32_e32 v224, v222, v221
	v_fma_f32 v220, -v220, v224, v223
	v_div_fmas_f32 v220, v220, v221, v224
	v_div_fixup_f32 v122, v220, v230, 1.0
	v_div_scale_f32 v225, s[66:67], v231, v231, 1.0
	v_rcp_f32_e32 v226, v225
	s_nop 0
	v_fma_f32 v227, -v225, v226, 1.0
	v_fmac_f32_e32 v226, v227, v226
	v_div_scale_f32 v228, vcc, 1.0, v231, 1.0
	v_mul_f32_e32 v229, v228, v226
	v_fma_f32 v227, -v225, v229, v228
	v_fmac_f32_e32 v229, v227, v226
	v_fma_f32 v225, -v225, v229, v228
	v_div_fmas_f32 v225, v225, v226, v229
	v_div_fixup_f32 v123, v225, v231, 1.0
	v_cvt_pk_bf16_f32 v158, v122, v123
	v_mul_f32_e32 v230, 0xbfb8aa3b, v120
	v_mul_f32_e32 v231, 0xbfb8aa3b, v121
	v_exp_f32_e32 v230, v230
	v_exp_f32_e32 v231, v231
	s_nop 0
	v_add_f32_e32 v230, 1.0, v230
	v_add_f32_e32 v231, 1.0, v231
	v_div_scale_f32 v220, s[66:67], v230, v230, 1.0
	v_rcp_f32_e32 v221, v220
	s_nop 0
	v_fma_f32 v222, -v220, v221, 1.0
	v_fmac_f32_e32 v221, v222, v221
	v_div_scale_f32 v223, vcc, 1.0, v230, 1.0
	v_mul_f32_e32 v224, v223, v221
	v_fma_f32 v222, -v220, v224, v223
	v_fmac_f32_e32 v224, v222, v221
	v_fma_f32 v220, -v220, v224, v223
	v_div_fmas_f32 v220, v220, v221, v224
	v_div_fixup_f32 v120, v220, v230, 1.0
	v_div_scale_f32 v225, s[66:67], v231, v231, 1.0
	v_rcp_f32_e32 v226, v225
	s_nop 0
	v_fma_f32 v227, -v225, v226, 1.0
	v_fmac_f32_e32 v226, v227, v226
	v_div_scale_f32 v228, vcc, 1.0, v231, 1.0
	v_mul_f32_e32 v229, v228, v226
	v_fma_f32 v227, -v225, v229, v228
	v_fmac_f32_e32 v229, v227, v226
	v_fma_f32 v225, -v225, v229, v228
	v_div_fmas_f32 v225, v225, v226, v229
	v_div_fixup_f32 v121, v225, v231, 1.0
	v_cvt_pk_bf16_f32 v157, v120, v121
	v_mul_f32_e32 v230, 0xbfb8aa3b, v118
	v_mul_f32_e32 v231, 0xbfb8aa3b, v119
	v_exp_f32_e32 v230, v230
	v_exp_f32_e32 v231, v231
	s_nop 0
	v_add_f32_e32 v230, 1.0, v230
	v_add_f32_e32 v231, 1.0, v231
	v_div_scale_f32 v220, s[66:67], v230, v230, 1.0
	v_rcp_f32_e32 v221, v220
	s_nop 0
	v_fma_f32 v222, -v220, v221, 1.0
	v_fmac_f32_e32 v221, v222, v221
	v_div_scale_f32 v223, vcc, 1.0, v230, 1.0
	v_mul_f32_e32 v224, v223, v221
	v_fma_f32 v222, -v220, v224, v223
	v_fmac_f32_e32 v224, v222, v221
	v_fma_f32 v220, -v220, v224, v223
	v_div_fmas_f32 v220, v220, v221, v224
	v_div_fixup_f32 v118, v220, v230, 1.0
	v_div_scale_f32 v225, s[66:67], v231, v231, 1.0
	v_rcp_f32_e32 v226, v225
	s_nop 0
	v_fma_f32 v227, -v225, v226, 1.0
	v_fmac_f32_e32 v226, v227, v226
	v_div_scale_f32 v228, vcc, 1.0, v231, 1.0
	v_mul_f32_e32 v229, v228, v226
	v_fma_f32 v227, -v225, v229, v228
	v_fmac_f32_e32 v229, v227, v226
	v_fma_f32 v225, -v225, v229, v228
	v_div_fmas_f32 v225, v225, v226, v229
	v_div_fixup_f32 v119, v225, v231, 1.0
	v_cvt_pk_bf16_f32 v156, v118, v119
	v_mul_f32_e32 v230, 0xbfb8aa3b, v116
	v_mul_f32_e32 v231, 0xbfb8aa3b, v117
	v_exp_f32_e32 v230, v230
	v_exp_f32_e32 v231, v231
	s_nop 0
	v_add_f32_e32 v230, 1.0, v230
	v_add_f32_e32 v231, 1.0, v231
	v_div_scale_f32 v220, s[66:67], v230, v230, 1.0
	v_rcp_f32_e32 v221, v220
	s_nop 0
	v_fma_f32 v222, -v220, v221, 1.0
	v_fmac_f32_e32 v221, v222, v221
	v_div_scale_f32 v223, vcc, 1.0, v230, 1.0
	v_mul_f32_e32 v224, v223, v221
	v_fma_f32 v222, -v220, v224, v223
	v_fmac_f32_e32 v224, v222, v221
	v_fma_f32 v220, -v220, v224, v223
	v_div_fmas_f32 v220, v220, v221, v224
	v_div_fixup_f32 v116, v220, v230, 1.0
	v_div_scale_f32 v225, s[66:67], v231, v231, 1.0
	v_rcp_f32_e32 v226, v225
	s_nop 0
	v_fma_f32 v227, -v225, v226, 1.0
	v_fmac_f32_e32 v226, v227, v226
	v_div_scale_f32 v228, vcc, 1.0, v231, 1.0
	v_mul_f32_e32 v229, v228, v226
	v_fma_f32 v227, -v225, v229, v228
	v_fmac_f32_e32 v229, v227, v226
	v_fma_f32 v225, -v225, v229, v228
	v_div_fmas_f32 v225, v225, v226, v229
	v_div_fixup_f32 v117, v225, v231, 1.0
	v_cvt_pk_bf16_f32 v155, v116, v117
	v_mul_f32_e32 v230, 0xbfb8aa3b, v114
	v_mul_f32_e32 v231, 0xbfb8aa3b, v115
	v_exp_f32_e32 v230, v230
	v_exp_f32_e32 v231, v231
	s_nop 0
	v_add_f32_e32 v230, 1.0, v230
	v_add_f32_e32 v231, 1.0, v231
	v_div_scale_f32 v220, s[66:67], v230, v230, 1.0
	v_rcp_f32_e32 v221, v220
	s_nop 0
	v_fma_f32 v222, -v220, v221, 1.0
	v_fmac_f32_e32 v221, v222, v221
	v_div_scale_f32 v223, vcc, 1.0, v230, 1.0
	v_mul_f32_e32 v224, v223, v221
	v_fma_f32 v222, -v220, v224, v223
	v_fmac_f32_e32 v224, v222, v221
	v_fma_f32 v220, -v220, v224, v223
	v_div_fmas_f32 v220, v220, v221, v224
	v_div_fixup_f32 v114, v220, v230, 1.0
	v_div_scale_f32 v225, s[66:67], v231, v231, 1.0
	v_rcp_f32_e32 v226, v225
	s_nop 0
	v_fma_f32 v227, -v225, v226, 1.0
	v_fmac_f32_e32 v226, v227, v226
	v_div_scale_f32 v228, vcc, 1.0, v231, 1.0
	v_mul_f32_e32 v229, v228, v226
	v_fma_f32 v227, -v225, v229, v228
	v_fmac_f32_e32 v229, v227, v226
	v_fma_f32 v225, -v225, v229, v228
	v_div_fmas_f32 v225, v225, v226, v229
	v_div_fixup_f32 v115, v225, v231, 1.0
	v_cvt_pk_bf16_f32 v154, v114, v115
	v_mul_f32_e32 v230, 0xbfb8aa3b, v112
	v_mul_f32_e32 v231, 0xbfb8aa3b, v113
	v_exp_f32_e32 v230, v230
	v_exp_f32_e32 v231, v231
	s_nop 0
	v_add_f32_e32 v230, 1.0, v230
	v_add_f32_e32 v231, 1.0, v231
	v_div_scale_f32 v220, s[66:67], v230, v230, 1.0
	v_rcp_f32_e32 v221, v220
	s_nop 0
	v_fma_f32 v222, -v220, v221, 1.0
	v_fmac_f32_e32 v221, v222, v221
	v_div_scale_f32 v223, vcc, 1.0, v230, 1.0
	v_mul_f32_e32 v224, v223, v221
	v_fma_f32 v222, -v220, v224, v223
	v_fmac_f32_e32 v224, v222, v221
	v_fma_f32 v220, -v220, v224, v223
	v_div_fmas_f32 v220, v220, v221, v224
	v_div_fixup_f32 v112, v220, v230, 1.0
	v_div_scale_f32 v225, s[66:67], v231, v231, 1.0
	v_rcp_f32_e32 v226, v225
	s_nop 0
	v_fma_f32 v227, -v225, v226, 1.0
	v_fmac_f32_e32 v226, v227, v226
	v_div_scale_f32 v228, vcc, 1.0, v231, 1.0
	v_mul_f32_e32 v229, v228, v226
	v_fma_f32 v227, -v225, v229, v228
	v_fmac_f32_e32 v229, v227, v226
	v_fma_f32 v225, -v225, v229, v228
	v_div_fmas_f32 v225, v225, v226, v229
	v_div_fixup_f32 v113, v225, v231, 1.0
	v_cvt_pk_bf16_f32 v153, v112, v113
	v_mul_f32_e32 v230, 0xbfb8aa3b, v110
	v_mul_f32_e32 v231, 0xbfb8aa3b, v111
	v_exp_f32_e32 v230, v230
	v_exp_f32_e32 v231, v231
	s_nop 0
	v_add_f32_e32 v230, 1.0, v230
	v_add_f32_e32 v231, 1.0, v231
	v_div_scale_f32 v220, s[66:67], v230, v230, 1.0
	v_rcp_f32_e32 v221, v220
	s_nop 0
	v_fma_f32 v222, -v220, v221, 1.0
	v_fmac_f32_e32 v221, v222, v221
	v_div_scale_f32 v223, vcc, 1.0, v230, 1.0
	v_mul_f32_e32 v224, v223, v221
	v_fma_f32 v222, -v220, v224, v223
	v_fmac_f32_e32 v224, v222, v221
	v_fma_f32 v220, -v220, v224, v223
	v_div_fmas_f32 v220, v220, v221, v224
	v_div_fixup_f32 v110, v220, v230, 1.0
	v_div_scale_f32 v225, s[66:67], v231, v231, 1.0
	v_rcp_f32_e32 v226, v225
	s_nop 0
	v_fma_f32 v227, -v225, v226, 1.0
	v_fmac_f32_e32 v226, v227, v226
	v_div_scale_f32 v228, vcc, 1.0, v231, 1.0
	v_mul_f32_e32 v229, v228, v226
	v_fma_f32 v227, -v225, v229, v228
	v_fmac_f32_e32 v229, v227, v226
	v_fma_f32 v225, -v225, v229, v228
	v_div_fmas_f32 v225, v225, v226, v229
	v_div_fixup_f32 v111, v225, v231, 1.0
	v_cvt_pk_bf16_f32 v152, v110, v111
	v_mul_f32_e32 v230, 0xbfb8aa3b, v108
	v_mul_f32_e32 v231, 0xbfb8aa3b, v109
	v_exp_f32_e32 v230, v230
	v_exp_f32_e32 v231, v231
	s_nop 0
	v_add_f32_e32 v230, 1.0, v230
	v_add_f32_e32 v231, 1.0, v231
	v_div_scale_f32 v220, s[66:67], v230, v230, 1.0
	v_rcp_f32_e32 v221, v220
	s_nop 0
	v_fma_f32 v222, -v220, v221, 1.0
	v_fmac_f32_e32 v221, v222, v221
	v_div_scale_f32 v223, vcc, 1.0, v230, 1.0
	v_mul_f32_e32 v224, v223, v221
	v_fma_f32 v222, -v220, v224, v223
	v_fmac_f32_e32 v224, v222, v221
	v_fma_f32 v220, -v220, v224, v223
	v_div_fmas_f32 v220, v220, v221, v224
	v_div_fixup_f32 v108, v220, v230, 1.0
	v_div_scale_f32 v225, s[66:67], v231, v231, 1.0
	v_rcp_f32_e32 v226, v225
	s_nop 0
	v_fma_f32 v227, -v225, v226, 1.0
	v_fmac_f32_e32 v226, v227, v226
	v_div_scale_f32 v228, vcc, 1.0, v231, 1.0
	v_mul_f32_e32 v229, v228, v226
	v_fma_f32 v227, -v225, v229, v228
	v_fmac_f32_e32 v229, v227, v226
	v_fma_f32 v225, -v225, v229, v228
	v_div_fmas_f32 v225, v225, v226, v229
	v_div_fixup_f32 v109, v225, v231, 1.0
	v_cvt_pk_bf16_f32 v151, v108, v109
	v_mul_f32_e32 v230, 0xbfb8aa3b, v106
	v_mul_f32_e32 v231, 0xbfb8aa3b, v107
	v_exp_f32_e32 v230, v230
	v_exp_f32_e32 v231, v231
	s_nop 0
	v_add_f32_e32 v230, 1.0, v230
	v_add_f32_e32 v231, 1.0, v231
	v_div_scale_f32 v220, s[66:67], v230, v230, 1.0
	v_rcp_f32_e32 v221, v220
	s_nop 0
	v_fma_f32 v222, -v220, v221, 1.0
	v_fmac_f32_e32 v221, v222, v221
	v_div_scale_f32 v223, vcc, 1.0, v230, 1.0
	v_mul_f32_e32 v224, v223, v221
	v_fma_f32 v222, -v220, v224, v223
	v_fmac_f32_e32 v224, v222, v221
	v_fma_f32 v220, -v220, v224, v223
	v_div_fmas_f32 v220, v220, v221, v224
	v_div_fixup_f32 v106, v220, v230, 1.0
	v_div_scale_f32 v225, s[66:67], v231, v231, 1.0
	v_rcp_f32_e32 v226, v225
	s_nop 0
	v_fma_f32 v227, -v225, v226, 1.0
	v_fmac_f32_e32 v226, v227, v226
	v_div_scale_f32 v228, vcc, 1.0, v231, 1.0
	v_mul_f32_e32 v229, v228, v226
	v_fma_f32 v227, -v225, v229, v228
	v_fmac_f32_e32 v229, v227, v226
	v_fma_f32 v225, -v225, v229, v228
	v_div_fmas_f32 v225, v225, v226, v229
	v_div_fixup_f32 v107, v225, v231, 1.0
	v_cvt_pk_bf16_f32 v150, v106, v107
	v_mul_f32_e32 v230, 0xbfb8aa3b, v104
	v_mul_f32_e32 v231, 0xbfb8aa3b, v105
	v_exp_f32_e32 v230, v230
	v_exp_f32_e32 v231, v231
	s_nop 0
	v_add_f32_e32 v230, 1.0, v230
	v_add_f32_e32 v231, 1.0, v231
	v_div_scale_f32 v220, s[66:67], v230, v230, 1.0
	v_rcp_f32_e32 v221, v220
	s_nop 0
	v_fma_f32 v222, -v220, v221, 1.0
	v_fmac_f32_e32 v221, v222, v221
	v_div_scale_f32 v223, vcc, 1.0, v230, 1.0
	v_mul_f32_e32 v224, v223, v221
	v_fma_f32 v222, -v220, v224, v223
	v_fmac_f32_e32 v224, v222, v221
	v_fma_f32 v220, -v220, v224, v223
	v_div_fmas_f32 v220, v220, v221, v224
	v_div_fixup_f32 v104, v220, v230, 1.0
	v_div_scale_f32 v225, s[66:67], v231, v231, 1.0
	v_rcp_f32_e32 v226, v225
	s_nop 0
	v_fma_f32 v227, -v225, v226, 1.0
	v_fmac_f32_e32 v226, v227, v226
	v_div_scale_f32 v228, vcc, 1.0, v231, 1.0
	v_mul_f32_e32 v229, v228, v226
	v_fma_f32 v227, -v225, v229, v228
	v_fmac_f32_e32 v229, v227, v226
	v_fma_f32 v225, -v225, v229, v228
	v_div_fmas_f32 v225, v225, v226, v229
	v_div_fixup_f32 v105, v225, v231, 1.0
	v_cvt_pk_bf16_f32 v149, v104, v105
	v_mul_f32_e32 v230, 0xbfb8aa3b, v102
	v_mul_f32_e32 v231, 0xbfb8aa3b, v103
	v_exp_f32_e32 v230, v230
	v_exp_f32_e32 v231, v231
	s_nop 0
	v_add_f32_e32 v230, 1.0, v230
	v_add_f32_e32 v231, 1.0, v231
	v_div_scale_f32 v220, s[66:67], v230, v230, 1.0
	v_rcp_f32_e32 v221, v220
	s_nop 0
	v_fma_f32 v222, -v220, v221, 1.0
	v_fmac_f32_e32 v221, v222, v221
	v_div_scale_f32 v223, vcc, 1.0, v230, 1.0
	v_mul_f32_e32 v224, v223, v221
	v_fma_f32 v222, -v220, v224, v223
	v_fmac_f32_e32 v224, v222, v221
	v_fma_f32 v220, -v220, v224, v223
	v_div_fmas_f32 v220, v220, v221, v224
	v_div_fixup_f32 v102, v220, v230, 1.0
	v_div_scale_f32 v225, s[66:67], v231, v231, 1.0
	v_rcp_f32_e32 v226, v225
	s_nop 0
	v_fma_f32 v227, -v225, v226, 1.0
	v_fmac_f32_e32 v226, v227, v226
	v_div_scale_f32 v228, vcc, 1.0, v231, 1.0
	v_mul_f32_e32 v229, v228, v226
	v_fma_f32 v227, -v225, v229, v228
	v_fmac_f32_e32 v229, v227, v226
	v_fma_f32 v225, -v225, v229, v228
	v_div_fmas_f32 v225, v225, v226, v229
	v_div_fixup_f32 v103, v225, v231, 1.0
	v_cvt_pk_bf16_f32 v148, v102, v103
	v_mul_f32_e32 v230, 0xbfb8aa3b, v100
	v_mul_f32_e32 v231, 0xbfb8aa3b, v101
	v_exp_f32_e32 v230, v230
	v_exp_f32_e32 v231, v231
	s_nop 0
	v_add_f32_e32 v230, 1.0, v230
	v_add_f32_e32 v231, 1.0, v231
	v_div_scale_f32 v220, s[66:67], v230, v230, 1.0
	v_rcp_f32_e32 v221, v220
	s_nop 0
	v_fma_f32 v222, -v220, v221, 1.0
	v_fmac_f32_e32 v221, v222, v221
	v_div_scale_f32 v223, vcc, 1.0, v230, 1.0
	v_mul_f32_e32 v224, v223, v221
	v_fma_f32 v222, -v220, v224, v223
	v_fmac_f32_e32 v224, v222, v221
	v_fma_f32 v220, -v220, v224, v223
	v_div_fmas_f32 v220, v220, v221, v224
	v_div_fixup_f32 v100, v220, v230, 1.0
	v_div_scale_f32 v225, s[66:67], v231, v231, 1.0
	v_rcp_f32_e32 v226, v225
	s_nop 0
	v_fma_f32 v227, -v225, v226, 1.0
	v_fmac_f32_e32 v226, v227, v226
	v_div_scale_f32 v228, vcc, 1.0, v231, 1.0
	v_mul_f32_e32 v229, v228, v226
	v_fma_f32 v227, -v225, v229, v228
	v_fmac_f32_e32 v229, v227, v226
	v_fma_f32 v225, -v225, v229, v228
	v_div_fmas_f32 v225, v225, v226, v229
	v_div_fixup_f32 v101, v225, v231, 1.0
	v_cvt_pk_bf16_f32 v147, v100, v101
	v_mul_f32_e32 v230, 0xbfb8aa3b, v98
	v_mul_f32_e32 v231, 0xbfb8aa3b, v99
	v_exp_f32_e32 v230, v230
	v_exp_f32_e32 v231, v231
	s_nop 0
	v_add_f32_e32 v230, 1.0, v230
	v_add_f32_e32 v231, 1.0, v231
	v_div_scale_f32 v220, s[66:67], v230, v230, 1.0
	v_rcp_f32_e32 v221, v220
	s_nop 0
	v_fma_f32 v222, -v220, v221, 1.0
	v_fmac_f32_e32 v221, v222, v221
	v_div_scale_f32 v223, vcc, 1.0, v230, 1.0
	v_mul_f32_e32 v224, v223, v221
	v_fma_f32 v222, -v220, v224, v223
	v_fmac_f32_e32 v224, v222, v221
	v_fma_f32 v220, -v220, v224, v223
	v_div_fmas_f32 v220, v220, v221, v224
	v_div_fixup_f32 v98, v220, v230, 1.0
	v_div_scale_f32 v225, s[66:67], v231, v231, 1.0
	v_rcp_f32_e32 v226, v225
	s_nop 0
	v_fma_f32 v227, -v225, v226, 1.0
	v_fmac_f32_e32 v226, v227, v226
	v_div_scale_f32 v228, vcc, 1.0, v231, 1.0
	v_mul_f32_e32 v229, v228, v226
	v_fma_f32 v227, -v225, v229, v228
	v_fmac_f32_e32 v229, v227, v226
	v_fma_f32 v225, -v225, v229, v228
	v_div_fmas_f32 v225, v225, v226, v229
	v_div_fixup_f32 v99, v225, v231, 1.0
	v_cvt_pk_bf16_f32 v146, v98, v99
	v_mul_f32_e32 v230, 0xbfb8aa3b, v96
	v_mul_f32_e32 v231, 0xbfb8aa3b, v97
	v_exp_f32_e32 v230, v230
	v_exp_f32_e32 v231, v231
	s_nop 0
	v_add_f32_e32 v230, 1.0, v230
	v_add_f32_e32 v231, 1.0, v231
	v_div_scale_f32 v220, s[66:67], v230, v230, 1.0
	v_rcp_f32_e32 v221, v220
	s_nop 0
	v_fma_f32 v222, -v220, v221, 1.0
	v_fmac_f32_e32 v221, v222, v221
	v_div_scale_f32 v223, vcc, 1.0, v230, 1.0
	v_mul_f32_e32 v224, v223, v221
	v_fma_f32 v222, -v220, v224, v223
	v_fmac_f32_e32 v224, v222, v221
	v_fma_f32 v220, -v220, v224, v223
	v_div_fmas_f32 v220, v220, v221, v224
	v_div_fixup_f32 v96, v220, v230, 1.0
	v_div_scale_f32 v225, s[66:67], v231, v231, 1.0
	v_rcp_f32_e32 v226, v225
	s_nop 0
	v_fma_f32 v227, -v225, v226, 1.0
	v_fmac_f32_e32 v226, v227, v226
	v_div_scale_f32 v228, vcc, 1.0, v231, 1.0
	v_mul_f32_e32 v229, v228, v226
	v_fma_f32 v227, -v225, v229, v228
	v_fmac_f32_e32 v229, v227, v226
	v_fma_f32 v225, -v225, v229, v228
	v_div_fmas_f32 v225, v225, v226, v229
	v_div_fixup_f32 v97, v225, v231, 1.0
	v_cvt_pk_bf16_f32 v145, v96, v97
	v_mul_f32_e32 v230, 0xbfb8aa3b, v94
	v_mul_f32_e32 v231, 0xbfb8aa3b, v95
	v_exp_f32_e32 v230, v230
	v_exp_f32_e32 v231, v231
	s_nop 0
	v_add_f32_e32 v230, 1.0, v230
	v_add_f32_e32 v231, 1.0, v231
	v_div_scale_f32 v220, s[66:67], v230, v230, 1.0
	v_rcp_f32_e32 v221, v220
	s_nop 0
	v_fma_f32 v222, -v220, v221, 1.0
	v_fmac_f32_e32 v221, v222, v221
	v_div_scale_f32 v223, vcc, 1.0, v230, 1.0
	v_mul_f32_e32 v224, v223, v221
	v_fma_f32 v222, -v220, v224, v223
	v_fmac_f32_e32 v224, v222, v221
	v_fma_f32 v220, -v220, v224, v223
	v_div_fmas_f32 v220, v220, v221, v224
	v_div_fixup_f32 v94, v220, v230, 1.0
	v_div_scale_f32 v225, s[66:67], v231, v231, 1.0
	v_rcp_f32_e32 v226, v225
	s_nop 0
	v_fma_f32 v227, -v225, v226, 1.0
	v_fmac_f32_e32 v226, v227, v226
	v_div_scale_f32 v228, vcc, 1.0, v231, 1.0
	v_mul_f32_e32 v229, v228, v226
	v_fma_f32 v227, -v225, v229, v228
	v_fmac_f32_e32 v229, v227, v226
	v_fma_f32 v225, -v225, v229, v228
	v_div_fmas_f32 v225, v225, v226, v229
	v_div_fixup_f32 v95, v225, v231, 1.0
	v_cvt_pk_bf16_f32 v144, v94, v95
	v_mul_f32_e32 v230, 0xbfb8aa3b, v92
	v_mul_f32_e32 v231, 0xbfb8aa3b, v93
	v_exp_f32_e32 v230, v230
	v_exp_f32_e32 v231, v231
	s_nop 0
	v_add_f32_e32 v230, 1.0, v230
	v_add_f32_e32 v231, 1.0, v231
	v_div_scale_f32 v220, s[66:67], v230, v230, 1.0
	v_rcp_f32_e32 v221, v220
	s_nop 0
	v_fma_f32 v222, -v220, v221, 1.0
	v_fmac_f32_e32 v221, v222, v221
	v_div_scale_f32 v223, vcc, 1.0, v230, 1.0
	v_mul_f32_e32 v224, v223, v221
	v_fma_f32 v222, -v220, v224, v223
	v_fmac_f32_e32 v224, v222, v221
	v_fma_f32 v220, -v220, v224, v223
	v_div_fmas_f32 v220, v220, v221, v224
	v_div_fixup_f32 v92, v220, v230, 1.0
	v_div_scale_f32 v225, s[66:67], v231, v231, 1.0
	v_rcp_f32_e32 v226, v225
	s_nop 0
	v_fma_f32 v227, -v225, v226, 1.0
	v_fmac_f32_e32 v226, v227, v226
	v_div_scale_f32 v228, vcc, 1.0, v231, 1.0
	v_mul_f32_e32 v229, v228, v226
	v_fma_f32 v227, -v225, v229, v228
	v_fmac_f32_e32 v229, v227, v226
	v_fma_f32 v225, -v225, v229, v228
	v_div_fmas_f32 v225, v225, v226, v229
	v_div_fixup_f32 v93, v225, v231, 1.0
	v_cvt_pk_bf16_f32 v143, v92, v93
	v_mul_f32_e32 v230, 0xbfb8aa3b, v90
	v_mul_f32_e32 v231, 0xbfb8aa3b, v91
	v_exp_f32_e32 v230, v230
	v_exp_f32_e32 v231, v231
	s_nop 0
	v_add_f32_e32 v230, 1.0, v230
	v_add_f32_e32 v231, 1.0, v231
	v_div_scale_f32 v220, s[66:67], v230, v230, 1.0
	v_rcp_f32_e32 v221, v220
	s_nop 0
	v_fma_f32 v222, -v220, v221, 1.0
	v_fmac_f32_e32 v221, v222, v221
	v_div_scale_f32 v223, vcc, 1.0, v230, 1.0
	v_mul_f32_e32 v224, v223, v221
	v_fma_f32 v222, -v220, v224, v223
	v_fmac_f32_e32 v224, v222, v221
	v_fma_f32 v220, -v220, v224, v223
	v_div_fmas_f32 v220, v220, v221, v224
	v_div_fixup_f32 v90, v220, v230, 1.0
	v_div_scale_f32 v225, s[66:67], v231, v231, 1.0
	v_rcp_f32_e32 v226, v225
	s_nop 0
	v_fma_f32 v227, -v225, v226, 1.0
	v_fmac_f32_e32 v226, v227, v226
	v_div_scale_f32 v228, vcc, 1.0, v231, 1.0
	v_mul_f32_e32 v229, v228, v226
	v_fma_f32 v227, -v225, v229, v228
	v_fmac_f32_e32 v229, v227, v226
	v_fma_f32 v225, -v225, v229, v228
	v_div_fmas_f32 v225, v225, v226, v229
	v_div_fixup_f32 v91, v225, v231, 1.0
	v_cvt_pk_bf16_f32 v142, v90, v91
	v_mul_f32_e32 v230, 0xbfb8aa3b, v88
	v_mul_f32_e32 v231, 0xbfb8aa3b, v89
	v_exp_f32_e32 v230, v230
	v_exp_f32_e32 v231, v231
	s_nop 0
	v_add_f32_e32 v230, 1.0, v230
	v_add_f32_e32 v231, 1.0, v231
	v_div_scale_f32 v220, s[66:67], v230, v230, 1.0
	v_rcp_f32_e32 v221, v220
	s_nop 0
	v_fma_f32 v222, -v220, v221, 1.0
	v_fmac_f32_e32 v221, v222, v221
	v_div_scale_f32 v223, vcc, 1.0, v230, 1.0
	v_mul_f32_e32 v224, v223, v221
	v_fma_f32 v222, -v220, v224, v223
	v_fmac_f32_e32 v224, v222, v221
	v_fma_f32 v220, -v220, v224, v223
	v_div_fmas_f32 v220, v220, v221, v224
	v_div_fixup_f32 v88, v220, v230, 1.0
	v_div_scale_f32 v225, s[66:67], v231, v231, 1.0
	v_rcp_f32_e32 v226, v225
	s_nop 0
	v_fma_f32 v227, -v225, v226, 1.0
	v_fmac_f32_e32 v226, v227, v226
	v_div_scale_f32 v228, vcc, 1.0, v231, 1.0
	v_mul_f32_e32 v229, v228, v226
	v_fma_f32 v227, -v225, v229, v228
	v_fmac_f32_e32 v229, v227, v226
	v_fma_f32 v225, -v225, v229, v228
	v_div_fmas_f32 v225, v225, v226, v229
	v_div_fixup_f32 v89, v225, v231, 1.0
	v_cvt_pk_bf16_f32 v141, v88, v89
	v_mul_f32_e32 v230, 0xbfb8aa3b, v86
	v_mul_f32_e32 v231, 0xbfb8aa3b, v87
	v_exp_f32_e32 v230, v230
	v_exp_f32_e32 v231, v231
	s_nop 0
	v_add_f32_e32 v230, 1.0, v230
	v_add_f32_e32 v231, 1.0, v231
	v_div_scale_f32 v220, s[66:67], v230, v230, 1.0
	v_rcp_f32_e32 v221, v220
	s_nop 0
	v_fma_f32 v222, -v220, v221, 1.0
	v_fmac_f32_e32 v221, v222, v221
	v_div_scale_f32 v223, vcc, 1.0, v230, 1.0
	v_mul_f32_e32 v224, v223, v221
	v_fma_f32 v222, -v220, v224, v223
	v_fmac_f32_e32 v224, v222, v221
	v_fma_f32 v220, -v220, v224, v223
	v_div_fmas_f32 v220, v220, v221, v224
	v_div_fixup_f32 v86, v220, v230, 1.0
	v_div_scale_f32 v225, s[66:67], v231, v231, 1.0
	v_rcp_f32_e32 v226, v225
	s_nop 0
	v_fma_f32 v227, -v225, v226, 1.0
	v_fmac_f32_e32 v226, v227, v226
	v_div_scale_f32 v228, vcc, 1.0, v231, 1.0
	v_mul_f32_e32 v229, v228, v226
	v_fma_f32 v227, -v225, v229, v228
	v_fmac_f32_e32 v229, v227, v226
	v_fma_f32 v225, -v225, v229, v228
	v_div_fmas_f32 v225, v225, v226, v229
	v_div_fixup_f32 v87, v225, v231, 1.0
	v_cvt_pk_bf16_f32 v140, v86, v87
	v_mul_f32_e32 v230, 0xbfb8aa3b, v84
	v_mul_f32_e32 v231, 0xbfb8aa3b, v85
	v_exp_f32_e32 v230, v230
	v_exp_f32_e32 v231, v231
	s_nop 0
	v_add_f32_e32 v230, 1.0, v230
	v_add_f32_e32 v231, 1.0, v231
	v_div_scale_f32 v220, s[66:67], v230, v230, 1.0
	v_rcp_f32_e32 v221, v220
	s_nop 0
	v_fma_f32 v222, -v220, v221, 1.0
	v_fmac_f32_e32 v221, v222, v221
	v_div_scale_f32 v223, vcc, 1.0, v230, 1.0
	v_mul_f32_e32 v224, v223, v221
	v_fma_f32 v222, -v220, v224, v223
	v_fmac_f32_e32 v224, v222, v221
	v_fma_f32 v220, -v220, v224, v223
	v_div_fmas_f32 v220, v220, v221, v224
	v_div_fixup_f32 v84, v220, v230, 1.0
	v_div_scale_f32 v225, s[66:67], v231, v231, 1.0
	v_rcp_f32_e32 v226, v225
	s_nop 0
	v_fma_f32 v227, -v225, v226, 1.0
	v_fmac_f32_e32 v226, v227, v226
	v_div_scale_f32 v228, vcc, 1.0, v231, 1.0
	v_mul_f32_e32 v229, v228, v226
	v_fma_f32 v227, -v225, v229, v228
	v_fmac_f32_e32 v229, v227, v226
	v_fma_f32 v225, -v225, v229, v228
	v_div_fmas_f32 v225, v225, v226, v229
	v_div_fixup_f32 v85, v225, v231, 1.0
	v_cvt_pk_bf16_f32 v139, v84, v85
	v_mul_f32_e32 v230, 0xbfb8aa3b, v82
	v_mul_f32_e32 v231, 0xbfb8aa3b, v83
	v_exp_f32_e32 v230, v230
	v_exp_f32_e32 v231, v231
	s_nop 0
	v_add_f32_e32 v230, 1.0, v230
	v_add_f32_e32 v231, 1.0, v231
	v_div_scale_f32 v220, s[66:67], v230, v230, 1.0
	v_rcp_f32_e32 v221, v220
	s_nop 0
	v_fma_f32 v222, -v220, v221, 1.0
	v_fmac_f32_e32 v221, v222, v221
	v_div_scale_f32 v223, vcc, 1.0, v230, 1.0
	v_mul_f32_e32 v224, v223, v221
	v_fma_f32 v222, -v220, v224, v223
	v_fmac_f32_e32 v224, v222, v221
	v_fma_f32 v220, -v220, v224, v223
	v_div_fmas_f32 v220, v220, v221, v224
	v_div_fixup_f32 v82, v220, v230, 1.0
	v_div_scale_f32 v225, s[66:67], v231, v231, 1.0
	v_rcp_f32_e32 v226, v225
	s_nop 0
	v_fma_f32 v227, -v225, v226, 1.0
	v_fmac_f32_e32 v226, v227, v226
	v_div_scale_f32 v228, vcc, 1.0, v231, 1.0
	v_mul_f32_e32 v229, v228, v226
	v_fma_f32 v227, -v225, v229, v228
	v_fmac_f32_e32 v229, v227, v226
	v_fma_f32 v225, -v225, v229, v228
	v_div_fmas_f32 v225, v225, v226, v229
	v_div_fixup_f32 v83, v225, v231, 1.0
	v_cvt_pk_bf16_f32 v138, v82, v83
	v_mul_f32_e32 v230, 0xbfb8aa3b, v80
	v_mul_f32_e32 v231, 0xbfb8aa3b, v81
	v_exp_f32_e32 v230, v230
	v_exp_f32_e32 v231, v231
	s_nop 0
	v_add_f32_e32 v230, 1.0, v230
	v_add_f32_e32 v231, 1.0, v231
	v_div_scale_f32 v220, s[66:67], v230, v230, 1.0
	v_rcp_f32_e32 v221, v220
	s_nop 0
	v_fma_f32 v222, -v220, v221, 1.0
	v_fmac_f32_e32 v221, v222, v221
	v_div_scale_f32 v223, vcc, 1.0, v230, 1.0
	v_mul_f32_e32 v224, v223, v221
	v_fma_f32 v222, -v220, v224, v223
	v_fmac_f32_e32 v224, v222, v221
	v_fma_f32 v220, -v220, v224, v223
	v_div_fmas_f32 v220, v220, v221, v224
	v_div_fixup_f32 v80, v220, v230, 1.0
	v_div_scale_f32 v225, s[66:67], v231, v231, 1.0
	v_rcp_f32_e32 v226, v225
	s_nop 0
	v_fma_f32 v227, -v225, v226, 1.0
	v_fmac_f32_e32 v226, v227, v226
	v_div_scale_f32 v228, vcc, 1.0, v231, 1.0
	v_mul_f32_e32 v229, v228, v226
	v_fma_f32 v227, -v225, v229, v228
	v_fmac_f32_e32 v229, v227, v226
	v_fma_f32 v225, -v225, v229, v228
	v_div_fmas_f32 v225, v225, v226, v229
	v_div_fixup_f32 v81, v225, v231, 1.0
	v_cvt_pk_bf16_f32 v137, v80, v81
	v_mul_f32_e32 v230, 0xbfb8aa3b, v78
	v_mul_f32_e32 v231, 0xbfb8aa3b, v79
	v_exp_f32_e32 v230, v230
	v_exp_f32_e32 v231, v231
	s_nop 0
	v_add_f32_e32 v230, 1.0, v230
	v_add_f32_e32 v231, 1.0, v231
	v_div_scale_f32 v220, s[66:67], v230, v230, 1.0
	v_rcp_f32_e32 v221, v220
	s_nop 0
	v_fma_f32 v222, -v220, v221, 1.0
	v_fmac_f32_e32 v221, v222, v221
	v_div_scale_f32 v223, vcc, 1.0, v230, 1.0
	v_mul_f32_e32 v224, v223, v221
	v_fma_f32 v222, -v220, v224, v223
	v_fmac_f32_e32 v224, v222, v221
	v_fma_f32 v220, -v220, v224, v223
	v_div_fmas_f32 v220, v220, v221, v224
	v_div_fixup_f32 v78, v220, v230, 1.0
	v_div_scale_f32 v225, s[66:67], v231, v231, 1.0
	v_rcp_f32_e32 v226, v225
	s_nop 0
	v_fma_f32 v227, -v225, v226, 1.0
	v_fmac_f32_e32 v226, v227, v226
	v_div_scale_f32 v228, vcc, 1.0, v231, 1.0
	v_mul_f32_e32 v229, v228, v226
	v_fma_f32 v227, -v225, v229, v228
	v_fmac_f32_e32 v229, v227, v226
	v_fma_f32 v225, -v225, v229, v228
	v_div_fmas_f32 v225, v225, v226, v229
	v_div_fixup_f32 v79, v225, v231, 1.0
	v_cvt_pk_bf16_f32 v136, v78, v79
	v_mul_f32_e32 v230, 0xbfb8aa3b, v76
	v_mul_f32_e32 v231, 0xbfb8aa3b, v77
	v_exp_f32_e32 v230, v230
	v_exp_f32_e32 v231, v231
	s_nop 0
	v_add_f32_e32 v230, 1.0, v230
	v_add_f32_e32 v231, 1.0, v231
	v_div_scale_f32 v220, s[66:67], v230, v230, 1.0
	v_rcp_f32_e32 v221, v220
	s_nop 0
	v_fma_f32 v222, -v220, v221, 1.0
	v_fmac_f32_e32 v221, v222, v221
	v_div_scale_f32 v223, vcc, 1.0, v230, 1.0
	v_mul_f32_e32 v224, v223, v221
	v_fma_f32 v222, -v220, v224, v223
	v_fmac_f32_e32 v224, v222, v221
	v_fma_f32 v220, -v220, v224, v223
	v_div_fmas_f32 v220, v220, v221, v224
	v_div_fixup_f32 v76, v220, v230, 1.0
	v_div_scale_f32 v225, s[66:67], v231, v231, 1.0
	v_rcp_f32_e32 v226, v225
	s_nop 0
	v_fma_f32 v227, -v225, v226, 1.0
	v_fmac_f32_e32 v226, v227, v226
	v_div_scale_f32 v228, vcc, 1.0, v231, 1.0
	v_mul_f32_e32 v229, v228, v226
	v_fma_f32 v227, -v225, v229, v228
	v_fmac_f32_e32 v229, v227, v226
	v_fma_f32 v225, -v225, v229, v228
	v_div_fmas_f32 v225, v225, v226, v229
	v_div_fixup_f32 v77, v225, v231, 1.0
	v_cvt_pk_bf16_f32 v135, v76, v77
	v_mul_f32_e32 v230, 0xbfb8aa3b, v74
	v_mul_f32_e32 v231, 0xbfb8aa3b, v75
	v_exp_f32_e32 v230, v230
	v_exp_f32_e32 v231, v231
	s_nop 0
	v_add_f32_e32 v230, 1.0, v230
	v_add_f32_e32 v231, 1.0, v231
	v_div_scale_f32 v220, s[66:67], v230, v230, 1.0
	v_rcp_f32_e32 v221, v220
	s_nop 0
	v_fma_f32 v222, -v220, v221, 1.0
	v_fmac_f32_e32 v221, v222, v221
	v_div_scale_f32 v223, vcc, 1.0, v230, 1.0
	v_mul_f32_e32 v224, v223, v221
	v_fma_f32 v222, -v220, v224, v223
	v_fmac_f32_e32 v224, v222, v221
	v_fma_f32 v220, -v220, v224, v223
	v_div_fmas_f32 v220, v220, v221, v224
	v_div_fixup_f32 v74, v220, v230, 1.0
	v_div_scale_f32 v225, s[66:67], v231, v231, 1.0
	v_rcp_f32_e32 v226, v225
	s_nop 0
	v_fma_f32 v227, -v225, v226, 1.0
	v_fmac_f32_e32 v226, v227, v226
	v_div_scale_f32 v228, vcc, 1.0, v231, 1.0
	v_mul_f32_e32 v229, v228, v226
	v_fma_f32 v227, -v225, v229, v228
	v_fmac_f32_e32 v229, v227, v226
	v_fma_f32 v225, -v225, v229, v228
	v_div_fmas_f32 v225, v225, v226, v229
	v_div_fixup_f32 v75, v225, v231, 1.0
	v_cvt_pk_bf16_f32 v134, v74, v75
	v_mul_f32_e32 v230, 0xbfb8aa3b, v72
	v_mul_f32_e32 v231, 0xbfb8aa3b, v73
	v_exp_f32_e32 v230, v230
	v_exp_f32_e32 v231, v231
	s_nop 0
	v_add_f32_e32 v230, 1.0, v230
	v_add_f32_e32 v231, 1.0, v231
	v_div_scale_f32 v220, s[66:67], v230, v230, 1.0
	v_rcp_f32_e32 v221, v220
	s_nop 0
	v_fma_f32 v222, -v220, v221, 1.0
	v_fmac_f32_e32 v221, v222, v221
	v_div_scale_f32 v223, vcc, 1.0, v230, 1.0
	v_mul_f32_e32 v224, v223, v221
	v_fma_f32 v222, -v220, v224, v223
	v_fmac_f32_e32 v224, v222, v221
	v_fma_f32 v220, -v220, v224, v223
	v_div_fmas_f32 v220, v220, v221, v224
	v_div_fixup_f32 v72, v220, v230, 1.0
	v_div_scale_f32 v225, s[66:67], v231, v231, 1.0
	v_rcp_f32_e32 v226, v225
	s_nop 0
	v_fma_f32 v227, -v225, v226, 1.0
	v_fmac_f32_e32 v226, v227, v226
	v_div_scale_f32 v228, vcc, 1.0, v231, 1.0
	v_mul_f32_e32 v229, v228, v226
	v_fma_f32 v227, -v225, v229, v228
	v_fmac_f32_e32 v229, v227, v226
	v_fma_f32 v225, -v225, v229, v228
	v_div_fmas_f32 v225, v225, v226, v229
	v_div_fixup_f32 v73, v225, v231, 1.0
	v_cvt_pk_bf16_f32 v133, v72, v73
	v_mul_f32_e32 v230, 0xbfb8aa3b, v70
	v_mul_f32_e32 v231, 0xbfb8aa3b, v71
	v_exp_f32_e32 v230, v230
	v_exp_f32_e32 v231, v231
	s_nop 0
	v_add_f32_e32 v230, 1.0, v230
	v_add_f32_e32 v231, 1.0, v231
	v_div_scale_f32 v220, s[66:67], v230, v230, 1.0
	v_rcp_f32_e32 v221, v220
	s_nop 0
	v_fma_f32 v222, -v220, v221, 1.0
	v_fmac_f32_e32 v221, v222, v221
	v_div_scale_f32 v223, vcc, 1.0, v230, 1.0
	v_mul_f32_e32 v224, v223, v221
	v_fma_f32 v222, -v220, v224, v223
	v_fmac_f32_e32 v224, v222, v221
	v_fma_f32 v220, -v220, v224, v223
	v_div_fmas_f32 v220, v220, v221, v224
	v_div_fixup_f32 v70, v220, v230, 1.0
	v_div_scale_f32 v225, s[66:67], v231, v231, 1.0
	v_rcp_f32_e32 v226, v225
	s_nop 0
	v_fma_f32 v227, -v225, v226, 1.0
	v_fmac_f32_e32 v226, v227, v226
	v_div_scale_f32 v228, vcc, 1.0, v231, 1.0
	v_mul_f32_e32 v229, v228, v226
	v_fma_f32 v227, -v225, v229, v228
	v_fmac_f32_e32 v229, v227, v226
	v_fma_f32 v225, -v225, v229, v228
	v_div_fmas_f32 v225, v225, v226, v229
	v_div_fixup_f32 v71, v225, v231, 1.0
	v_cvt_pk_bf16_f32 v132, v70, v71
	v_mul_f32_e32 v230, 0xbfb8aa3b, v68
	v_mul_f32_e32 v231, 0xbfb8aa3b, v69
	v_exp_f32_e32 v230, v230
	v_exp_f32_e32 v231, v231
	s_nop 0
	v_add_f32_e32 v230, 1.0, v230
	v_add_f32_e32 v231, 1.0, v231
	v_div_scale_f32 v220, s[66:67], v230, v230, 1.0
	v_rcp_f32_e32 v221, v220
	s_nop 0
	v_fma_f32 v222, -v220, v221, 1.0
	v_fmac_f32_e32 v221, v222, v221
	v_div_scale_f32 v223, vcc, 1.0, v230, 1.0
	v_mul_f32_e32 v224, v223, v221
	v_fma_f32 v222, -v220, v224, v223
	v_fmac_f32_e32 v224, v222, v221
	v_fma_f32 v220, -v220, v224, v223
	v_div_fmas_f32 v220, v220, v221, v224
	v_div_fixup_f32 v68, v220, v230, 1.0
	v_div_scale_f32 v225, s[66:67], v231, v231, 1.0
	v_rcp_f32_e32 v226, v225
	s_nop 0
	v_fma_f32 v227, -v225, v226, 1.0
	v_fmac_f32_e32 v226, v227, v226
	v_div_scale_f32 v228, vcc, 1.0, v231, 1.0
	v_mul_f32_e32 v229, v228, v226
	v_fma_f32 v227, -v225, v229, v228
	v_fmac_f32_e32 v229, v227, v226
	v_fma_f32 v225, -v225, v229, v228
	v_div_fmas_f32 v225, v225, v226, v229
	v_div_fixup_f32 v69, v225, v231, 1.0
	v_cvt_pk_bf16_f32 v131, v68, v69
	v_mul_f32_e32 v230, 0xbfb8aa3b, v66
	v_mul_f32_e32 v231, 0xbfb8aa3b, v67
	v_exp_f32_e32 v230, v230
	v_exp_f32_e32 v231, v231
	s_nop 0
	v_add_f32_e32 v230, 1.0, v230
	v_add_f32_e32 v231, 1.0, v231
	v_div_scale_f32 v220, s[66:67], v230, v230, 1.0
	v_rcp_f32_e32 v221, v220
	s_nop 0
	v_fma_f32 v222, -v220, v221, 1.0
	v_fmac_f32_e32 v221, v222, v221
	v_div_scale_f32 v223, vcc, 1.0, v230, 1.0
	v_mul_f32_e32 v224, v223, v221
	v_fma_f32 v222, -v220, v224, v223
	v_fmac_f32_e32 v224, v222, v221
	v_fma_f32 v220, -v220, v224, v223
	v_div_fmas_f32 v220, v220, v221, v224
	v_div_fixup_f32 v66, v220, v230, 1.0
	v_div_scale_f32 v225, s[66:67], v231, v231, 1.0
	v_rcp_f32_e32 v226, v225
	s_nop 0
	v_fma_f32 v227, -v225, v226, 1.0
	v_fmac_f32_e32 v226, v227, v226
	v_div_scale_f32 v228, vcc, 1.0, v231, 1.0
	v_mul_f32_e32 v229, v228, v226
	v_fma_f32 v227, -v225, v229, v228
	v_fmac_f32_e32 v229, v227, v226
	v_fma_f32 v225, -v225, v229, v228
	v_div_fmas_f32 v225, v225, v226, v229
	v_div_fixup_f32 v67, v225, v231, 1.0
	v_cvt_pk_bf16_f32 v130, v66, v67
	v_mul_f32_e32 v230, 0xbfb8aa3b, v64
	v_mul_f32_e32 v231, 0xbfb8aa3b, v65
	v_exp_f32_e32 v230, v230
	v_exp_f32_e32 v231, v231
	s_nop 0
	v_add_f32_e32 v230, 1.0, v230
	v_add_f32_e32 v231, 1.0, v231
	v_div_scale_f32 v220, s[66:67], v230, v230, 1.0
	v_rcp_f32_e32 v221, v220
	s_nop 0
	v_fma_f32 v222, -v220, v221, 1.0
	v_fmac_f32_e32 v221, v222, v221
	v_div_scale_f32 v223, vcc, 1.0, v230, 1.0
	v_mul_f32_e32 v224, v223, v221
	v_fma_f32 v222, -v220, v224, v223
	v_fmac_f32_e32 v224, v222, v221
	v_fma_f32 v220, -v220, v224, v223
	v_div_fmas_f32 v220, v220, v221, v224
	v_div_fixup_f32 v64, v220, v230, 1.0
	v_div_scale_f32 v225, s[66:67], v231, v231, 1.0
	v_rcp_f32_e32 v226, v225
	s_nop 0
	v_fma_f32 v227, -v225, v226, 1.0
	v_fmac_f32_e32 v226, v227, v226
	v_div_scale_f32 v228, vcc, 1.0, v231, 1.0
	v_mul_f32_e32 v229, v228, v226
	v_fma_f32 v227, -v225, v229, v228
	v_fmac_f32_e32 v229, v227, v226
	v_fma_f32 v225, -v225, v229, v228
	v_div_fmas_f32 v225, v225, v226, v229
	v_div_fixup_f32 v65, v225, v231, 1.0
	v_cvt_pk_bf16_f32 v129, v64, v65
	v_mul_f32_e32 v230, 0xbfb8aa3b, v62
	v_mul_f32_e32 v231, 0xbfb8aa3b, v63
	v_exp_f32_e32 v230, v230
	v_exp_f32_e32 v231, v231
	s_nop 0
	v_add_f32_e32 v230, 1.0, v230
	v_add_f32_e32 v231, 1.0, v231
	v_div_scale_f32 v220, s[66:67], v230, v230, 1.0
	v_rcp_f32_e32 v221, v220
	s_nop 0
	v_fma_f32 v222, -v220, v221, 1.0
	v_fmac_f32_e32 v221, v222, v221
	v_div_scale_f32 v223, vcc, 1.0, v230, 1.0
	v_mul_f32_e32 v224, v223, v221
	v_fma_f32 v222, -v220, v224, v223
	v_fmac_f32_e32 v224, v222, v221
	v_fma_f32 v220, -v220, v224, v223
	v_div_fmas_f32 v220, v220, v221, v224
	v_div_fixup_f32 v62, v220, v230, 1.0
	v_div_scale_f32 v225, s[66:67], v231, v231, 1.0
	v_rcp_f32_e32 v226, v225
	s_nop 0
	v_fma_f32 v227, -v225, v226, 1.0
	v_fmac_f32_e32 v226, v227, v226
	v_div_scale_f32 v228, vcc, 1.0, v231, 1.0
	v_mul_f32_e32 v229, v228, v226
	v_fma_f32 v227, -v225, v229, v228
	v_fmac_f32_e32 v229, v227, v226
	v_fma_f32 v225, -v225, v229, v228
	v_div_fmas_f32 v225, v225, v226, v229
	v_div_fixup_f32 v63, v225, v231, 1.0
	v_cvt_pk_bf16_f32 v128, v62, v63
	v_mul_f32_e32 v230, 0xbfb8aa3b, v60
	v_mul_f32_e32 v231, 0xbfb8aa3b, v61
	v_exp_f32_e32 v230, v230
	v_exp_f32_e32 v231, v231
	s_nop 0
	v_add_f32_e32 v230, 1.0, v230
	v_add_f32_e32 v231, 1.0, v231
	v_div_scale_f32 v220, s[66:67], v230, v230, 1.0
	v_rcp_f32_e32 v221, v220
	s_nop 0
	v_fma_f32 v222, -v220, v221, 1.0
	v_fmac_f32_e32 v221, v222, v221
	v_div_scale_f32 v223, vcc, 1.0, v230, 1.0
	v_mul_f32_e32 v224, v223, v221
	v_fma_f32 v222, -v220, v224, v223
	v_fmac_f32_e32 v224, v222, v221
	v_fma_f32 v220, -v220, v224, v223
	v_div_fmas_f32 v220, v220, v221, v224
	v_div_fixup_f32 v60, v220, v230, 1.0
	v_div_scale_f32 v225, s[66:67], v231, v231, 1.0
	v_rcp_f32_e32 v226, v225
	s_nop 0
	v_fma_f32 v227, -v225, v226, 1.0
	v_fmac_f32_e32 v226, v227, v226
	v_div_scale_f32 v228, vcc, 1.0, v231, 1.0
	v_mul_f32_e32 v229, v228, v226
	v_fma_f32 v227, -v225, v229, v228
	v_fmac_f32_e32 v229, v227, v226
	v_fma_f32 v225, -v225, v229, v228
	v_div_fmas_f32 v225, v225, v226, v229
	v_div_fixup_f32 v61, v225, v231, 1.0
	v_cvt_pk_bf16_f32 v127, v60, v61
	v_mul_f32_e32 v230, 0xbfb8aa3b, v58
	v_mul_f32_e32 v231, 0xbfb8aa3b, v59
	v_exp_f32_e32 v230, v230
	v_exp_f32_e32 v231, v231
	s_nop 0
	v_add_f32_e32 v230, 1.0, v230
	v_add_f32_e32 v231, 1.0, v231
	v_div_scale_f32 v220, s[66:67], v230, v230, 1.0
	v_rcp_f32_e32 v221, v220
	s_nop 0
	v_fma_f32 v222, -v220, v221, 1.0
	v_fmac_f32_e32 v221, v222, v221
	v_div_scale_f32 v223, vcc, 1.0, v230, 1.0
	v_mul_f32_e32 v224, v223, v221
	v_fma_f32 v222, -v220, v224, v223
	v_fmac_f32_e32 v224, v222, v221
	v_fma_f32 v220, -v220, v224, v223
	v_div_fmas_f32 v220, v220, v221, v224
	v_div_fixup_f32 v58, v220, v230, 1.0
	v_div_scale_f32 v225, s[66:67], v231, v231, 1.0
	v_rcp_f32_e32 v226, v225
	s_nop 0
	v_fma_f32 v227, -v225, v226, 1.0
	v_fmac_f32_e32 v226, v227, v226
	v_div_scale_f32 v228, vcc, 1.0, v231, 1.0
	v_mul_f32_e32 v229, v228, v226
	v_fma_f32 v227, -v225, v229, v228
	v_fmac_f32_e32 v229, v227, v226
	v_fma_f32 v225, -v225, v229, v228
	v_div_fmas_f32 v225, v225, v226, v229
	v_div_fixup_f32 v59, v225, v231, 1.0
	v_cvt_pk_bf16_f32 v126, v58, v59
	v_mul_f32_e32 v230, 0xbfb8aa3b, v56
	v_mul_f32_e32 v231, 0xbfb8aa3b, v57
	v_exp_f32_e32 v230, v230
	v_exp_f32_e32 v231, v231
	s_nop 0
	v_add_f32_e32 v230, 1.0, v230
	v_add_f32_e32 v231, 1.0, v231
	v_div_scale_f32 v220, s[66:67], v230, v230, 1.0
	v_rcp_f32_e32 v221, v220
	s_nop 0
	v_fma_f32 v222, -v220, v221, 1.0
	v_fmac_f32_e32 v221, v222, v221
	v_div_scale_f32 v223, vcc, 1.0, v230, 1.0
	v_mul_f32_e32 v224, v223, v221
	v_fma_f32 v222, -v220, v224, v223
	v_fmac_f32_e32 v224, v222, v221
	v_fma_f32 v220, -v220, v224, v223
	v_div_fmas_f32 v220, v220, v221, v224
	v_div_fixup_f32 v56, v220, v230, 1.0
	v_div_scale_f32 v225, s[66:67], v231, v231, 1.0
	v_rcp_f32_e32 v226, v225
	s_nop 0
	v_fma_f32 v227, -v225, v226, 1.0
	v_fmac_f32_e32 v226, v227, v226
	v_div_scale_f32 v228, vcc, 1.0, v231, 1.0
	v_mul_f32_e32 v229, v228, v226
	v_fma_f32 v227, -v225, v229, v228
	v_fmac_f32_e32 v229, v227, v226
	v_fma_f32 v225, -v225, v229, v228
	v_div_fmas_f32 v225, v225, v226, v229
	v_div_fixup_f32 v57, v225, v231, 1.0
	v_cvt_pk_bf16_f32 v125, v56, v57
	v_mul_f32_e32 v230, 0xbfb8aa3b, v54
	v_mul_f32_e32 v231, 0xbfb8aa3b, v55
	v_exp_f32_e32 v230, v230
	v_exp_f32_e32 v231, v231
	s_nop 0
	v_add_f32_e32 v230, 1.0, v230
	v_add_f32_e32 v231, 1.0, v231
	v_div_scale_f32 v220, s[66:67], v230, v230, 1.0
	v_rcp_f32_e32 v221, v220
	s_nop 0
	v_fma_f32 v222, -v220, v221, 1.0
	v_fmac_f32_e32 v221, v222, v221
	v_div_scale_f32 v223, vcc, 1.0, v230, 1.0
	v_mul_f32_e32 v224, v223, v221
	v_fma_f32 v222, -v220, v224, v223
	v_fmac_f32_e32 v224, v222, v221
	v_fma_f32 v220, -v220, v224, v223
	v_div_fmas_f32 v220, v220, v221, v224
	v_div_fixup_f32 v54, v220, v230, 1.0
	v_div_scale_f32 v225, s[66:67], v231, v231, 1.0
	v_rcp_f32_e32 v226, v225
	s_nop 0
	v_fma_f32 v227, -v225, v226, 1.0
	v_fmac_f32_e32 v226, v227, v226
	v_div_scale_f32 v228, vcc, 1.0, v231, 1.0
	v_mul_f32_e32 v229, v228, v226
	v_fma_f32 v227, -v225, v229, v228
	v_fmac_f32_e32 v229, v227, v226
	v_fma_f32 v225, -v225, v229, v228
	v_div_fmas_f32 v225, v225, v226, v229
	v_div_fixup_f32 v55, v225, v231, 1.0
	v_cvt_pk_bf16_f32 v124, v54, v55
	v_mul_f32_e32 v230, 0xbfb8aa3b, v52
	v_mul_f32_e32 v231, 0xbfb8aa3b, v53
	v_exp_f32_e32 v230, v230
	v_exp_f32_e32 v231, v231
	s_nop 0
	v_add_f32_e32 v230, 1.0, v230
	v_add_f32_e32 v231, 1.0, v231
	v_div_scale_f32 v220, s[66:67], v230, v230, 1.0
	v_rcp_f32_e32 v221, v220
	s_nop 0
	v_fma_f32 v222, -v220, v221, 1.0
	v_fmac_f32_e32 v221, v222, v221
	v_div_scale_f32 v223, vcc, 1.0, v230, 1.0
	v_mul_f32_e32 v224, v223, v221
	v_fma_f32 v222, -v220, v224, v223
	v_fmac_f32_e32 v224, v222, v221
	v_fma_f32 v220, -v220, v224, v223
	v_div_fmas_f32 v220, v220, v221, v224
	v_div_fixup_f32 v52, v220, v230, 1.0
	v_div_scale_f32 v225, s[66:67], v231, v231, 1.0
	v_rcp_f32_e32 v226, v225
	s_nop 0
	v_fma_f32 v227, -v225, v226, 1.0
	v_fmac_f32_e32 v226, v227, v226
	v_div_scale_f32 v228, vcc, 1.0, v231, 1.0
	v_mul_f32_e32 v229, v228, v226
	v_fma_f32 v227, -v225, v229, v228
	v_fmac_f32_e32 v229, v227, v226
	v_fma_f32 v225, -v225, v229, v228
	v_div_fmas_f32 v225, v225, v226, v229
	v_div_fixup_f32 v53, v225, v231, 1.0
	v_cvt_pk_bf16_f32 v123, v52, v53
	v_mul_f32_e32 v230, 0xbfb8aa3b, v50
	v_mul_f32_e32 v231, 0xbfb8aa3b, v51
	v_exp_f32_e32 v230, v230
	v_exp_f32_e32 v231, v231
	s_nop 0
	v_add_f32_e32 v230, 1.0, v230
	v_add_f32_e32 v231, 1.0, v231
	v_div_scale_f32 v220, s[66:67], v230, v230, 1.0
	v_rcp_f32_e32 v221, v220
	s_nop 0
	v_fma_f32 v222, -v220, v221, 1.0
	v_fmac_f32_e32 v221, v222, v221
	v_div_scale_f32 v223, vcc, 1.0, v230, 1.0
	v_mul_f32_e32 v224, v223, v221
	v_fma_f32 v222, -v220, v224, v223
	v_fmac_f32_e32 v224, v222, v221
	v_fma_f32 v220, -v220, v224, v223
	v_div_fmas_f32 v220, v220, v221, v224
	v_div_fixup_f32 v50, v220, v230, 1.0
	v_div_scale_f32 v225, s[66:67], v231, v231, 1.0
	v_rcp_f32_e32 v226, v225
	s_nop 0
	v_fma_f32 v227, -v225, v226, 1.0
	v_fmac_f32_e32 v226, v227, v226
	v_div_scale_f32 v228, vcc, 1.0, v231, 1.0
	v_mul_f32_e32 v229, v228, v226
	v_fma_f32 v227, -v225, v229, v228
	v_fmac_f32_e32 v229, v227, v226
	v_fma_f32 v225, -v225, v229, v228
	v_div_fmas_f32 v225, v225, v226, v229
	v_div_fixup_f32 v51, v225, v231, 1.0
	v_cvt_pk_bf16_f32 v122, v50, v51
	v_mul_f32_e32 v230, 0xbfb8aa3b, v48
	v_mul_f32_e32 v231, 0xbfb8aa3b, v49
	v_exp_f32_e32 v230, v230
	v_exp_f32_e32 v231, v231
	s_nop 0
	v_add_f32_e32 v230, 1.0, v230
	v_add_f32_e32 v231, 1.0, v231
	v_div_scale_f32 v220, s[66:67], v230, v230, 1.0
	v_rcp_f32_e32 v221, v220
	s_nop 0
	v_fma_f32 v222, -v220, v221, 1.0
	v_fmac_f32_e32 v221, v222, v221
	v_div_scale_f32 v223, vcc, 1.0, v230, 1.0
	v_mul_f32_e32 v224, v223, v221
	v_fma_f32 v222, -v220, v224, v223
	v_fmac_f32_e32 v224, v222, v221
	v_fma_f32 v220, -v220, v224, v223
	v_div_fmas_f32 v220, v220, v221, v224
	v_div_fixup_f32 v48, v220, v230, 1.0
	v_div_scale_f32 v225, s[66:67], v231, v231, 1.0
	v_rcp_f32_e32 v226, v225
	s_nop 0
	v_fma_f32 v227, -v225, v226, 1.0
	v_fmac_f32_e32 v226, v227, v226
	v_div_scale_f32 v228, vcc, 1.0, v231, 1.0
	v_mul_f32_e32 v229, v228, v226
	v_fma_f32 v227, -v225, v229, v228
	v_fmac_f32_e32 v229, v227, v226
	v_fma_f32 v225, -v225, v229, v228
	v_div_fmas_f32 v225, v225, v226, v229
	v_div_fixup_f32 v49, v225, v231, 1.0
	v_cvt_pk_bf16_f32 v121, v48, v49
	v_mul_f32_e32 v230, 0xbfb8aa3b, v46
	v_mul_f32_e32 v231, 0xbfb8aa3b, v47
	v_exp_f32_e32 v230, v230
	v_exp_f32_e32 v231, v231
	s_nop 0
	v_add_f32_e32 v230, 1.0, v230
	v_add_f32_e32 v231, 1.0, v231
	v_div_scale_f32 v220, s[66:67], v230, v230, 1.0
	v_rcp_f32_e32 v221, v220
	s_nop 0
	v_fma_f32 v222, -v220, v221, 1.0
	v_fmac_f32_e32 v221, v222, v221
	v_div_scale_f32 v223, vcc, 1.0, v230, 1.0
	v_mul_f32_e32 v224, v223, v221
	v_fma_f32 v222, -v220, v224, v223
	v_fmac_f32_e32 v224, v222, v221
	v_fma_f32 v220, -v220, v224, v223
	v_div_fmas_f32 v220, v220, v221, v224
	v_div_fixup_f32 v46, v220, v230, 1.0
	v_div_scale_f32 v225, s[66:67], v231, v231, 1.0
	v_rcp_f32_e32 v226, v225
	s_nop 0
	v_fma_f32 v227, -v225, v226, 1.0
	v_fmac_f32_e32 v226, v227, v226
	v_div_scale_f32 v228, vcc, 1.0, v231, 1.0
	v_mul_f32_e32 v229, v228, v226
	v_fma_f32 v227, -v225, v229, v228
	v_fmac_f32_e32 v229, v227, v226
	v_fma_f32 v225, -v225, v229, v228
	v_div_fmas_f32 v225, v225, v226, v229
	v_div_fixup_f32 v47, v225, v231, 1.0
	v_cvt_pk_bf16_f32 v120, v46, v47
	v_mul_f32_e32 v230, 0xbfb8aa3b, v44
	v_mul_f32_e32 v231, 0xbfb8aa3b, v45
	v_exp_f32_e32 v230, v230
	v_exp_f32_e32 v231, v231
	s_nop 0
	v_add_f32_e32 v230, 1.0, v230
	v_add_f32_e32 v231, 1.0, v231
	v_div_scale_f32 v220, s[66:67], v230, v230, 1.0
	v_rcp_f32_e32 v221, v220
	s_nop 0
	v_fma_f32 v222, -v220, v221, 1.0
	v_fmac_f32_e32 v221, v222, v221
	v_div_scale_f32 v223, vcc, 1.0, v230, 1.0
	v_mul_f32_e32 v224, v223, v221
	v_fma_f32 v222, -v220, v224, v223
	v_fmac_f32_e32 v224, v222, v221
	v_fma_f32 v220, -v220, v224, v223
	v_div_fmas_f32 v220, v220, v221, v224
	v_div_fixup_f32 v44, v220, v230, 1.0
	v_div_scale_f32 v225, s[66:67], v231, v231, 1.0
	v_rcp_f32_e32 v226, v225
	s_nop 0
	v_fma_f32 v227, -v225, v226, 1.0
	v_fmac_f32_e32 v226, v227, v226
	v_div_scale_f32 v228, vcc, 1.0, v231, 1.0
	v_mul_f32_e32 v229, v228, v226
	v_fma_f32 v227, -v225, v229, v228
	v_fmac_f32_e32 v229, v227, v226
	v_fma_f32 v225, -v225, v229, v228
	v_div_fmas_f32 v225, v225, v226, v229
	v_div_fixup_f32 v45, v225, v231, 1.0
	v_cvt_pk_bf16_f32 v119, v44, v45
	v_mul_f32_e32 v230, 0xbfb8aa3b, v42
	v_mul_f32_e32 v231, 0xbfb8aa3b, v43
	v_exp_f32_e32 v230, v230
	v_exp_f32_e32 v231, v231
	s_nop 0
	v_add_f32_e32 v230, 1.0, v230
	v_add_f32_e32 v231, 1.0, v231
	v_div_scale_f32 v220, s[66:67], v230, v230, 1.0
	v_rcp_f32_e32 v221, v220
	s_nop 0
	v_fma_f32 v222, -v220, v221, 1.0
	v_fmac_f32_e32 v221, v222, v221
	v_div_scale_f32 v223, vcc, 1.0, v230, 1.0
	v_mul_f32_e32 v224, v223, v221
	v_fma_f32 v222, -v220, v224, v223
	v_fmac_f32_e32 v224, v222, v221
	v_fma_f32 v220, -v220, v224, v223
	v_div_fmas_f32 v220, v220, v221, v224
	v_div_fixup_f32 v42, v220, v230, 1.0
	v_div_scale_f32 v225, s[66:67], v231, v231, 1.0
	v_rcp_f32_e32 v226, v225
	s_nop 0
	v_fma_f32 v227, -v225, v226, 1.0
	v_fmac_f32_e32 v226, v227, v226
	v_div_scale_f32 v228, vcc, 1.0, v231, 1.0
	v_mul_f32_e32 v229, v228, v226
	v_fma_f32 v227, -v225, v229, v228
	v_fmac_f32_e32 v229, v227, v226
	v_fma_f32 v225, -v225, v229, v228
	v_div_fmas_f32 v225, v225, v226, v229
	v_div_fixup_f32 v43, v225, v231, 1.0
	v_cvt_pk_bf16_f32 v118, v42, v43
	v_mul_f32_e32 v230, 0xbfb8aa3b, v40
	v_mul_f32_e32 v231, 0xbfb8aa3b, v41
	v_exp_f32_e32 v230, v230
	v_exp_f32_e32 v231, v231
	s_nop 0
	v_add_f32_e32 v230, 1.0, v230
	v_add_f32_e32 v231, 1.0, v231
	v_div_scale_f32 v220, s[66:67], v230, v230, 1.0
	v_rcp_f32_e32 v221, v220
	s_nop 0
	v_fma_f32 v222, -v220, v221, 1.0
	v_fmac_f32_e32 v221, v222, v221
	v_div_scale_f32 v223, vcc, 1.0, v230, 1.0
	v_mul_f32_e32 v224, v223, v221
	v_fma_f32 v222, -v220, v224, v223
	v_fmac_f32_e32 v224, v222, v221
	v_fma_f32 v220, -v220, v224, v223
	v_div_fmas_f32 v220, v220, v221, v224
	v_div_fixup_f32 v40, v220, v230, 1.0
	v_div_scale_f32 v225, s[66:67], v231, v231, 1.0
	v_rcp_f32_e32 v226, v225
	s_nop 0
	v_fma_f32 v227, -v225, v226, 1.0
	v_fmac_f32_e32 v226, v227, v226
	v_div_scale_f32 v228, vcc, 1.0, v231, 1.0
	v_mul_f32_e32 v229, v228, v226
	v_fma_f32 v227, -v225, v229, v228
	v_fmac_f32_e32 v229, v227, v226
	v_fma_f32 v225, -v225, v229, v228
	v_div_fmas_f32 v225, v225, v226, v229
	v_div_fixup_f32 v41, v225, v231, 1.0
	v_cvt_pk_bf16_f32 v117, v40, v41
	v_mul_f32_e32 v230, 0xbfb8aa3b, v38
	v_mul_f32_e32 v231, 0xbfb8aa3b, v39
	v_exp_f32_e32 v230, v230
	v_exp_f32_e32 v231, v231
	s_nop 0
	v_add_f32_e32 v230, 1.0, v230
	v_add_f32_e32 v231, 1.0, v231
	v_div_scale_f32 v220, s[66:67], v230, v230, 1.0
	v_rcp_f32_e32 v221, v220
	s_nop 0
	v_fma_f32 v222, -v220, v221, 1.0
	v_fmac_f32_e32 v221, v222, v221
	v_div_scale_f32 v223, vcc, 1.0, v230, 1.0
	v_mul_f32_e32 v224, v223, v221
	v_fma_f32 v222, -v220, v224, v223
	v_fmac_f32_e32 v224, v222, v221
	v_fma_f32 v220, -v220, v224, v223
	v_div_fmas_f32 v220, v220, v221, v224
	v_div_fixup_f32 v38, v220, v230, 1.0
	v_div_scale_f32 v225, s[66:67], v231, v231, 1.0
	v_rcp_f32_e32 v226, v225
	s_nop 0
	v_fma_f32 v227, -v225, v226, 1.0
	v_fmac_f32_e32 v226, v227, v226
	v_div_scale_f32 v228, vcc, 1.0, v231, 1.0
	v_mul_f32_e32 v229, v228, v226
	v_fma_f32 v227, -v225, v229, v228
	v_fmac_f32_e32 v229, v227, v226
	v_fma_f32 v225, -v225, v229, v228
	v_div_fmas_f32 v225, v225, v226, v229
	v_div_fixup_f32 v39, v225, v231, 1.0
	v_cvt_pk_bf16_f32 v116, v38, v39
	v_mul_f32_e32 v230, 0xbfb8aa3b, v36
	v_mul_f32_e32 v231, 0xbfb8aa3b, v37
	v_exp_f32_e32 v230, v230
	v_exp_f32_e32 v231, v231
	s_nop 0
	v_add_f32_e32 v230, 1.0, v230
	v_add_f32_e32 v231, 1.0, v231
	v_div_scale_f32 v220, s[66:67], v230, v230, 1.0
	v_rcp_f32_e32 v221, v220
	s_nop 0
	v_fma_f32 v222, -v220, v221, 1.0
	v_fmac_f32_e32 v221, v222, v221
	v_div_scale_f32 v223, vcc, 1.0, v230, 1.0
	v_mul_f32_e32 v224, v223, v221
	v_fma_f32 v222, -v220, v224, v223
	v_fmac_f32_e32 v224, v222, v221
	v_fma_f32 v220, -v220, v224, v223
	v_div_fmas_f32 v220, v220, v221, v224
	v_div_fixup_f32 v36, v220, v230, 1.0
	v_div_scale_f32 v225, s[66:67], v231, v231, 1.0
	v_rcp_f32_e32 v226, v225
	s_nop 0
	v_fma_f32 v227, -v225, v226, 1.0
	v_fmac_f32_e32 v226, v227, v226
	v_div_scale_f32 v228, vcc, 1.0, v231, 1.0
	v_mul_f32_e32 v229, v228, v226
	v_fma_f32 v227, -v225, v229, v228
	v_fmac_f32_e32 v229, v227, v226
	v_fma_f32 v225, -v225, v229, v228
	v_div_fmas_f32 v225, v225, v226, v229
	v_div_fixup_f32 v37, v225, v231, 1.0
	v_cvt_pk_bf16_f32 v115, v36, v37
	v_mul_f32_e32 v230, 0xbfb8aa3b, v34
	v_mul_f32_e32 v231, 0xbfb8aa3b, v35
	v_exp_f32_e32 v230, v230
	v_exp_f32_e32 v231, v231
	s_nop 0
	v_add_f32_e32 v230, 1.0, v230
	v_add_f32_e32 v231, 1.0, v231
	v_div_scale_f32 v220, s[66:67], v230, v230, 1.0
	v_rcp_f32_e32 v221, v220
	s_nop 0
	v_fma_f32 v222, -v220, v221, 1.0
	v_fmac_f32_e32 v221, v222, v221
	v_div_scale_f32 v223, vcc, 1.0, v230, 1.0
	v_mul_f32_e32 v224, v223, v221
	v_fma_f32 v222, -v220, v224, v223
	v_fmac_f32_e32 v224, v222, v221
	v_fma_f32 v220, -v220, v224, v223
	v_div_fmas_f32 v220, v220, v221, v224
	v_div_fixup_f32 v34, v220, v230, 1.0
	v_div_scale_f32 v225, s[66:67], v231, v231, 1.0
	v_rcp_f32_e32 v226, v225
	s_nop 0
	v_fma_f32 v227, -v225, v226, 1.0
	v_fmac_f32_e32 v226, v227, v226
	v_div_scale_f32 v228, vcc, 1.0, v231, 1.0
	v_mul_f32_e32 v229, v228, v226
	v_fma_f32 v227, -v225, v229, v228
	v_fmac_f32_e32 v229, v227, v226
	v_fma_f32 v225, -v225, v229, v228
	v_div_fmas_f32 v225, v225, v226, v229
	v_div_fixup_f32 v35, v225, v231, 1.0
	v_cvt_pk_bf16_f32 v114, v34, v35
	v_mul_f32_e32 v230, 0xbfb8aa3b, v32
	v_mul_f32_e32 v231, 0xbfb8aa3b, v33
	v_exp_f32_e32 v230, v230
	v_exp_f32_e32 v231, v231
	s_nop 0
	v_add_f32_e32 v230, 1.0, v230
	v_add_f32_e32 v231, 1.0, v231
	v_div_scale_f32 v220, s[66:67], v230, v230, 1.0
	v_rcp_f32_e32 v221, v220
	s_nop 0
	v_fma_f32 v222, -v220, v221, 1.0
	v_fmac_f32_e32 v221, v222, v221
	v_div_scale_f32 v223, vcc, 1.0, v230, 1.0
	v_mul_f32_e32 v224, v223, v221
	v_fma_f32 v222, -v220, v224, v223
	v_fmac_f32_e32 v224, v222, v221
	v_fma_f32 v220, -v220, v224, v223
	v_div_fmas_f32 v220, v220, v221, v224
	v_div_fixup_f32 v32, v220, v230, 1.0
	v_div_scale_f32 v225, s[66:67], v231, v231, 1.0
	v_rcp_f32_e32 v226, v225
	s_nop 0
	v_fma_f32 v227, -v225, v226, 1.0
	v_fmac_f32_e32 v226, v227, v226
	v_div_scale_f32 v228, vcc, 1.0, v231, 1.0
	v_mul_f32_e32 v229, v228, v226
	v_fma_f32 v227, -v225, v229, v228
	v_fmac_f32_e32 v229, v227, v226
	v_fma_f32 v225, -v225, v229, v228
	v_div_fmas_f32 v225, v225, v226, v229
	v_div_fixup_f32 v33, v225, v231, 1.0
	v_cvt_pk_bf16_f32 v113, v32, v33
	v_mul_f32_e32 v230, 0xbfb8aa3b, v30
	v_mul_f32_e32 v231, 0xbfb8aa3b, v31
	v_exp_f32_e32 v230, v230
	v_exp_f32_e32 v231, v231
	s_nop 0
	v_add_f32_e32 v230, 1.0, v230
	v_add_f32_e32 v231, 1.0, v231
	v_div_scale_f32 v220, s[66:67], v230, v230, 1.0
	v_rcp_f32_e32 v221, v220
	s_nop 0
	v_fma_f32 v222, -v220, v221, 1.0
	v_fmac_f32_e32 v221, v222, v221
	v_div_scale_f32 v223, vcc, 1.0, v230, 1.0
	v_mul_f32_e32 v224, v223, v221
	v_fma_f32 v222, -v220, v224, v223
	v_fmac_f32_e32 v224, v222, v221
	v_fma_f32 v220, -v220, v224, v223
	v_div_fmas_f32 v220, v220, v221, v224
	v_div_fixup_f32 v30, v220, v230, 1.0
	v_div_scale_f32 v225, s[66:67], v231, v231, 1.0
	v_rcp_f32_e32 v226, v225
	s_nop 0
	v_fma_f32 v227, -v225, v226, 1.0
	v_fmac_f32_e32 v226, v227, v226
	v_div_scale_f32 v228, vcc, 1.0, v231, 1.0
	v_mul_f32_e32 v229, v228, v226
	v_fma_f32 v227, -v225, v229, v228
	v_fmac_f32_e32 v229, v227, v226
	v_fma_f32 v225, -v225, v229, v228
	v_div_fmas_f32 v225, v225, v226, v229
	v_div_fixup_f32 v31, v225, v231, 1.0
	v_cvt_pk_bf16_f32 v112, v30, v31
	v_mul_f32_e32 v230, 0xbfb8aa3b, v28
	v_mul_f32_e32 v231, 0xbfb8aa3b, v29
	v_exp_f32_e32 v230, v230
	v_exp_f32_e32 v231, v231
	s_nop 0
	v_add_f32_e32 v230, 1.0, v230
	v_add_f32_e32 v231, 1.0, v231
	v_div_scale_f32 v220, s[66:67], v230, v230, 1.0
	v_rcp_f32_e32 v221, v220
	s_nop 0
	v_fma_f32 v222, -v220, v221, 1.0
	v_fmac_f32_e32 v221, v222, v221
	v_div_scale_f32 v223, vcc, 1.0, v230, 1.0
	v_mul_f32_e32 v224, v223, v221
	v_fma_f32 v222, -v220, v224, v223
	v_fmac_f32_e32 v224, v222, v221
	v_fma_f32 v220, -v220, v224, v223
	v_div_fmas_f32 v220, v220, v221, v224
	v_div_fixup_f32 v28, v220, v230, 1.0
	v_div_scale_f32 v225, s[66:67], v231, v231, 1.0
	v_rcp_f32_e32 v226, v225
	s_nop 0
	v_fma_f32 v227, -v225, v226, 1.0
	v_fmac_f32_e32 v226, v227, v226
	v_div_scale_f32 v228, vcc, 1.0, v231, 1.0
	v_mul_f32_e32 v229, v228, v226
	v_fma_f32 v227, -v225, v229, v228
	v_fmac_f32_e32 v229, v227, v226
	v_fma_f32 v225, -v225, v229, v228
	v_div_fmas_f32 v225, v225, v226, v229
	v_div_fixup_f32 v29, v225, v231, 1.0
	v_cvt_pk_bf16_f32 v111, v28, v29
	v_mul_f32_e32 v230, 0xbfb8aa3b, v26
	v_mul_f32_e32 v231, 0xbfb8aa3b, v27
	v_exp_f32_e32 v230, v230
	v_exp_f32_e32 v231, v231
	s_nop 0
	v_add_f32_e32 v230, 1.0, v230
	v_add_f32_e32 v231, 1.0, v231
	v_div_scale_f32 v220, s[66:67], v230, v230, 1.0
	v_rcp_f32_e32 v221, v220
	s_nop 0
	v_fma_f32 v222, -v220, v221, 1.0
	v_fmac_f32_e32 v221, v222, v221
	v_div_scale_f32 v223, vcc, 1.0, v230, 1.0
	v_mul_f32_e32 v224, v223, v221
	v_fma_f32 v222, -v220, v224, v223
	v_fmac_f32_e32 v224, v222, v221
	v_fma_f32 v220, -v220, v224, v223
	v_div_fmas_f32 v220, v220, v221, v224
	v_div_fixup_f32 v26, v220, v230, 1.0
	v_div_scale_f32 v225, s[66:67], v231, v231, 1.0
	v_rcp_f32_e32 v226, v225
	s_nop 0
	v_fma_f32 v227, -v225, v226, 1.0
	v_fmac_f32_e32 v226, v227, v226
	v_div_scale_f32 v228, vcc, 1.0, v231, 1.0
	v_mul_f32_e32 v229, v228, v226
	v_fma_f32 v227, -v225, v229, v228
	v_fmac_f32_e32 v229, v227, v226
	v_fma_f32 v225, -v225, v229, v228
	v_div_fmas_f32 v225, v225, v226, v229
	v_div_fixup_f32 v27, v225, v231, 1.0
	v_cvt_pk_bf16_f32 v110, v26, v27
	v_mul_f32_e32 v230, 0xbfb8aa3b, v24
	v_mul_f32_e32 v231, 0xbfb8aa3b, v25
	v_exp_f32_e32 v230, v230
	v_exp_f32_e32 v231, v231
	s_nop 0
	v_add_f32_e32 v230, 1.0, v230
	v_add_f32_e32 v231, 1.0, v231
	v_div_scale_f32 v220, s[66:67], v230, v230, 1.0
	v_rcp_f32_e32 v221, v220
	s_nop 0
	v_fma_f32 v222, -v220, v221, 1.0
	v_fmac_f32_e32 v221, v222, v221
	v_div_scale_f32 v223, vcc, 1.0, v230, 1.0
	v_mul_f32_e32 v224, v223, v221
	v_fma_f32 v222, -v220, v224, v223
	v_fmac_f32_e32 v224, v222, v221
	v_fma_f32 v220, -v220, v224, v223
	v_div_fmas_f32 v220, v220, v221, v224
	v_div_fixup_f32 v24, v220, v230, 1.0
	v_div_scale_f32 v225, s[66:67], v231, v231, 1.0
	v_rcp_f32_e32 v226, v225
	s_nop 0
	v_fma_f32 v227, -v225, v226, 1.0
	v_fmac_f32_e32 v226, v227, v226
	v_div_scale_f32 v228, vcc, 1.0, v231, 1.0
	v_mul_f32_e32 v229, v228, v226
	v_fma_f32 v227, -v225, v229, v228
	v_fmac_f32_e32 v229, v227, v226
	v_fma_f32 v225, -v225, v229, v228
	v_div_fmas_f32 v225, v225, v226, v229
	v_div_fixup_f32 v25, v225, v231, 1.0
	v_cvt_pk_bf16_f32 v109, v24, v25
	v_mul_f32_e32 v230, 0xbfb8aa3b, v22
	v_mul_f32_e32 v231, 0xbfb8aa3b, v23
	v_exp_f32_e32 v230, v230
	v_exp_f32_e32 v231, v231
	s_nop 0
	v_add_f32_e32 v230, 1.0, v230
	v_add_f32_e32 v231, 1.0, v231
	v_div_scale_f32 v220, s[66:67], v230, v230, 1.0
	v_rcp_f32_e32 v221, v220
	s_nop 0
	v_fma_f32 v222, -v220, v221, 1.0
	v_fmac_f32_e32 v221, v222, v221
	v_div_scale_f32 v223, vcc, 1.0, v230, 1.0
	v_mul_f32_e32 v224, v223, v221
	v_fma_f32 v222, -v220, v224, v223
	v_fmac_f32_e32 v224, v222, v221
	v_fma_f32 v220, -v220, v224, v223
	v_div_fmas_f32 v220, v220, v221, v224
	v_div_fixup_f32 v22, v220, v230, 1.0
	v_div_scale_f32 v225, s[66:67], v231, v231, 1.0
	v_rcp_f32_e32 v226, v225
	s_nop 0
	v_fma_f32 v227, -v225, v226, 1.0
	v_fmac_f32_e32 v226, v227, v226
	v_div_scale_f32 v228, vcc, 1.0, v231, 1.0
	v_mul_f32_e32 v229, v228, v226
	v_fma_f32 v227, -v225, v229, v228
	v_fmac_f32_e32 v229, v227, v226
	v_fma_f32 v225, -v225, v229, v228
	v_div_fmas_f32 v225, v225, v226, v229
	v_div_fixup_f32 v23, v225, v231, 1.0
	v_cvt_pk_bf16_f32 v108, v22, v23
	v_mul_f32_e32 v230, 0xbfb8aa3b, v20
	v_mul_f32_e32 v231, 0xbfb8aa3b, v21
	v_exp_f32_e32 v230, v230
	v_exp_f32_e32 v231, v231
	s_nop 0
	v_add_f32_e32 v230, 1.0, v230
	v_add_f32_e32 v231, 1.0, v231
	v_div_scale_f32 v220, s[66:67], v230, v230, 1.0
	v_rcp_f32_e32 v221, v220
	s_nop 0
	v_fma_f32 v222, -v220, v221, 1.0
	v_fmac_f32_e32 v221, v222, v221
	v_div_scale_f32 v223, vcc, 1.0, v230, 1.0
	v_mul_f32_e32 v224, v223, v221
	v_fma_f32 v222, -v220, v224, v223
	v_fmac_f32_e32 v224, v222, v221
	v_fma_f32 v220, -v220, v224, v223
	v_div_fmas_f32 v220, v220, v221, v224
	v_div_fixup_f32 v20, v220, v230, 1.0
	v_div_scale_f32 v225, s[66:67], v231, v231, 1.0
	v_rcp_f32_e32 v226, v225
	s_nop 0
	v_fma_f32 v227, -v225, v226, 1.0
	v_fmac_f32_e32 v226, v227, v226
	v_div_scale_f32 v228, vcc, 1.0, v231, 1.0
	v_mul_f32_e32 v229, v228, v226
	v_fma_f32 v227, -v225, v229, v228
	v_fmac_f32_e32 v229, v227, v226
	v_fma_f32 v225, -v225, v229, v228
	v_div_fmas_f32 v225, v225, v226, v229
	v_div_fixup_f32 v21, v225, v231, 1.0
	v_cvt_pk_bf16_f32 v107, v20, v21
	v_mul_f32_e32 v230, 0xbfb8aa3b, v18
	v_mul_f32_e32 v231, 0xbfb8aa3b, v19
	v_exp_f32_e32 v230, v230
	v_exp_f32_e32 v231, v231
	s_nop 0
	v_add_f32_e32 v230, 1.0, v230
	v_add_f32_e32 v231, 1.0, v231
	v_div_scale_f32 v220, s[66:67], v230, v230, 1.0
	v_rcp_f32_e32 v221, v220
	s_nop 0
	v_fma_f32 v222, -v220, v221, 1.0
	v_fmac_f32_e32 v221, v222, v221
	v_div_scale_f32 v223, vcc, 1.0, v230, 1.0
	v_mul_f32_e32 v224, v223, v221
	v_fma_f32 v222, -v220, v224, v223
	v_fmac_f32_e32 v224, v222, v221
	v_fma_f32 v220, -v220, v224, v223
	v_div_fmas_f32 v220, v220, v221, v224
	v_div_fixup_f32 v18, v220, v230, 1.0
	v_div_scale_f32 v225, s[66:67], v231, v231, 1.0
	v_rcp_f32_e32 v226, v225
	s_nop 0
	v_fma_f32 v227, -v225, v226, 1.0
	v_fmac_f32_e32 v226, v227, v226
	v_div_scale_f32 v228, vcc, 1.0, v231, 1.0
	v_mul_f32_e32 v229, v228, v226
	v_fma_f32 v227, -v225, v229, v228
	v_fmac_f32_e32 v229, v227, v226
	v_fma_f32 v225, -v225, v229, v228
	v_div_fmas_f32 v225, v225, v226, v229
	v_div_fixup_f32 v19, v225, v231, 1.0
	v_cvt_pk_bf16_f32 v106, v18, v19
	v_mul_f32_e32 v230, 0xbfb8aa3b, v16
	v_mul_f32_e32 v231, 0xbfb8aa3b, v17
	v_exp_f32_e32 v230, v230
	v_exp_f32_e32 v231, v231
	s_nop 0
	v_add_f32_e32 v230, 1.0, v230
	v_add_f32_e32 v231, 1.0, v231
	v_div_scale_f32 v220, s[66:67], v230, v230, 1.0
	v_rcp_f32_e32 v221, v220
	s_nop 0
	v_fma_f32 v222, -v220, v221, 1.0
	v_fmac_f32_e32 v221, v222, v221
	v_div_scale_f32 v223, vcc, 1.0, v230, 1.0
	v_mul_f32_e32 v224, v223, v221
	v_fma_f32 v222, -v220, v224, v223
	v_fmac_f32_e32 v224, v222, v221
	v_fma_f32 v220, -v220, v224, v223
	v_div_fmas_f32 v220, v220, v221, v224
	v_div_fixup_f32 v16, v220, v230, 1.0
	v_div_scale_f32 v225, s[66:67], v231, v231, 1.0
	v_rcp_f32_e32 v226, v225
	s_nop 0
	v_fma_f32 v227, -v225, v226, 1.0
	v_fmac_f32_e32 v226, v227, v226
	v_div_scale_f32 v228, vcc, 1.0, v231, 1.0
	v_mul_f32_e32 v229, v228, v226
	v_fma_f32 v227, -v225, v229, v228
	v_fmac_f32_e32 v229, v227, v226
	v_fma_f32 v225, -v225, v229, v228
	v_div_fmas_f32 v225, v225, v226, v229
	v_div_fixup_f32 v17, v225, v231, 1.0
	v_cvt_pk_bf16_f32 v105, v16, v17
	v_mul_f32_e32 v230, 0xbfb8aa3b, v14
	v_mul_f32_e32 v231, 0xbfb8aa3b, v15
	v_exp_f32_e32 v230, v230
	v_exp_f32_e32 v231, v231
	s_nop 0
	v_add_f32_e32 v230, 1.0, v230
	v_add_f32_e32 v231, 1.0, v231
	v_div_scale_f32 v220, s[66:67], v230, v230, 1.0
	v_rcp_f32_e32 v221, v220
	s_nop 0
	v_fma_f32 v222, -v220, v221, 1.0
	v_fmac_f32_e32 v221, v222, v221
	v_div_scale_f32 v223, vcc, 1.0, v230, 1.0
	v_mul_f32_e32 v224, v223, v221
	v_fma_f32 v222, -v220, v224, v223
	v_fmac_f32_e32 v224, v222, v221
	v_fma_f32 v220, -v220, v224, v223
	v_div_fmas_f32 v220, v220, v221, v224
	v_div_fixup_f32 v14, v220, v230, 1.0
	v_div_scale_f32 v225, s[66:67], v231, v231, 1.0
	v_rcp_f32_e32 v226, v225
	s_nop 0
	v_fma_f32 v227, -v225, v226, 1.0
	v_fmac_f32_e32 v226, v227, v226
	v_div_scale_f32 v228, vcc, 1.0, v231, 1.0
	v_mul_f32_e32 v229, v228, v226
	v_fma_f32 v227, -v225, v229, v228
	v_fmac_f32_e32 v229, v227, v226
	v_fma_f32 v225, -v225, v229, v228
	v_div_fmas_f32 v225, v225, v226, v229
	v_div_fixup_f32 v15, v225, v231, 1.0
	v_cvt_pk_bf16_f32 v104, v14, v15
	v_mul_f32_e32 v230, 0xbfb8aa3b, v12
	v_mul_f32_e32 v231, 0xbfb8aa3b, v13
	v_exp_f32_e32 v230, v230
	v_exp_f32_e32 v231, v231
	s_nop 0
	v_add_f32_e32 v230, 1.0, v230
	v_add_f32_e32 v231, 1.0, v231
	v_div_scale_f32 v220, s[66:67], v230, v230, 1.0
	v_rcp_f32_e32 v221, v220
	s_nop 0
	v_fma_f32 v222, -v220, v221, 1.0
	v_fmac_f32_e32 v221, v222, v221
	v_div_scale_f32 v223, vcc, 1.0, v230, 1.0
	v_mul_f32_e32 v224, v223, v221
	v_fma_f32 v222, -v220, v224, v223
	v_fmac_f32_e32 v224, v222, v221
	v_fma_f32 v220, -v220, v224, v223
	v_div_fmas_f32 v220, v220, v221, v224
	v_div_fixup_f32 v12, v220, v230, 1.0
	v_div_scale_f32 v225, s[66:67], v231, v231, 1.0
	v_rcp_f32_e32 v226, v225
	s_nop 0
	v_fma_f32 v227, -v225, v226, 1.0
	v_fmac_f32_e32 v226, v227, v226
	v_div_scale_f32 v228, vcc, 1.0, v231, 1.0
	v_mul_f32_e32 v229, v228, v226
	v_fma_f32 v227, -v225, v229, v228
	v_fmac_f32_e32 v229, v227, v226
	v_fma_f32 v225, -v225, v229, v228
	v_div_fmas_f32 v225, v225, v226, v229
	v_div_fixup_f32 v13, v225, v231, 1.0
	v_cvt_pk_bf16_f32 v103, v12, v13
	v_mul_f32_e32 v230, 0xbfb8aa3b, v10
	v_mul_f32_e32 v231, 0xbfb8aa3b, v11
	v_exp_f32_e32 v230, v230
	v_exp_f32_e32 v231, v231
	s_nop 0
	v_add_f32_e32 v230, 1.0, v230
	v_add_f32_e32 v231, 1.0, v231
	v_div_scale_f32 v220, s[66:67], v230, v230, 1.0
	v_rcp_f32_e32 v221, v220
	s_nop 0
	v_fma_f32 v222, -v220, v221, 1.0
	v_fmac_f32_e32 v221, v222, v221
	v_div_scale_f32 v223, vcc, 1.0, v230, 1.0
	v_mul_f32_e32 v224, v223, v221
	v_fma_f32 v222, -v220, v224, v223
	v_fmac_f32_e32 v224, v222, v221
	v_fma_f32 v220, -v220, v224, v223
	v_div_fmas_f32 v220, v220, v221, v224
	v_div_fixup_f32 v10, v220, v230, 1.0
	v_div_scale_f32 v225, s[66:67], v231, v231, 1.0
	v_rcp_f32_e32 v226, v225
	s_nop 0
	v_fma_f32 v227, -v225, v226, 1.0
	v_fmac_f32_e32 v226, v227, v226
	v_div_scale_f32 v228, vcc, 1.0, v231, 1.0
	v_mul_f32_e32 v229, v228, v226
	v_fma_f32 v227, -v225, v229, v228
	v_fmac_f32_e32 v229, v227, v226
	v_fma_f32 v225, -v225, v229, v228
	v_div_fmas_f32 v225, v225, v226, v229
	v_div_fixup_f32 v11, v225, v231, 1.0
	v_cvt_pk_bf16_f32 v102, v10, v11
	v_mul_f32_e32 v230, 0xbfb8aa3b, v8
	v_mul_f32_e32 v231, 0xbfb8aa3b, v9
	v_exp_f32_e32 v230, v230
	v_exp_f32_e32 v231, v231
	s_nop 0
	v_add_f32_e32 v230, 1.0, v230
	v_add_f32_e32 v231, 1.0, v231
	v_div_scale_f32 v220, s[66:67], v230, v230, 1.0
	v_rcp_f32_e32 v221, v220
	s_nop 0
	v_fma_f32 v222, -v220, v221, 1.0
	v_fmac_f32_e32 v221, v222, v221
	v_div_scale_f32 v223, vcc, 1.0, v230, 1.0
	v_mul_f32_e32 v224, v223, v221
	v_fma_f32 v222, -v220, v224, v223
	v_fmac_f32_e32 v224, v222, v221
	v_fma_f32 v220, -v220, v224, v223
	v_div_fmas_f32 v220, v220, v221, v224
	v_div_fixup_f32 v8, v220, v230, 1.0
	v_div_scale_f32 v225, s[66:67], v231, v231, 1.0
	v_rcp_f32_e32 v226, v225
	s_nop 0
	v_fma_f32 v227, -v225, v226, 1.0
	v_fmac_f32_e32 v226, v227, v226
	v_div_scale_f32 v228, vcc, 1.0, v231, 1.0
	v_mul_f32_e32 v229, v228, v226
	v_fma_f32 v227, -v225, v229, v228
	v_fmac_f32_e32 v229, v227, v226
	v_fma_f32 v225, -v225, v229, v228
	v_div_fmas_f32 v225, v225, v226, v229
	v_div_fixup_f32 v9, v225, v231, 1.0
	v_cvt_pk_bf16_f32 v101, v8, v9
	v_mul_f32_e32 v230, 0xbfb8aa3b, v6
	v_mul_f32_e32 v231, 0xbfb8aa3b, v7
	v_exp_f32_e32 v230, v230
	v_exp_f32_e32 v231, v231
	s_nop 0
	v_add_f32_e32 v230, 1.0, v230
	v_add_f32_e32 v231, 1.0, v231
	v_div_scale_f32 v220, s[66:67], v230, v230, 1.0
	v_rcp_f32_e32 v221, v220
	s_nop 0
	v_fma_f32 v222, -v220, v221, 1.0
	v_fmac_f32_e32 v221, v222, v221
	v_div_scale_f32 v223, vcc, 1.0, v230, 1.0
	v_mul_f32_e32 v224, v223, v221
	v_fma_f32 v222, -v220, v224, v223
	v_fmac_f32_e32 v224, v222, v221
	v_fma_f32 v220, -v220, v224, v223
	v_div_fmas_f32 v220, v220, v221, v224
	v_div_fixup_f32 v6, v220, v230, 1.0
	v_div_scale_f32 v225, s[66:67], v231, v231, 1.0
	v_rcp_f32_e32 v226, v225
	s_nop 0
	v_fma_f32 v227, -v225, v226, 1.0
	v_fmac_f32_e32 v226, v227, v226
	v_div_scale_f32 v228, vcc, 1.0, v231, 1.0
	v_mul_f32_e32 v229, v228, v226
	v_fma_f32 v227, -v225, v229, v228
	v_fmac_f32_e32 v229, v227, v226
	v_fma_f32 v225, -v225, v229, v228
	v_div_fmas_f32 v225, v225, v226, v229
	v_div_fixup_f32 v7, v225, v231, 1.0
	v_cvt_pk_bf16_f32 v100, v6, v7
	v_mul_f32_e32 v230, 0xbfb8aa3b, v4
	v_mul_f32_e32 v231, 0xbfb8aa3b, v5
	v_exp_f32_e32 v230, v230
	v_exp_f32_e32 v231, v231
	s_nop 0
	v_add_f32_e32 v230, 1.0, v230
	v_add_f32_e32 v231, 1.0, v231
	v_div_scale_f32 v220, s[66:67], v230, v230, 1.0
	v_rcp_f32_e32 v221, v220
	s_nop 0
	v_fma_f32 v222, -v220, v221, 1.0
	v_fmac_f32_e32 v221, v222, v221
	v_div_scale_f32 v223, vcc, 1.0, v230, 1.0
	v_mul_f32_e32 v224, v223, v221
	v_fma_f32 v222, -v220, v224, v223
	v_fmac_f32_e32 v224, v222, v221
	v_fma_f32 v220, -v220, v224, v223
	v_div_fmas_f32 v220, v220, v221, v224
	v_div_fixup_f32 v4, v220, v230, 1.0
	v_div_scale_f32 v225, s[66:67], v231, v231, 1.0
	v_rcp_f32_e32 v226, v225
	s_nop 0
	v_fma_f32 v227, -v225, v226, 1.0
	v_fmac_f32_e32 v226, v227, v226
	v_div_scale_f32 v228, vcc, 1.0, v231, 1.0
	v_mul_f32_e32 v229, v228, v226
	v_fma_f32 v227, -v225, v229, v228
	v_fmac_f32_e32 v229, v227, v226
	v_fma_f32 v225, -v225, v229, v228
	v_div_fmas_f32 v225, v225, v226, v229
	v_div_fixup_f32 v5, v225, v231, 1.0
	v_cvt_pk_bf16_f32 v99, v4, v5
	v_mul_f32_e32 v230, 0xbfb8aa3b, v2
	v_mul_f32_e32 v231, 0xbfb8aa3b, v3
	v_exp_f32_e32 v230, v230
	v_exp_f32_e32 v231, v231
	s_nop 0
	v_add_f32_e32 v230, 1.0, v230
	v_add_f32_e32 v231, 1.0, v231
	v_div_scale_f32 v220, s[66:67], v230, v230, 1.0
	v_rcp_f32_e32 v221, v220
	s_nop 0
	v_fma_f32 v222, -v220, v221, 1.0
	v_fmac_f32_e32 v221, v222, v221
	v_div_scale_f32 v223, vcc, 1.0, v230, 1.0
	v_mul_f32_e32 v224, v223, v221
	v_fma_f32 v222, -v220, v224, v223
	v_fmac_f32_e32 v224, v222, v221
	v_fma_f32 v220, -v220, v224, v223
	v_div_fmas_f32 v220, v220, v221, v224
	v_div_fixup_f32 v2, v220, v230, 1.0
	v_div_scale_f32 v225, s[66:67], v231, v231, 1.0
	v_rcp_f32_e32 v226, v225
	s_nop 0
	v_fma_f32 v227, -v225, v226, 1.0
	v_fmac_f32_e32 v226, v227, v226
	v_div_scale_f32 v228, vcc, 1.0, v231, 1.0
	v_mul_f32_e32 v229, v228, v226
	v_fma_f32 v227, -v225, v229, v228
	v_fmac_f32_e32 v229, v227, v226
	v_fma_f32 v225, -v225, v229, v228
	v_div_fmas_f32 v225, v225, v226, v229
	v_div_fixup_f32 v3, v225, v231, 1.0
	v_cvt_pk_bf16_f32 v98, v2, v3
	s_add_u32 s98, s48, 0x0
	s_addc_u32 s99, s49, 0
	s_add_u32 s100, s44, 0x0
	s_addc_u32 s101, s45, 0
	s_mov_b32 s51, 2
	v_mov_b32_e32 v12, v199
	v_lshrrev_b32_e32 v2, 3, v12
	v_and_b32_e32 v3, 7, v12
	v_bfe_u32 v4, v12, 4, 3
	v_xor_b32_e32 v3, v3, v4
	v_lshlrev_b32_e32 v3, 4, v3
	v_mul_u32_u24_e32 v2, 0x700, v2
	v_add_u32_e32 v220, v2, v3
	v_add_u32_e32 v221, 0xe000, v220
	v_add_u32_e32 v222, 0x1c000, v220
	v_add_u32_e32 v223, 0x2a000, v220
	v_lshlrev_b32_e32 v4, 4, v12
	v_and_b32_e32 v5, 31, v12
	v_bfe_u32 v6, v12, 5, 1
	v_bfe_u32 v7, v12, 1, 3
	v_xor_b32_e32 v6, v6, v7
	v_lshlrev_b32_e32 v226, 4, v6
	v_lshlrev_b32_e32 v5, 7, v5
	v_bfe_u32 v8, v12, 7, 1
	v_bfe_u32 v9, v12, 6, 1
	v_lshl_or_b32 v224, v8, 13, v5
	v_lshl_or_b32 v225, v9, 13, v5
	v_readfirstlane_b32 s52, v4
	s_waitcnt vmcnt(0)
	s_barrier
	s_add_u32 m0, s52, 0x0
	v_mov_b32_e32 v2, 0
	global_load_lds_dwordx4 v220, s[98:99]
	s_add_u32 m0, s52, 0x1000
	v_mov_b32_e32 v3, 0
	global_load_lds_dwordx4 v221, s[98:99]
	s_add_u32 m0, s52, 0x2000
	v_mov_b32_e32 v4, 0
	global_load_lds_dwordx4 v222, s[98:99]
	s_add_u32 m0, s52, 0x3000
	v_mov_b32_e32 v5, 0
	global_load_lds_dwordx4 v223, s[98:99]
	s_add_u32 m0, s52, 0x4000
	v_mov_b32_e32 v6, 0
	global_load_lds_dwordx4 v220, s[100:101]
	s_add_u32 m0, s52, 0x5000
	v_mov_b32_e32 v7, 0
	global_load_lds_dwordx4 v221, s[100:101]
	s_add_u32 m0, s52, 0x6000
	v_mov_b32_e32 v8, 0
	global_load_lds_dwordx4 v222, s[100:101]
	s_add_u32 m0, s52, 0x7000
	v_mov_b32_e32 v9, 0
	global_load_lds_dwordx4 v223, s[100:101]
	s_add_u32 s98, s98, 0x80
	s_addc_u32 s99, s99, 0
	s_add_u32 s100, s100, 0x80
	s_addc_u32 s101, s101, 0
	s_add_u32 m0, s52, 0x8000
	v_mov_b32_e32 v10, 0
	global_load_lds_dwordx4 v220, s[98:99]
	s_add_u32 m0, s52, 0x9000
	v_mov_b32_e32 v11, 0
	global_load_lds_dwordx4 v221, s[98:99]
	s_add_u32 m0, s52, 0xa000
	v_mov_b32_e32 v12, 0
	global_load_lds_dwordx4 v222, s[98:99]
	s_add_u32 m0, s52, 0xb000
	v_mov_b32_e32 v13, 0
	global_load_lds_dwordx4 v223, s[98:99]
	s_add_u32 m0, s52, 0xc000
	v_mov_b32_e32 v14, 0
	global_load_lds_dwordx4 v220, s[100:101]
	s_add_u32 m0, s52, 0xd000
	v_mov_b32_e32 v15, 0
	global_load_lds_dwordx4 v221, s[100:101]
	s_add_u32 m0, s52, 0xe000
	v_mov_b32_e32 v16, 0
	global_load_lds_dwordx4 v222, s[100:101]
	s_add_u32 m0, s52, 0xf000
	v_mov_b32_e32 v17, 0
	global_load_lds_dwordx4 v223, s[100:101]
	s_add_u32 s98, s98, 0x80
	s_addc_u32 s99, s99, 0
	s_add_u32 s100, s100, 0x80
	s_addc_u32 s101, s101, 0
	v_mov_b32_e32 v18, 0
	v_mov_b32_e32 v19, 0
	v_mov_b32_e32 v20, 0
	v_mov_b32_e32 v21, 0
	v_mov_b32_e32 v22, 0
	v_mov_b32_e32 v23, 0
	v_mov_b32_e32 v24, 0
	v_mov_b32_e32 v25, 0
	v_mov_b32_e32 v26, 0
	v_mov_b32_e32 v27, 0
	v_mov_b32_e32 v28, 0
	v_mov_b32_e32 v29, 0
	v_mov_b32_e32 v30, 0
	v_mov_b32_e32 v31, 0
	v_mov_b32_e32 v32, 0
	v_mov_b32_e32 v33, 0
	v_mov_b32_e32 v34, 0
	v_mov_b32_e32 v35, 0
	v_mov_b32_e32 v36, 0
	v_mov_b32_e32 v37, 0
	v_mov_b32_e32 v38, 0
	v_mov_b32_e32 v39, 0
	v_mov_b32_e32 v40, 0
	v_mov_b32_e32 v41, 0
	v_mov_b32_e32 v42, 0
	v_mov_b32_e32 v43, 0
	v_mov_b32_e32 v44, 0
	v_mov_b32_e32 v45, 0
	v_mov_b32_e32 v46, 0
	v_mov_b32_e32 v47, 0
	v_mov_b32_e32 v48, 0
	v_mov_b32_e32 v49, 0
	v_mov_b32_e32 v50, 0
	v_mov_b32_e32 v51, 0
	v_mov_b32_e32 v52, 0
	v_mov_b32_e32 v53, 0
	v_mov_b32_e32 v54, 0
	v_mov_b32_e32 v55, 0
	v_mov_b32_e32 v56, 0
	v_mov_b32_e32 v57, 0
	v_mov_b32_e32 v58, 0
	v_mov_b32_e32 v59, 0
	v_mov_b32_e32 v60, 0
	v_mov_b32_e32 v61, 0
	v_mov_b32_e32 v62, 0
	v_mov_b32_e32 v63, 0
	v_mov_b32_e32 v64, 0
	v_mov_b32_e32 v65, 0
	s_waitcnt vmcnt(8)
	s_barrier
	v_add_u32_e32 v66, v226, v224
	v_add_u32_e32 v70, v226, v225
	ds_read_b128 v[78:81], v66
	ds_read_b128 v[66:69], v66 offset:4096
	ds_read_b128 v[74:77], v70 offset:16384
	ds_read_b128 v[70:73], v70 offset:20480
.Lp4f_b0_loop:
	s_waitcnt lgkmcnt(0)
	v_mfma_f32_32x32x16_bf16 v[50:65], v[74:77], v[78:81], v[50:65]
	v_xor_b32_e32 v86, 0x20, v226
	v_add_u32_e32 v82, v86, v224
	v_add_u32_e32 v86, v86, v225
	v_mfma_f32_32x32x16_bf16 v[34:49], v[70:73], v[78:81], v[34:49]
	ds_read_b128 v[78:81], v82
	ds_read_b128 v[82:85], v82 offset:4096
	v_mfma_f32_32x32x16_bf16 v[18:33], v[74:77], v[66:69], v[18:33]
	ds_read_b128 v[74:77], v86 offset:16384
	ds_read_b128 v[86:89], v86 offset:20480
	v_mfma_f32_32x32x16_bf16 v[2:17], v[70:73], v[66:69], v[2:17]
	s_waitcnt lgkmcnt(0)
	v_mfma_f32_32x32x16_bf16 v[50:65], v[74:77], v[78:81], v[50:65]
	v_xor_b32_e32 v70, 0x40, v226
	v_add_u32_e32 v66, v70, v224
	v_add_u32_e32 v70, v70, v225
	v_mfma_f32_32x32x16_bf16 v[34:49], v[86:89], v[78:81], v[34:49]
	ds_read_b128 v[78:81], v66
	ds_read_b128 v[66:69], v66 offset:4096
	v_mfma_f32_32x32x16_bf16 v[18:33], v[74:77], v[82:85], v[18:33]
	ds_read_b128 v[74:77], v70 offset:16384
	ds_read_b128 v[70:73], v70 offset:20480
	v_mfma_f32_32x32x16_bf16 v[2:17], v[86:89], v[82:85], v[2:17]
	s_waitcnt lgkmcnt(0)
	v_mfma_f32_32x32x16_bf16 v[50:65], v[74:77], v[78:81], v[50:65]
	v_xor_b32_e32 v86, 0x60, v226
	v_add_u32_e32 v82, v86, v224
	v_add_u32_e32 v86, v86, v225
	v_mfma_f32_32x32x16_bf16 v[34:49], v[70:73], v[78:81], v[34:49]
	ds_read_b128 v[78:81], v82
	ds_read_b128 v[82:85], v82 offset:4096
	v_mfma_f32_32x32x16_bf16 v[18:33], v[74:77], v[66:69], v[18:33]
	ds_read_b128 v[74:77], v86 offset:16384
	ds_read_b128 v[86:89], v86 offset:20480
	v_mfma_f32_32x32x16_bf16 v[2:17], v[70:73], v[66:69], v[2:17]
	s_waitcnt vmcnt(0) lgkmcnt(0)
	s_barrier
	s_waitcnt lgkmcnt(0)
	v_mfma_f32_32x32x16_bf16 v[50:65], v[74:77], v[78:81], v[50:65]
	v_mov_b32_e32 v70, v226
	v_add_u32_e32 v66, v70, v224
	v_add_u32_e32 v70, v70, v225
	v_mfma_f32_32x32x16_bf16 v[34:49], v[86:89], v[78:81], v[34:49]
	ds_read_b128 v[78:81], v66 offset:32768
	ds_read_b128 v[66:69], v66 offset:36864
	s_add_u32 m0, s52, 0x0
	s_nop 0
	global_load_lds_dwordx4 v220, s[98:99]
	s_add_u32 m0, s52, 0x1000
	s_nop 0
	global_load_lds_dwordx4 v221, s[98:99]
	v_mfma_f32_32x32x16_bf16 v[18:33], v[74:77], v[82:85], v[18:33]
	ds_read_b128 v[74:77], v70 offset:49152
	ds_read_b128 v[70:73], v70 offset:53248
	s_add_u32 m0, s52, 0x2000
	s_nop 0
	global_load_lds_dwordx4 v222, s[98:99]
	s_add_u32 m0, s52, 0x3000
	s_nop 0
	global_load_lds_dwordx4 v223, s[98:99]
	v_mfma_f32_32x32x16_bf16 v[2:17], v[86:89], v[82:85], v[2:17]
	s_add_u32 m0, s52, 0x4000
	s_nop 0
	global_load_lds_dwordx4 v220, s[100:101]
	s_add_u32 m0, s52, 0x5000
	s_nop 0
	global_load_lds_dwordx4 v221, s[100:101]
	s_add_u32 m0, s52, 0x6000
	s_nop 0
	global_load_lds_dwordx4 v222, s[100:101]
	s_add_u32 m0, s52, 0x7000
	s_nop 0
	global_load_lds_dwordx4 v223, s[100:101]
	s_add_u32 s98, s98, 0x80
	s_addc_u32 s99, s99, 0
	s_add_u32 s100, s100, 0x80
	s_addc_u32 s101, s101, 0
	s_waitcnt lgkmcnt(0)
	v_mfma_f32_32x32x16_bf16 v[50:65], v[74:77], v[78:81], v[50:65]
	v_xor_b32_e32 v86, 0x20, v226
	v_add_u32_e32 v82, v86, v224
	v_add_u32_e32 v86, v86, v225
	v_mfma_f32_32x32x16_bf16 v[34:49], v[70:73], v[78:81], v[34:49]
	ds_read_b128 v[78:81], v82 offset:32768
	ds_read_b128 v[82:85], v82 offset:36864
	v_mfma_f32_32x32x16_bf16 v[18:33], v[74:77], v[66:69], v[18:33]
	ds_read_b128 v[74:77], v86 offset:49152
	ds_read_b128 v[86:89], v86 offset:53248
	v_mfma_f32_32x32x16_bf16 v[2:17], v[70:73], v[66:69], v[2:17]
	s_waitcnt lgkmcnt(0)
	v_mfma_f32_32x32x16_bf16 v[50:65], v[74:77], v[78:81], v[50:65]
	v_xor_b32_e32 v70, 0x40, v226
	v_add_u32_e32 v66, v70, v224
	v_add_u32_e32 v70, v70, v225
	v_mfma_f32_32x32x16_bf16 v[34:49], v[86:89], v[78:81], v[34:49]
	ds_read_b128 v[78:81], v66 offset:32768
	ds_read_b128 v[66:69], v66 offset:36864
	v_mfma_f32_32x32x16_bf16 v[18:33], v[74:77], v[82:85], v[18:33]
	ds_read_b128 v[74:77], v70 offset:49152
	ds_read_b128 v[70:73], v70 offset:53248
	v_mfma_f32_32x32x16_bf16 v[2:17], v[86:89], v[82:85], v[2:17]
	s_waitcnt lgkmcnt(0)
	v_mfma_f32_32x32x16_bf16 v[50:65], v[74:77], v[78:81], v[50:65]
	v_xor_b32_e32 v86, 0x60, v226
	v_add_u32_e32 v82, v86, v224
	v_add_u32_e32 v86, v86, v225
	v_mfma_f32_32x32x16_bf16 v[34:49], v[70:73], v[78:81], v[34:49]
	ds_read_b128 v[78:81], v82 offset:32768
	ds_read_b128 v[82:85], v82 offset:36864
	v_mfma_f32_32x32x16_bf16 v[18:33], v[74:77], v[66:69], v[18:33]
	ds_read_b128 v[74:77], v86 offset:49152
	ds_read_b128 v[86:89], v86 offset:53248
	v_mfma_f32_32x32x16_bf16 v[2:17], v[70:73], v[66:69], v[2:17]
	s_waitcnt vmcnt(0) lgkmcnt(0)
	s_barrier
	s_waitcnt lgkmcnt(0)
	v_mfma_f32_32x32x16_bf16 v[50:65], v[74:77], v[78:81], v[50:65]
	v_mov_b32_e32 v70, v226
	v_add_u32_e32 v66, v70, v224
	v_add_u32_e32 v70, v70, v225
	v_mfma_f32_32x32x16_bf16 v[34:49], v[86:89], v[78:81], v[34:49]
	ds_read_b128 v[78:81], v66
	ds_read_b128 v[66:69], v66 offset:4096
	s_add_u32 m0, s52, 0x8000
	s_nop 0
	global_load_lds_dwordx4 v220, s[98:99]
	s_add_u32 m0, s52, 0x9000
	s_nop 0
	global_load_lds_dwordx4 v221, s[98:99]
	v_mfma_f32_32x32x16_bf16 v[18:33], v[74:77], v[82:85], v[18:33]
	ds_read_b128 v[74:77], v70 offset:16384
	ds_read_b128 v[70:73], v70 offset:20480
	s_add_u32 m0, s52, 0xa000
	s_nop 0
	global_load_lds_dwordx4 v222, s[98:99]
	s_add_u32 m0, s52, 0xb000
	s_nop 0
	global_load_lds_dwordx4 v223, s[98:99]
	v_mfma_f32_32x32x16_bf16 v[2:17], v[86:89], v[82:85], v[2:17]
	s_add_u32 m0, s52, 0xc000
	s_nop 0
	global_load_lds_dwordx4 v220, s[100:101]
	s_add_u32 m0, s52, 0xd000
	s_nop 0
	global_load_lds_dwordx4 v221, s[100:101]
	s_add_u32 m0, s52, 0xe000
	s_nop 0
	global_load_lds_dwordx4 v222, s[100:101]
	s_add_u32 m0, s52, 0xf000
	s_nop 0
	global_load_lds_dwordx4 v223, s[100:101]
	s_add_u32 s98, s98, 0x80
	s_addc_u32 s99, s99, 0
	s_add_u32 s100, s100, 0x80
	s_addc_u32 s101, s101, 0
	s_sub_u32 s51, s51, 1
	s_cmp_lg_u32 s51, 0
	s_cbranch_scc1 .Lp4f_b0_loop
	s_waitcnt lgkmcnt(0)
	v_mfma_f32_32x32x16_bf16 v[50:65], v[74:77], v[78:81], v[50:65]
	v_xor_b32_e32 v86, 0x20, v226
	v_add_u32_e32 v82, v86, v224
	v_add_u32_e32 v86, v86, v225
	v_mfma_f32_32x32x16_bf16 v[34:49], v[70:73], v[78:81], v[34:49]
	ds_read_b128 v[78:81], v82
	ds_read_b128 v[82:85], v82 offset:4096
	v_mfma_f32_32x32x16_bf16 v[18:33], v[74:77], v[66:69], v[18:33]
	ds_read_b128 v[74:77], v86 offset:16384
	ds_read_b128 v[86:89], v86 offset:20480
	v_mfma_f32_32x32x16_bf16 v[2:17], v[70:73], v[66:69], v[2:17]
	s_waitcnt lgkmcnt(0)
	v_mfma_f32_32x32x16_bf16 v[50:65], v[74:77], v[78:81], v[50:65]
	v_xor_b32_e32 v70, 0x40, v226
	v_add_u32_e32 v66, v70, v224
	v_add_u32_e32 v70, v70, v225
	v_mfma_f32_32x32x16_bf16 v[34:49], v[86:89], v[78:81], v[34:49]
	ds_read_b128 v[78:81], v66
	ds_read_b128 v[66:69], v66 offset:4096
	v_mfma_f32_32x32x16_bf16 v[18:33], v[74:77], v[82:85], v[18:33]
	ds_read_b128 v[74:77], v70 offset:16384
	ds_read_b128 v[70:73], v70 offset:20480
	v_mfma_f32_32x32x16_bf16 v[2:17], v[86:89], v[82:85], v[2:17]
	s_waitcnt lgkmcnt(0)
	v_mfma_f32_32x32x16_bf16 v[50:65], v[74:77], v[78:81], v[50:65]
	v_xor_b32_e32 v86, 0x60, v226
	v_add_u32_e32 v82, v86, v224
	v_add_u32_e32 v86, v86, v225
	v_mfma_f32_32x32x16_bf16 v[34:49], v[70:73], v[78:81], v[34:49]
	ds_read_b128 v[78:81], v82
	ds_read_b128 v[82:85], v82 offset:4096
	v_mfma_f32_32x32x16_bf16 v[18:33], v[74:77], v[66:69], v[18:33]
	ds_read_b128 v[74:77], v86 offset:16384
	ds_read_b128 v[86:89], v86 offset:20480
	v_mfma_f32_32x32x16_bf16 v[2:17], v[70:73], v[66:69], v[2:17]
	s_waitcnt vmcnt(0) lgkmcnt(0)
	s_barrier
	s_waitcnt lgkmcnt(0)
	v_mfma_f32_32x32x16_bf16 v[50:65], v[74:77], v[78:81], v[50:65]
	v_mov_b32_e32 v70, v226
	v_add_u32_e32 v66, v70, v224
	v_add_u32_e32 v70, v70, v225
	v_mfma_f32_32x32x16_bf16 v[34:49], v[86:89], v[78:81], v[34:49]
	ds_read_b128 v[78:81], v66 offset:32768
	ds_read_b128 v[66:69], v66 offset:36864
	v_mfma_f32_32x32x16_bf16 v[18:33], v[74:77], v[82:85], v[18:33]
	ds_read_b128 v[74:77], v70 offset:49152
	ds_read_b128 v[70:73], v70 offset:53248
	v_mfma_f32_32x32x16_bf16 v[2:17], v[86:89], v[82:85], v[2:17]
	s_waitcnt lgkmcnt(0)
	v_mfma_f32_32x32x16_bf16 v[50:65], v[74:77], v[78:81], v[50:65]
	v_xor_b32_e32 v86, 0x20, v226
	v_add_u32_e32 v82, v86, v224
	v_add_u32_e32 v86, v86, v225
	v_mfma_f32_32x32x16_bf16 v[34:49], v[70:73], v[78:81], v[34:49]
	ds_read_b128 v[78:81], v82 offset:32768
	ds_read_b128 v[82:85], v82 offset:36864
	v_mfma_f32_32x32x16_bf16 v[18:33], v[74:77], v[66:69], v[18:33]
	ds_read_b128 v[74:77], v86 offset:49152
	ds_read_b128 v[86:89], v86 offset:53248
	v_mfma_f32_32x32x16_bf16 v[2:17], v[70:73], v[66:69], v[2:17]
	s_waitcnt lgkmcnt(0)
	v_mfma_f32_32x32x16_bf16 v[50:65], v[74:77], v[78:81], v[50:65]
	v_xor_b32_e32 v70, 0x40, v226
	v_add_u32_e32 v66, v70, v224
	v_add_u32_e32 v70, v70, v225
	v_mfma_f32_32x32x16_bf16 v[34:49], v[86:89], v[78:81], v[34:49]
	ds_read_b128 v[78:81], v66 offset:32768
	ds_read_b128 v[66:69], v66 offset:36864
	v_mfma_f32_32x32x16_bf16 v[18:33], v[74:77], v[82:85], v[18:33]
	ds_read_b128 v[74:77], v70 offset:49152
	ds_read_b128 v[70:73], v70 offset:53248
	v_mfma_f32_32x32x16_bf16 v[2:17], v[86:89], v[82:85], v[2:17]
	s_waitcnt lgkmcnt(0)
	v_mfma_f32_32x32x16_bf16 v[50:65], v[74:77], v[78:81], v[50:65]
	v_xor_b32_e32 v86, 0x60, v226
	v_add_u32_e32 v82, v86, v224
	v_add_u32_e32 v86, v86, v225
	v_mfma_f32_32x32x16_bf16 v[34:49], v[70:73], v[78:81], v[34:49]
	ds_read_b128 v[78:81], v82 offset:32768
	ds_read_b128 v[82:85], v82 offset:36864
	v_mfma_f32_32x32x16_bf16 v[18:33], v[74:77], v[66:69], v[18:33]
	ds_read_b128 v[74:77], v86 offset:49152
	ds_read_b128 v[86:89], v86 offset:53248
	v_mfma_f32_32x32x16_bf16 v[2:17], v[70:73], v[66:69], v[2:17]
	s_waitcnt lgkmcnt(0)
	v_mfma_f32_32x32x16_bf16 v[50:65], v[74:77], v[78:81], v[50:65]
	v_mfma_f32_32x32x16_bf16 v[34:49], v[86:89], v[78:81], v[34:49]
	v_mfma_f32_32x32x16_bf16 v[18:33], v[74:77], v[82:85], v[18:33]
	v_mfma_f32_32x32x16_bf16 v[2:17], v[86:89], v[82:85], v[2:17]
	s_nop 15
	v_lshlrev_b32_e32 v66, 16, v98
	v_and_b32_e32 v67, 0xffff0000, v98
	v_mul_f32_e32 v227, v2, v66
	v_mul_f32_e32 v228, v3, v67
	v_lshlrev_b32_e32 v66, 16, v99
	v_and_b32_e32 v67, 0xffff0000, v99
	v_mul_f32_e32 v229, v4, v66
	v_mul_f32_e32 v230, v5, v67
	v_lshlrev_b32_e32 v66, 16, v100
	v_and_b32_e32 v67, 0xffff0000, v100
	v_mul_f32_e32 v231, v6, v66
	v_mul_f32_e32 v232, v7, v67
	v_lshlrev_b32_e32 v66, 16, v101
	v_and_b32_e32 v67, 0xffff0000, v101
	v_mul_f32_e32 v233, v8, v66
	v_mul_f32_e32 v234, v9, v67
	v_lshlrev_b32_e32 v66, 16, v102
	v_and_b32_e32 v67, 0xffff0000, v102
	v_mul_f32_e32 v235, v10, v66
	v_mul_f32_e32 v236, v11, v67
	v_lshlrev_b32_e32 v66, 16, v103
	v_and_b32_e32 v67, 0xffff0000, v103
	v_mul_f32_e32 v237, v12, v66
	v_mul_f32_e32 v238, v13, v67
	v_lshlrev_b32_e32 v66, 16, v104
	v_and_b32_e32 v67, 0xffff0000, v104
	v_mul_f32_e32 v239, v14, v66
	v_mul_f32_e32 v240, v15, v67
	v_lshlrev_b32_e32 v66, 16, v105
	v_and_b32_e32 v67, 0xffff0000, v105
	v_mul_f32_e32 v241, v16, v66
	v_mul_f32_e32 v242, v17, v67
	v_lshlrev_b32_e32 v66, 16, v106
	v_and_b32_e32 v67, 0xffff0000, v106
	v_mul_f32_e32 v243, v18, v66
	v_mul_f32_e32 v244, v19, v67
	v_lshlrev_b32_e32 v66, 16, v107
	v_and_b32_e32 v67, 0xffff0000, v107
	v_mul_f32_e32 v245, v20, v66
	v_mul_f32_e32 v246, v21, v67
	v_lshlrev_b32_e32 v66, 16, v108
	v_and_b32_e32 v67, 0xffff0000, v108
	v_mul_f32_e32 v247, v22, v66
	v_mul_f32_e32 v248, v23, v67
	v_lshlrev_b32_e32 v66, 16, v109
	v_and_b32_e32 v67, 0xffff0000, v109
	v_mul_f32_e32 v249, v24, v66
	v_mul_f32_e32 v250, v25, v67
	v_lshlrev_b32_e32 v66, 16, v110
	v_and_b32_e32 v67, 0xffff0000, v110
	v_mul_f32_e32 v251, v26, v66
	v_mul_f32_e32 v90, v27, v67
	v_lshlrev_b32_e32 v66, 16, v111
	v_and_b32_e32 v67, 0xffff0000, v111
	v_mul_f32_e32 v91, v28, v66
	v_mul_f32_e32 v92, v29, v67
	v_lshlrev_b32_e32 v66, 16, v112
	v_and_b32_e32 v67, 0xffff0000, v112
	v_mul_f32_e32 v93, v30, v66
	v_mul_f32_e32 v94, v31, v67
	v_lshlrev_b32_e32 v66, 16, v113
	v_and_b32_e32 v67, 0xffff0000, v113
	v_mul_f32_e32 v95, v32, v66
	v_mul_f32_e32 v96, v33, v67
	v_lshlrev_b32_e32 v66, 16, v114
	v_and_b32_e32 v67, 0xffff0000, v114
	v_mul_f32_e32 v98, v34, v66
	v_mul_f32_e32 v99, v35, v67
	v_lshlrev_b32_e32 v66, 16, v115
	v_and_b32_e32 v67, 0xffff0000, v115
	v_mul_f32_e32 v100, v36, v66
	v_mul_f32_e32 v101, v37, v67
	v_lshlrev_b32_e32 v66, 16, v116
	v_and_b32_e32 v67, 0xffff0000, v116
	v_mul_f32_e32 v102, v38, v66
	v_mul_f32_e32 v103, v39, v67
	v_lshlrev_b32_e32 v66, 16, v117
	v_and_b32_e32 v67, 0xffff0000, v117
	v_mul_f32_e32 v104, v40, v66
	v_mul_f32_e32 v105, v41, v67
	v_lshlrev_b32_e32 v66, 16, v118
	v_and_b32_e32 v67, 0xffff0000, v118
	v_mul_f32_e32 v106, v42, v66
	v_mul_f32_e32 v107, v43, v67
	v_lshlrev_b32_e32 v66, 16, v119
	v_and_b32_e32 v67, 0xffff0000, v119
	v_mul_f32_e32 v108, v44, v66
	v_mul_f32_e32 v109, v45, v67
	v_lshlrev_b32_e32 v66, 16, v120
	v_and_b32_e32 v67, 0xffff0000, v120
	v_mul_f32_e32 v110, v46, v66
	v_mul_f32_e32 v111, v47, v67
	v_lshlrev_b32_e32 v66, 16, v121
	v_and_b32_e32 v67, 0xffff0000, v121
	v_mul_f32_e32 v112, v48, v66
	v_mul_f32_e32 v113, v49, v67
	v_lshlrev_b32_e32 v66, 16, v122
	v_and_b32_e32 v67, 0xffff0000, v122
	v_mul_f32_e32 v114, v50, v66
	v_mul_f32_e32 v115, v51, v67
	v_lshlrev_b32_e32 v66, 16, v123
	v_and_b32_e32 v67, 0xffff0000, v123
	v_mul_f32_e32 v116, v52, v66
	v_mul_f32_e32 v117, v53, v67
	v_lshlrev_b32_e32 v66, 16, v124
	v_and_b32_e32 v67, 0xffff0000, v124
	v_mul_f32_e32 v118, v54, v66
	v_mul_f32_e32 v119, v55, v67
	v_lshlrev_b32_e32 v66, 16, v125
	v_and_b32_e32 v67, 0xffff0000, v125
	v_mul_f32_e32 v120, v56, v66
	v_mul_f32_e32 v121, v57, v67
	v_lshlrev_b32_e32 v66, 16, v126
	v_and_b32_e32 v67, 0xffff0000, v126
	v_mul_f32_e32 v122, v58, v66
	v_mul_f32_e32 v123, v59, v67
	v_lshlrev_b32_e32 v66, 16, v127
	v_and_b32_e32 v67, 0xffff0000, v127
	v_mul_f32_e32 v124, v60, v66
	v_mul_f32_e32 v125, v61, v67
	v_lshlrev_b32_e32 v66, 16, v128
	v_and_b32_e32 v67, 0xffff0000, v128
	v_mul_f32_e32 v126, v62, v66
	v_mul_f32_e32 v127, v63, v67
	v_lshlrev_b32_e32 v66, 16, v129
	v_and_b32_e32 v67, 0xffff0000, v129
	v_mul_f32_e32 v128, v64, v66
	v_mul_f32_e32 v129, v65, v67
	s_add_u32 s98, s48, 0x300
	s_addc_u32 s99, s49, 0
	s_add_u32 s100, s44, 0x300
	s_addc_u32 s101, s45, 0
	s_mov_b32 s51, 1
	v_mov_b32_e32 v12, v199
	v_lshrrev_b32_e32 v2, 3, v12
	v_and_b32_e32 v3, 7, v12
	v_bfe_u32 v4, v12, 4, 3
	v_xor_b32_e32 v3, v3, v4
	v_lshlrev_b32_e32 v3, 4, v3
	v_mul_u32_u24_e32 v2, 0x700, v2
	v_add_u32_e32 v220, v2, v3
	v_add_u32_e32 v221, 0xe000, v220
	v_add_u32_e32 v222, 0x1c000, v220
	v_add_u32_e32 v223, 0x2a000, v220
	v_lshlrev_b32_e32 v4, 4, v12
	v_and_b32_e32 v5, 31, v12
	v_bfe_u32 v6, v12, 5, 1
	v_bfe_u32 v7, v12, 1, 3
	v_xor_b32_e32 v6, v6, v7
	v_lshlrev_b32_e32 v226, 4, v6
	v_lshlrev_b32_e32 v5, 7, v5
	v_bfe_u32 v8, v12, 7, 1
	v_bfe_u32 v9, v12, 6, 1
	v_lshl_or_b32 v224, v8, 13, v5
	v_lshl_or_b32 v225, v9, 13, v5
	v_readfirstlane_b32 s52, v4
	s_waitcnt vmcnt(0)
	s_barrier
	s_add_u32 m0, s52, 0x0
	v_mov_b32_e32 v2, 0
	global_load_lds_dwordx4 v220, s[98:99]
	s_add_u32 m0, s52, 0x1000
	v_mov_b32_e32 v3, 0
	global_load_lds_dwordx4 v221, s[98:99]
	s_add_u32 m0, s52, 0x2000
	v_mov_b32_e32 v4, 0
	global_load_lds_dwordx4 v222, s[98:99]
	s_add_u32 m0, s52, 0x3000
	v_mov_b32_e32 v5, 0
	global_load_lds_dwordx4 v223, s[98:99]
	s_add_u32 m0, s52, 0x4000
	v_mov_b32_e32 v6, 0
	global_load_lds_dwordx4 v220, s[100:101]
	s_add_u32 m0, s52, 0x5000
	v_mov_b32_e32 v7, 0
	global_load_lds_dwordx4 v221, s[100:101]
	s_add_u32 m0, s52, 0x6000
	v_mov_b32_e32 v8, 0
	global_load_lds_dwordx4 v222, s[100:101]
	s_add_u32 m0, s52, 0x7000
	v_mov_b32_e32 v9, 0
	global_load_lds_dwordx4 v223, s[100:101]
	s_add_u32 s98, s98, 0x80
	s_addc_u32 s99, s99, 0
	s_add_u32 s100, s100, 0x80
	s_addc_u32 s101, s101, 0
	s_add_u32 m0, s52, 0x8000
	v_mov_b32_e32 v10, 0
	global_load_lds_dwordx4 v220, s[98:99]
	s_add_u32 m0, s52, 0x9000
	v_mov_b32_e32 v11, 0
	global_load_lds_dwordx4 v221, s[98:99]
	s_add_u32 m0, s52, 0xa000
	v_mov_b32_e32 v12, 0
	global_load_lds_dwordx4 v222, s[98:99]
	s_add_u32 m0, s52, 0xb000
	v_mov_b32_e32 v13, 0
	global_load_lds_dwordx4 v223, s[98:99]
	s_add_u32 m0, s52, 0xc000
	v_mov_b32_e32 v14, 0
	global_load_lds_dwordx4 v220, s[100:101]
	s_add_u32 m0, s52, 0xd000
	v_mov_b32_e32 v15, 0
	global_load_lds_dwordx4 v221, s[100:101]
	s_add_u32 m0, s52, 0xe000
	v_mov_b32_e32 v16, 0
	global_load_lds_dwordx4 v222, s[100:101]
	s_add_u32 m0, s52, 0xf000
	v_mov_b32_e32 v17, 0
	global_load_lds_dwordx4 v223, s[100:101]
	s_add_u32 s98, s98, 0x80
	s_addc_u32 s99, s99, 0
	s_add_u32 s100, s100, 0x80
	s_addc_u32 s101, s101, 0
	v_mov_b32_e32 v18, 0
	v_mov_b32_e32 v19, 0
	v_mov_b32_e32 v20, 0
	v_mov_b32_e32 v21, 0
	v_mov_b32_e32 v22, 0
	v_mov_b32_e32 v23, 0
	v_mov_b32_e32 v24, 0
	v_mov_b32_e32 v25, 0
	v_mov_b32_e32 v26, 0
	v_mov_b32_e32 v27, 0
	v_mov_b32_e32 v28, 0
	v_mov_b32_e32 v29, 0
	v_mov_b32_e32 v30, 0
	v_mov_b32_e32 v31, 0
	v_mov_b32_e32 v32, 0
	v_mov_b32_e32 v33, 0
	v_mov_b32_e32 v34, 0
	v_mov_b32_e32 v35, 0
	v_mov_b32_e32 v36, 0
	v_mov_b32_e32 v37, 0
	v_mov_b32_e32 v38, 0
	v_mov_b32_e32 v39, 0
	v_mov_b32_e32 v40, 0
	v_mov_b32_e32 v41, 0
	v_mov_b32_e32 v42, 0
	v_mov_b32_e32 v43, 0
	v_mov_b32_e32 v44, 0
	v_mov_b32_e32 v45, 0
	v_mov_b32_e32 v46, 0
	v_mov_b32_e32 v47, 0
	v_mov_b32_e32 v48, 0
	v_mov_b32_e32 v49, 0
	v_mov_b32_e32 v50, 0
	v_mov_b32_e32 v51, 0
	v_mov_b32_e32 v52, 0
	v_mov_b32_e32 v53, 0
	v_mov_b32_e32 v54, 0
	v_mov_b32_e32 v55, 0
	v_mov_b32_e32 v56, 0
	v_mov_b32_e32 v57, 0
	v_mov_b32_e32 v58, 0
	v_mov_b32_e32 v59, 0
	v_mov_b32_e32 v60, 0
	v_mov_b32_e32 v61, 0
	v_mov_b32_e32 v62, 0
	v_mov_b32_e32 v63, 0
	v_mov_b32_e32 v64, 0
	v_mov_b32_e32 v65, 0
	s_waitcnt vmcnt(8)
	s_barrier
	v_add_u32_e32 v66, v226, v224
	v_add_u32_e32 v70, v226, v225
	ds_read_b128 v[78:81], v66
	ds_read_b128 v[66:69], v66 offset:4096
	ds_read_b128 v[74:77], v70 offset:16384
	ds_read_b128 v[70:73], v70 offset:20480
.Lp4f_b1_loop:
	s_waitcnt lgkmcnt(0)
	v_mfma_f32_32x32x16_bf16 v[50:65], v[74:77], v[78:81], v[50:65]
	v_xor_b32_e32 v86, 0x20, v226
	v_add_u32_e32 v82, v86, v224
	v_add_u32_e32 v86, v86, v225
	v_mfma_f32_32x32x16_bf16 v[34:49], v[70:73], v[78:81], v[34:49]
	ds_read_b128 v[78:81], v82
	ds_read_b128 v[82:85], v82 offset:4096
	v_mfma_f32_32x32x16_bf16 v[18:33], v[74:77], v[66:69], v[18:33]
	ds_read_b128 v[74:77], v86 offset:16384
	ds_read_b128 v[86:89], v86 offset:20480
	v_mfma_f32_32x32x16_bf16 v[2:17], v[70:73], v[66:69], v[2:17]
	s_waitcnt lgkmcnt(0)
	v_mfma_f32_32x32x16_bf16 v[50:65], v[74:77], v[78:81], v[50:65]
	v_xor_b32_e32 v70, 0x40, v226
	v_add_u32_e32 v66, v70, v224
	v_add_u32_e32 v70, v70, v225
	v_mfma_f32_32x32x16_bf16 v[34:49], v[86:89], v[78:81], v[34:49]
	ds_read_b128 v[78:81], v66
	ds_read_b128 v[66:69], v66 offset:4096
	v_mfma_f32_32x32x16_bf16 v[18:33], v[74:77], v[82:85], v[18:33]
	ds_read_b128 v[74:77], v70 offset:16384
	ds_read_b128 v[70:73], v70 offset:20480
	v_mfma_f32_32x32x16_bf16 v[2:17], v[86:89], v[82:85], v[2:17]
	s_waitcnt lgkmcnt(0)
	v_mfma_f32_32x32x16_bf16 v[50:65], v[74:77], v[78:81], v[50:65]
	v_xor_b32_e32 v86, 0x60, v226
	v_add_u32_e32 v82, v86, v224
	v_add_u32_e32 v86, v86, v225
	v_mfma_f32_32x32x16_bf16 v[34:49], v[70:73], v[78:81], v[34:49]
	ds_read_b128 v[78:81], v82
	ds_read_b128 v[82:85], v82 offset:4096
	v_mfma_f32_32x32x16_bf16 v[18:33], v[74:77], v[66:69], v[18:33]
	ds_read_b128 v[74:77], v86 offset:16384
	ds_read_b128 v[86:89], v86 offset:20480
	v_mfma_f32_32x32x16_bf16 v[2:17], v[70:73], v[66:69], v[2:17]
	s_waitcnt vmcnt(0) lgkmcnt(0)
	s_barrier
	s_waitcnt lgkmcnt(0)
	v_mfma_f32_32x32x16_bf16 v[50:65], v[74:77], v[78:81], v[50:65]
	v_mov_b32_e32 v70, v226
	v_add_u32_e32 v66, v70, v224
	v_add_u32_e32 v70, v70, v225
	v_mfma_f32_32x32x16_bf16 v[34:49], v[86:89], v[78:81], v[34:49]
	ds_read_b128 v[78:81], v66 offset:32768
	ds_read_b128 v[66:69], v66 offset:36864
	s_add_u32 m0, s52, 0x0
	s_nop 0
	global_load_lds_dwordx4 v220, s[98:99]
	s_add_u32 m0, s52, 0x1000
	s_nop 0
	global_load_lds_dwordx4 v221, s[98:99]
	v_mfma_f32_32x32x16_bf16 v[18:33], v[74:77], v[82:85], v[18:33]
	ds_read_b128 v[74:77], v70 offset:49152
	ds_read_b128 v[70:73], v70 offset:53248
	s_add_u32 m0, s52, 0x2000
	s_nop 0
	global_load_lds_dwordx4 v222, s[98:99]
	s_add_u32 m0, s52, 0x3000
	s_nop 0
	global_load_lds_dwordx4 v223, s[98:99]
	v_mfma_f32_32x32x16_bf16 v[2:17], v[86:89], v[82:85], v[2:17]
	s_add_u32 m0, s52, 0x4000
	s_nop 0
	global_load_lds_dwordx4 v220, s[100:101]
	s_add_u32 m0, s52, 0x5000
	s_nop 0
	global_load_lds_dwordx4 v221, s[100:101]
	s_add_u32 m0, s52, 0x6000
	s_nop 0
	global_load_lds_dwordx4 v222, s[100:101]
	s_add_u32 m0, s52, 0x7000
	s_nop 0
	global_load_lds_dwordx4 v223, s[100:101]
	s_add_u32 s98, s98, 0x80
	s_addc_u32 s99, s99, 0
	s_add_u32 s100, s100, 0x80
	s_addc_u32 s101, s101, 0
	s_waitcnt lgkmcnt(0)
	v_mfma_f32_32x32x16_bf16 v[50:65], v[74:77], v[78:81], v[50:65]
	v_xor_b32_e32 v86, 0x20, v226
	v_add_u32_e32 v82, v86, v224
	v_add_u32_e32 v86, v86, v225
	v_mfma_f32_32x32x16_bf16 v[34:49], v[70:73], v[78:81], v[34:49]
	ds_read_b128 v[78:81], v82 offset:32768
	ds_read_b128 v[82:85], v82 offset:36864
	v_mfma_f32_32x32x16_bf16 v[18:33], v[74:77], v[66:69], v[18:33]
	ds_read_b128 v[74:77], v86 offset:49152
	ds_read_b128 v[86:89], v86 offset:53248
	v_mfma_f32_32x32x16_bf16 v[2:17], v[70:73], v[66:69], v[2:17]
	s_waitcnt lgkmcnt(0)
	v_mfma_f32_32x32x16_bf16 v[50:65], v[74:77], v[78:81], v[50:65]
	v_xor_b32_e32 v70, 0x40, v226
	v_add_u32_e32 v66, v70, v224
	v_add_u32_e32 v70, v70, v225
	v_mfma_f32_32x32x16_bf16 v[34:49], v[86:89], v[78:81], v[34:49]
	ds_read_b128 v[78:81], v66 offset:32768
	ds_read_b128 v[66:69], v66 offset:36864
	v_mfma_f32_32x32x16_bf16 v[18:33], v[74:77], v[82:85], v[18:33]
	ds_read_b128 v[74:77], v70 offset:49152
	ds_read_b128 v[70:73], v70 offset:53248
	v_mfma_f32_32x32x16_bf16 v[2:17], v[86:89], v[82:85], v[2:17]
	s_waitcnt lgkmcnt(0)
	v_mfma_f32_32x32x16_bf16 v[50:65], v[74:77], v[78:81], v[50:65]
	v_xor_b32_e32 v86, 0x60, v226
	v_add_u32_e32 v82, v86, v224
	v_add_u32_e32 v86, v86, v225
	v_mfma_f32_32x32x16_bf16 v[34:49], v[70:73], v[78:81], v[34:49]
	ds_read_b128 v[78:81], v82 offset:32768
	ds_read_b128 v[82:85], v82 offset:36864
	v_mfma_f32_32x32x16_bf16 v[18:33], v[74:77], v[66:69], v[18:33]
	ds_read_b128 v[74:77], v86 offset:49152
	ds_read_b128 v[86:89], v86 offset:53248
	v_mfma_f32_32x32x16_bf16 v[2:17], v[70:73], v[66:69], v[2:17]
	s_waitcnt vmcnt(0) lgkmcnt(0)
	s_barrier
	s_waitcnt lgkmcnt(0)
	v_mfma_f32_32x32x16_bf16 v[50:65], v[74:77], v[78:81], v[50:65]
	v_mov_b32_e32 v70, v226
	v_add_u32_e32 v66, v70, v224
	v_add_u32_e32 v70, v70, v225
	v_mfma_f32_32x32x16_bf16 v[34:49], v[86:89], v[78:81], v[34:49]
	ds_read_b128 v[78:81], v66
	ds_read_b128 v[66:69], v66 offset:4096
	s_add_u32 m0, s52, 0x8000
	s_nop 0
	global_load_lds_dwordx4 v220, s[98:99]
	s_add_u32 m0, s52, 0x9000
	s_nop 0
	global_load_lds_dwordx4 v221, s[98:99]
	v_mfma_f32_32x32x16_bf16 v[18:33], v[74:77], v[82:85], v[18:33]
	ds_read_b128 v[74:77], v70 offset:16384
	ds_read_b128 v[70:73], v70 offset:20480
	s_add_u32 m0, s52, 0xa000
	s_nop 0
	global_load_lds_dwordx4 v222, s[98:99]
	s_add_u32 m0, s52, 0xb000
	s_nop 0
	global_load_lds_dwordx4 v223, s[98:99]
	v_mfma_f32_32x32x16_bf16 v[2:17], v[86:89], v[82:85], v[2:17]
	s_add_u32 m0, s52, 0xc000
	s_nop 0
	global_load_lds_dwordx4 v220, s[100:101]
	s_add_u32 m0, s52, 0xd000
	s_nop 0
	global_load_lds_dwordx4 v221, s[100:101]
	s_add_u32 m0, s52, 0xe000
	s_nop 0
	global_load_lds_dwordx4 v222, s[100:101]
	s_add_u32 m0, s52, 0xf000
	s_nop 0
	global_load_lds_dwordx4 v223, s[100:101]
	s_add_u32 s98, s98, 0x80
	s_addc_u32 s99, s99, 0
	s_add_u32 s100, s100, 0x80
	s_addc_u32 s101, s101, 0
	s_sub_u32 s51, s51, 1
	s_cmp_lg_u32 s51, 0
	s_cbranch_scc1 .Lp4f_b1_loop
	s_waitcnt lgkmcnt(0)
	v_mfma_f32_32x32x16_bf16 v[50:65], v[74:77], v[78:81], v[50:65]
	v_xor_b32_e32 v86, 0x20, v226
	v_add_u32_e32 v82, v86, v224
	v_add_u32_e32 v86, v86, v225
	v_mfma_f32_32x32x16_bf16 v[34:49], v[70:73], v[78:81], v[34:49]
	ds_read_b128 v[78:81], v82
	ds_read_b128 v[82:85], v82 offset:4096
	v_mfma_f32_32x32x16_bf16 v[18:33], v[74:77], v[66:69], v[18:33]
	ds_read_b128 v[74:77], v86 offset:16384
	ds_read_b128 v[86:89], v86 offset:20480
	v_mfma_f32_32x32x16_bf16 v[2:17], v[70:73], v[66:69], v[2:17]
	s_waitcnt lgkmcnt(0)
	v_mfma_f32_32x32x16_bf16 v[50:65], v[74:77], v[78:81], v[50:65]
	v_xor_b32_e32 v70, 0x40, v226
	v_add_u32_e32 v66, v70, v224
	v_add_u32_e32 v70, v70, v225
	v_mfma_f32_32x32x16_bf16 v[34:49], v[86:89], v[78:81], v[34:49]
	ds_read_b128 v[78:81], v66
	ds_read_b128 v[66:69], v66 offset:4096
	v_mfma_f32_32x32x16_bf16 v[18:33], v[74:77], v[82:85], v[18:33]
	ds_read_b128 v[74:77], v70 offset:16384
	ds_read_b128 v[70:73], v70 offset:20480
	v_mfma_f32_32x32x16_bf16 v[2:17], v[86:89], v[82:85], v[2:17]
	s_waitcnt lgkmcnt(0)
	v_mfma_f32_32x32x16_bf16 v[50:65], v[74:77], v[78:81], v[50:65]
	v_xor_b32_e32 v86, 0x60, v226
	v_add_u32_e32 v82, v86, v224
	v_add_u32_e32 v86, v86, v225
	v_mfma_f32_32x32x16_bf16 v[34:49], v[70:73], v[78:81], v[34:49]
	ds_read_b128 v[78:81], v82
	ds_read_b128 v[82:85], v82 offset:4096
	v_mfma_f32_32x32x16_bf16 v[18:33], v[74:77], v[66:69], v[18:33]
	ds_read_b128 v[74:77], v86 offset:16384
	ds_read_b128 v[86:89], v86 offset:20480
	v_mfma_f32_32x32x16_bf16 v[2:17], v[70:73], v[66:69], v[2:17]
	s_waitcnt vmcnt(0) lgkmcnt(0)
	s_barrier
	s_waitcnt lgkmcnt(0)
	v_mfma_f32_32x32x16_bf16 v[50:65], v[74:77], v[78:81], v[50:65]
	v_mov_b32_e32 v70, v226
	v_add_u32_e32 v66, v70, v224
	v_add_u32_e32 v70, v70, v225
	v_mfma_f32_32x32x16_bf16 v[34:49], v[86:89], v[78:81], v[34:49]
	ds_read_b128 v[78:81], v66 offset:32768
	ds_read_b128 v[66:69], v66 offset:36864
	v_mfma_f32_32x32x16_bf16 v[18:33], v[74:77], v[82:85], v[18:33]
	ds_read_b128 v[74:77], v70 offset:49152
	ds_read_b128 v[70:73], v70 offset:53248
	v_mfma_f32_32x32x16_bf16 v[2:17], v[86:89], v[82:85], v[2:17]
	s_waitcnt lgkmcnt(0)
	v_mfma_f32_32x32x16_bf16 v[50:65], v[74:77], v[78:81], v[50:65]
	v_xor_b32_e32 v86, 0x20, v226
	v_add_u32_e32 v82, v86, v224
	v_add_u32_e32 v86, v86, v225
	v_mfma_f32_32x32x16_bf16 v[34:49], v[70:73], v[78:81], v[34:49]
	ds_read_b128 v[78:81], v82 offset:32768
	ds_read_b128 v[82:85], v82 offset:36864
	v_mfma_f32_32x32x16_bf16 v[18:33], v[74:77], v[66:69], v[18:33]
	ds_read_b128 v[74:77], v86 offset:49152
	ds_read_b128 v[86:89], v86 offset:53248
	v_mfma_f32_32x32x16_bf16 v[2:17], v[70:73], v[66:69], v[2:17]
	s_waitcnt lgkmcnt(0)
	v_mfma_f32_32x32x16_bf16 v[50:65], v[74:77], v[78:81], v[50:65]
	v_xor_b32_e32 v70, 0x40, v226
	v_add_u32_e32 v66, v70, v224
	v_add_u32_e32 v70, v70, v225
	v_mfma_f32_32x32x16_bf16 v[34:49], v[86:89], v[78:81], v[34:49]
	ds_read_b128 v[78:81], v66 offset:32768
	ds_read_b128 v[66:69], v66 offset:36864
	v_mfma_f32_32x32x16_bf16 v[18:33], v[74:77], v[82:85], v[18:33]
	ds_read_b128 v[74:77], v70 offset:49152
	ds_read_b128 v[70:73], v70 offset:53248
	v_mfma_f32_32x32x16_bf16 v[2:17], v[86:89], v[82:85], v[2:17]
	s_waitcnt lgkmcnt(0)
	v_mfma_f32_32x32x16_bf16 v[50:65], v[74:77], v[78:81], v[50:65]
	v_xor_b32_e32 v86, 0x60, v226
	v_add_u32_e32 v82, v86, v224
	v_add_u32_e32 v86, v86, v225
	v_mfma_f32_32x32x16_bf16 v[34:49], v[70:73], v[78:81], v[34:49]
	ds_read_b128 v[78:81], v82 offset:32768
	ds_read_b128 v[82:85], v82 offset:36864
	v_mfma_f32_32x32x16_bf16 v[18:33], v[74:77], v[66:69], v[18:33]
	ds_read_b128 v[74:77], v86 offset:49152
	ds_read_b128 v[86:89], v86 offset:53248
	v_mfma_f32_32x32x16_bf16 v[2:17], v[70:73], v[66:69], v[2:17]
	s_waitcnt lgkmcnt(0)
	v_mfma_f32_32x32x16_bf16 v[50:65], v[74:77], v[78:81], v[50:65]
	v_mfma_f32_32x32x16_bf16 v[34:49], v[86:89], v[78:81], v[34:49]
	v_mfma_f32_32x32x16_bf16 v[18:33], v[74:77], v[82:85], v[18:33]
	v_mfma_f32_32x32x16_bf16 v[2:17], v[86:89], v[82:85], v[2:17]
	s_nop 15
	v_lshlrev_b32_e32 v66, 16, v130
	v_and_b32_e32 v67, 0xffff0000, v130
	v_fmac_f32_e32 v227, v2, v66
	v_fmac_f32_e32 v228, v3, v67
	v_lshlrev_b32_e32 v66, 16, v131
	v_and_b32_e32 v67, 0xffff0000, v131
	v_fmac_f32_e32 v229, v4, v66
	v_fmac_f32_e32 v230, v5, v67
	v_lshlrev_b32_e32 v66, 16, v132
	v_and_b32_e32 v67, 0xffff0000, v132
	v_fmac_f32_e32 v231, v6, v66
	v_fmac_f32_e32 v232, v7, v67
	v_lshlrev_b32_e32 v66, 16, v133
	v_and_b32_e32 v67, 0xffff0000, v133
	v_fmac_f32_e32 v233, v8, v66
	v_fmac_f32_e32 v234, v9, v67
	v_lshlrev_b32_e32 v66, 16, v134
	v_and_b32_e32 v67, 0xffff0000, v134
	v_fmac_f32_e32 v235, v10, v66
	v_fmac_f32_e32 v236, v11, v67
	v_lshlrev_b32_e32 v66, 16, v135
	v_and_b32_e32 v67, 0xffff0000, v135
	v_fmac_f32_e32 v237, v12, v66
	v_fmac_f32_e32 v238, v13, v67
	v_lshlrev_b32_e32 v66, 16, v136
	v_and_b32_e32 v67, 0xffff0000, v136
	v_fmac_f32_e32 v239, v14, v66
	v_fmac_f32_e32 v240, v15, v67
	v_lshlrev_b32_e32 v66, 16, v137
	v_and_b32_e32 v67, 0xffff0000, v137
	v_fmac_f32_e32 v241, v16, v66
	v_fmac_f32_e32 v242, v17, v67
	v_lshlrev_b32_e32 v66, 16, v138
	v_and_b32_e32 v67, 0xffff0000, v138
	v_fmac_f32_e32 v243, v18, v66
	v_fmac_f32_e32 v244, v19, v67
	v_lshlrev_b32_e32 v66, 16, v139
	v_and_b32_e32 v67, 0xffff0000, v139
	v_fmac_f32_e32 v245, v20, v66
	v_fmac_f32_e32 v246, v21, v67
	v_lshlrev_b32_e32 v66, 16, v140
	v_and_b32_e32 v67, 0xffff0000, v140
	v_fmac_f32_e32 v247, v22, v66
	v_fmac_f32_e32 v248, v23, v67
	v_lshlrev_b32_e32 v66, 16, v141
	v_and_b32_e32 v67, 0xffff0000, v141
	v_fmac_f32_e32 v249, v24, v66
	v_fmac_f32_e32 v250, v25, v67
	v_lshlrev_b32_e32 v66, 16, v142
	v_and_b32_e32 v67, 0xffff0000, v142
	v_fmac_f32_e32 v251, v26, v66
	v_fmac_f32_e32 v90, v27, v67
	v_lshlrev_b32_e32 v66, 16, v143
	v_and_b32_e32 v67, 0xffff0000, v143
	v_fmac_f32_e32 v91, v28, v66
	v_fmac_f32_e32 v92, v29, v67
	v_lshlrev_b32_e32 v66, 16, v144
	v_and_b32_e32 v67, 0xffff0000, v144
	v_fmac_f32_e32 v93, v30, v66
	v_fmac_f32_e32 v94, v31, v67
	v_lshlrev_b32_e32 v66, 16, v145
	v_and_b32_e32 v67, 0xffff0000, v145
	v_fmac_f32_e32 v95, v32, v66
	v_fmac_f32_e32 v96, v33, v67
	v_lshlrev_b32_e32 v66, 16, v146
	v_and_b32_e32 v67, 0xffff0000, v146
	v_fmac_f32_e32 v98, v34, v66
	v_fmac_f32_e32 v99, v35, v67
	v_lshlrev_b32_e32 v66, 16, v147
	v_and_b32_e32 v67, 0xffff0000, v147
	v_fmac_f32_e32 v100, v36, v66
	v_fmac_f32_e32 v101, v37, v67
	v_lshlrev_b32_e32 v66, 16, v148
	v_and_b32_e32 v67, 0xffff0000, v148
	v_fmac_f32_e32 v102, v38, v66
	v_fmac_f32_e32 v103, v39, v67
	v_lshlrev_b32_e32 v66, 16, v149
	v_and_b32_e32 v67, 0xffff0000, v149
	v_fmac_f32_e32 v104, v40, v66
	v_fmac_f32_e32 v105, v41, v67
	v_lshlrev_b32_e32 v66, 16, v150
	v_and_b32_e32 v67, 0xffff0000, v150
	v_fmac_f32_e32 v106, v42, v66
	v_fmac_f32_e32 v107, v43, v67
	v_lshlrev_b32_e32 v66, 16, v151
	v_and_b32_e32 v67, 0xffff0000, v151
	v_fmac_f32_e32 v108, v44, v66
	v_fmac_f32_e32 v109, v45, v67
	v_lshlrev_b32_e32 v66, 16, v152
	v_and_b32_e32 v67, 0xffff0000, v152
	v_fmac_f32_e32 v110, v46, v66
	v_fmac_f32_e32 v111, v47, v67
	v_lshlrev_b32_e32 v66, 16, v153
	v_and_b32_e32 v67, 0xffff0000, v153
	v_fmac_f32_e32 v112, v48, v66
	v_fmac_f32_e32 v113, v49, v67
	v_lshlrev_b32_e32 v66, 16, v154
	v_and_b32_e32 v67, 0xffff0000, v154
	v_fmac_f32_e32 v114, v50, v66
	v_fmac_f32_e32 v115, v51, v67
	v_lshlrev_b32_e32 v66, 16, v155
	v_and_b32_e32 v67, 0xffff0000, v155
	v_fmac_f32_e32 v116, v52, v66
	v_fmac_f32_e32 v117, v53, v67
	v_lshlrev_b32_e32 v66, 16, v156
	v_and_b32_e32 v67, 0xffff0000, v156
	v_fmac_f32_e32 v118, v54, v66
	v_fmac_f32_e32 v119, v55, v67
	v_lshlrev_b32_e32 v66, 16, v157
	v_and_b32_e32 v67, 0xffff0000, v157
	v_fmac_f32_e32 v120, v56, v66
	v_fmac_f32_e32 v121, v57, v67
	v_lshlrev_b32_e32 v66, 16, v158
	v_and_b32_e32 v67, 0xffff0000, v158
	v_fmac_f32_e32 v122, v58, v66
	v_fmac_f32_e32 v123, v59, v67
	v_lshlrev_b32_e32 v66, 16, v159
	v_and_b32_e32 v67, 0xffff0000, v159
	v_fmac_f32_e32 v124, v60, v66
	v_fmac_f32_e32 v125, v61, v67
	v_lshlrev_b32_e32 v66, 16, v160
	v_and_b32_e32 v67, 0xffff0000, v160
	v_fmac_f32_e32 v126, v62, v66
	v_fmac_f32_e32 v127, v63, v67
	v_lshlrev_b32_e32 v66, 16, v161
	v_and_b32_e32 v67, 0xffff0000, v161
	v_fmac_f32_e32 v128, v64, v66
	v_fmac_f32_e32 v129, v65, v67
	s_add_u32 s98, s48, 0x500
	s_addc_u32 s99, s49, 0
	s_add_u32 s100, s44, 0x500
	s_addc_u32 s101, s45, 0
	s_mov_b32 s51, 1
	v_mov_b32_e32 v12, v199
	v_lshrrev_b32_e32 v2, 3, v12
	v_and_b32_e32 v3, 7, v12
	v_bfe_u32 v4, v12, 4, 3
	v_xor_b32_e32 v3, v3, v4
	v_lshlrev_b32_e32 v3, 4, v3
	v_mul_u32_u24_e32 v2, 0x700, v2
	v_add_u32_e32 v220, v2, v3
	v_add_u32_e32 v221, 0xe000, v220
	v_add_u32_e32 v222, 0x1c000, v220
	v_add_u32_e32 v223, 0x2a000, v220
	v_lshlrev_b32_e32 v4, 4, v12
	v_and_b32_e32 v5, 31, v12
	v_bfe_u32 v6, v12, 5, 1
	v_bfe_u32 v7, v12, 1, 3
	v_xor_b32_e32 v6, v6, v7
	v_lshlrev_b32_e32 v226, 4, v6
	v_lshlrev_b32_e32 v5, 7, v5
	v_bfe_u32 v8, v12, 7, 1
	v_bfe_u32 v9, v12, 6, 1
	v_lshl_or_b32 v224, v8, 13, v5
	v_lshl_or_b32 v225, v9, 13, v5
	v_readfirstlane_b32 s52, v4
	s_waitcnt vmcnt(0)
	s_barrier
	s_add_u32 m0, s52, 0x0
	v_mov_b32_e32 v2, 0
	global_load_lds_dwordx4 v220, s[98:99]
	s_add_u32 m0, s52, 0x1000
	v_mov_b32_e32 v3, 0
	global_load_lds_dwordx4 v221, s[98:99]
	s_add_u32 m0, s52, 0x2000
	v_mov_b32_e32 v4, 0
	global_load_lds_dwordx4 v222, s[98:99]
	s_add_u32 m0, s52, 0x3000
	v_mov_b32_e32 v5, 0
	global_load_lds_dwordx4 v223, s[98:99]
	s_add_u32 m0, s52, 0x4000
	v_mov_b32_e32 v6, 0
	global_load_lds_dwordx4 v220, s[100:101]
	s_add_u32 m0, s52, 0x5000
	v_mov_b32_e32 v7, 0
	global_load_lds_dwordx4 v221, s[100:101]
	s_add_u32 m0, s52, 0x6000
	v_mov_b32_e32 v8, 0
	global_load_lds_dwordx4 v222, s[100:101]
	s_add_u32 m0, s52, 0x7000
	v_mov_b32_e32 v9, 0
	global_load_lds_dwordx4 v223, s[100:101]
	s_add_u32 s98, s98, 0x80
	s_addc_u32 s99, s99, 0
	s_add_u32 s100, s100, 0x80
	s_addc_u32 s101, s101, 0
	s_add_u32 m0, s52, 0x8000
	v_mov_b32_e32 v10, 0
	global_load_lds_dwordx4 v220, s[98:99]
	s_add_u32 m0, s52, 0x9000
	v_mov_b32_e32 v11, 0
	global_load_lds_dwordx4 v221, s[98:99]
	s_add_u32 m0, s52, 0xa000
	v_mov_b32_e32 v12, 0
	global_load_lds_dwordx4 v222, s[98:99]
	s_add_u32 m0, s52, 0xb000
	v_mov_b32_e32 v13, 0
	global_load_lds_dwordx4 v223, s[98:99]
	s_add_u32 m0, s52, 0xc000
	v_mov_b32_e32 v14, 0
	global_load_lds_dwordx4 v220, s[100:101]
	s_add_u32 m0, s52, 0xd000
	v_mov_b32_e32 v15, 0
	global_load_lds_dwordx4 v221, s[100:101]
	s_add_u32 m0, s52, 0xe000
	v_mov_b32_e32 v16, 0
	global_load_lds_dwordx4 v222, s[100:101]
	s_add_u32 m0, s52, 0xf000
	v_mov_b32_e32 v17, 0
	global_load_lds_dwordx4 v223, s[100:101]
	s_add_u32 s98, s98, 0x80
	s_addc_u32 s99, s99, 0
	s_add_u32 s100, s100, 0x80
	s_addc_u32 s101, s101, 0
	v_mov_b32_e32 v18, 0
	v_mov_b32_e32 v19, 0
	v_mov_b32_e32 v20, 0
	v_mov_b32_e32 v21, 0
	v_mov_b32_e32 v22, 0
	v_mov_b32_e32 v23, 0
	v_mov_b32_e32 v24, 0
	v_mov_b32_e32 v25, 0
	v_mov_b32_e32 v26, 0
	v_mov_b32_e32 v27, 0
	v_mov_b32_e32 v28, 0
	v_mov_b32_e32 v29, 0
	v_mov_b32_e32 v30, 0
	v_mov_b32_e32 v31, 0
	v_mov_b32_e32 v32, 0
	v_mov_b32_e32 v33, 0
	v_mov_b32_e32 v34, 0
	v_mov_b32_e32 v35, 0
	v_mov_b32_e32 v36, 0
	v_mov_b32_e32 v37, 0
	v_mov_b32_e32 v38, 0
	v_mov_b32_e32 v39, 0
	v_mov_b32_e32 v40, 0
	v_mov_b32_e32 v41, 0
	v_mov_b32_e32 v42, 0
	v_mov_b32_e32 v43, 0
	v_mov_b32_e32 v44, 0
	v_mov_b32_e32 v45, 0
	v_mov_b32_e32 v46, 0
	v_mov_b32_e32 v47, 0
	v_mov_b32_e32 v48, 0
	v_mov_b32_e32 v49, 0
	v_mov_b32_e32 v50, 0
	v_mov_b32_e32 v51, 0
	v_mov_b32_e32 v52, 0
	v_mov_b32_e32 v53, 0
	v_mov_b32_e32 v54, 0
	v_mov_b32_e32 v55, 0
	v_mov_b32_e32 v56, 0
	v_mov_b32_e32 v57, 0
	v_mov_b32_e32 v58, 0
	v_mov_b32_e32 v59, 0
	v_mov_b32_e32 v60, 0
	v_mov_b32_e32 v61, 0
	v_mov_b32_e32 v62, 0
	v_mov_b32_e32 v63, 0
	v_mov_b32_e32 v64, 0
	v_mov_b32_e32 v65, 0
	s_waitcnt vmcnt(8)
	s_barrier
	v_add_u32_e32 v66, v226, v224
	v_add_u32_e32 v70, v226, v225
	ds_read_b128 v[78:81], v66
	ds_read_b128 v[66:69], v66 offset:4096
	ds_read_b128 v[74:77], v70 offset:16384
	ds_read_b128 v[70:73], v70 offset:20480
.Lp4f_b2_loop:
	s_waitcnt lgkmcnt(0)
	v_mfma_f32_32x32x16_bf16 v[50:65], v[74:77], v[78:81], v[50:65]
	v_xor_b32_e32 v86, 0x20, v226
	v_add_u32_e32 v82, v86, v224
	v_add_u32_e32 v86, v86, v225
	v_mfma_f32_32x32x16_bf16 v[34:49], v[70:73], v[78:81], v[34:49]
	ds_read_b128 v[78:81], v82
	ds_read_b128 v[82:85], v82 offset:4096
	v_mfma_f32_32x32x16_bf16 v[18:33], v[74:77], v[66:69], v[18:33]
	ds_read_b128 v[74:77], v86 offset:16384
	ds_read_b128 v[86:89], v86 offset:20480
	v_mfma_f32_32x32x16_bf16 v[2:17], v[70:73], v[66:69], v[2:17]
	s_waitcnt lgkmcnt(0)
	v_mfma_f32_32x32x16_bf16 v[50:65], v[74:77], v[78:81], v[50:65]
	v_xor_b32_e32 v70, 0x40, v226
	v_add_u32_e32 v66, v70, v224
	v_add_u32_e32 v70, v70, v225
	v_mfma_f32_32x32x16_bf16 v[34:49], v[86:89], v[78:81], v[34:49]
	ds_read_b128 v[78:81], v66
	ds_read_b128 v[66:69], v66 offset:4096
	v_mfma_f32_32x32x16_bf16 v[18:33], v[74:77], v[82:85], v[18:33]
	ds_read_b128 v[74:77], v70 offset:16384
	ds_read_b128 v[70:73], v70 offset:20480
	v_mfma_f32_32x32x16_bf16 v[2:17], v[86:89], v[82:85], v[2:17]
	s_waitcnt lgkmcnt(0)
	v_mfma_f32_32x32x16_bf16 v[50:65], v[74:77], v[78:81], v[50:65]
	v_xor_b32_e32 v86, 0x60, v226
	v_add_u32_e32 v82, v86, v224
	v_add_u32_e32 v86, v86, v225
	v_mfma_f32_32x32x16_bf16 v[34:49], v[70:73], v[78:81], v[34:49]
	ds_read_b128 v[78:81], v82
	ds_read_b128 v[82:85], v82 offset:4096
	v_mfma_f32_32x32x16_bf16 v[18:33], v[74:77], v[66:69], v[18:33]
	ds_read_b128 v[74:77], v86 offset:16384
	ds_read_b128 v[86:89], v86 offset:20480
	v_mfma_f32_32x32x16_bf16 v[2:17], v[70:73], v[66:69], v[2:17]
	s_waitcnt vmcnt(0) lgkmcnt(0)
	s_barrier
	s_waitcnt lgkmcnt(0)
	v_mfma_f32_32x32x16_bf16 v[50:65], v[74:77], v[78:81], v[50:65]
	v_mov_b32_e32 v70, v226
	v_add_u32_e32 v66, v70, v224
	v_add_u32_e32 v70, v70, v225
	v_mfma_f32_32x32x16_bf16 v[34:49], v[86:89], v[78:81], v[34:49]
	ds_read_b128 v[78:81], v66 offset:32768
	ds_read_b128 v[66:69], v66 offset:36864
	s_add_u32 m0, s52, 0x0
	s_nop 0
	global_load_lds_dwordx4 v220, s[98:99]
	s_add_u32 m0, s52, 0x1000
	s_nop 0
	global_load_lds_dwordx4 v221, s[98:99]
	v_mfma_f32_32x32x16_bf16 v[18:33], v[74:77], v[82:85], v[18:33]
	ds_read_b128 v[74:77], v70 offset:49152
	ds_read_b128 v[70:73], v70 offset:53248
	s_add_u32 m0, s52, 0x2000
	s_nop 0
	global_load_lds_dwordx4 v222, s[98:99]
	s_add_u32 m0, s52, 0x3000
	s_nop 0
	global_load_lds_dwordx4 v223, s[98:99]
	v_mfma_f32_32x32x16_bf16 v[2:17], v[86:89], v[82:85], v[2:17]
	s_add_u32 m0, s52, 0x4000
	s_nop 0
	global_load_lds_dwordx4 v220, s[100:101]
	s_add_u32 m0, s52, 0x5000
	s_nop 0
	global_load_lds_dwordx4 v221, s[100:101]
	s_add_u32 m0, s52, 0x6000
	s_nop 0
	global_load_lds_dwordx4 v222, s[100:101]
	s_add_u32 m0, s52, 0x7000
	s_nop 0
	global_load_lds_dwordx4 v223, s[100:101]
	s_add_u32 s98, s98, 0x80
	s_addc_u32 s99, s99, 0
	s_add_u32 s100, s100, 0x80
	s_addc_u32 s101, s101, 0
	s_waitcnt lgkmcnt(0)
	v_mfma_f32_32x32x16_bf16 v[50:65], v[74:77], v[78:81], v[50:65]
	v_xor_b32_e32 v86, 0x20, v226
	v_add_u32_e32 v82, v86, v224
	v_add_u32_e32 v86, v86, v225
	v_mfma_f32_32x32x16_bf16 v[34:49], v[70:73], v[78:81], v[34:49]
	ds_read_b128 v[78:81], v82 offset:32768
	ds_read_b128 v[82:85], v82 offset:36864
	v_mfma_f32_32x32x16_bf16 v[18:33], v[74:77], v[66:69], v[18:33]
	ds_read_b128 v[74:77], v86 offset:49152
	ds_read_b128 v[86:89], v86 offset:53248
	v_mfma_f32_32x32x16_bf16 v[2:17], v[70:73], v[66:69], v[2:17]
	s_waitcnt lgkmcnt(0)
	v_mfma_f32_32x32x16_bf16 v[50:65], v[74:77], v[78:81], v[50:65]
	v_xor_b32_e32 v70, 0x40, v226
	v_add_u32_e32 v66, v70, v224
	v_add_u32_e32 v70, v70, v225
	v_mfma_f32_32x32x16_bf16 v[34:49], v[86:89], v[78:81], v[34:49]
	ds_read_b128 v[78:81], v66 offset:32768
	ds_read_b128 v[66:69], v66 offset:36864
	v_mfma_f32_32x32x16_bf16 v[18:33], v[74:77], v[82:85], v[18:33]
	ds_read_b128 v[74:77], v70 offset:49152
	ds_read_b128 v[70:73], v70 offset:53248
	v_mfma_f32_32x32x16_bf16 v[2:17], v[86:89], v[82:85], v[2:17]
	s_waitcnt lgkmcnt(0)
	v_mfma_f32_32x32x16_bf16 v[50:65], v[74:77], v[78:81], v[50:65]
	v_xor_b32_e32 v86, 0x60, v226
	v_add_u32_e32 v82, v86, v224
	v_add_u32_e32 v86, v86, v225
	v_mfma_f32_32x32x16_bf16 v[34:49], v[70:73], v[78:81], v[34:49]
	ds_read_b128 v[78:81], v82 offset:32768
	ds_read_b128 v[82:85], v82 offset:36864
	v_mfma_f32_32x32x16_bf16 v[18:33], v[74:77], v[66:69], v[18:33]
	ds_read_b128 v[74:77], v86 offset:49152
	ds_read_b128 v[86:89], v86 offset:53248
	v_mfma_f32_32x32x16_bf16 v[2:17], v[70:73], v[66:69], v[2:17]
	s_waitcnt vmcnt(0) lgkmcnt(0)
	s_barrier
	s_waitcnt lgkmcnt(0)
	v_mfma_f32_32x32x16_bf16 v[50:65], v[74:77], v[78:81], v[50:65]
	v_mov_b32_e32 v70, v226
	v_add_u32_e32 v66, v70, v224
	v_add_u32_e32 v70, v70, v225
	v_mfma_f32_32x32x16_bf16 v[34:49], v[86:89], v[78:81], v[34:49]
	ds_read_b128 v[78:81], v66
	ds_read_b128 v[66:69], v66 offset:4096
	s_add_u32 m0, s52, 0x8000
	s_nop 0
	global_load_lds_dwordx4 v220, s[98:99]
	s_add_u32 m0, s52, 0x9000
	s_nop 0
	global_load_lds_dwordx4 v221, s[98:99]
	v_mfma_f32_32x32x16_bf16 v[18:33], v[74:77], v[82:85], v[18:33]
	ds_read_b128 v[74:77], v70 offset:16384
	ds_read_b128 v[70:73], v70 offset:20480
	s_add_u32 m0, s52, 0xa000
	s_nop 0
	global_load_lds_dwordx4 v222, s[98:99]
	s_add_u32 m0, s52, 0xb000
	s_nop 0
	global_load_lds_dwordx4 v223, s[98:99]
	v_mfma_f32_32x32x16_bf16 v[2:17], v[86:89], v[82:85], v[2:17]
	s_add_u32 m0, s52, 0xc000
	s_nop 0
	global_load_lds_dwordx4 v220, s[100:101]
	s_add_u32 m0, s52, 0xd000
	s_nop 0
	global_load_lds_dwordx4 v221, s[100:101]
	s_add_u32 m0, s52, 0xe000
	s_nop 0
	global_load_lds_dwordx4 v222, s[100:101]
	s_add_u32 m0, s52, 0xf000
	s_nop 0
	global_load_lds_dwordx4 v223, s[100:101]
	s_add_u32 s98, s98, 0x80
	s_addc_u32 s99, s99, 0
	s_add_u32 s100, s100, 0x80
	s_addc_u32 s101, s101, 0
	s_sub_u32 s51, s51, 1
	s_cmp_lg_u32 s51, 0
	s_cbranch_scc1 .Lp4f_b2_loop
	s_waitcnt lgkmcnt(0)
	v_mfma_f32_32x32x16_bf16 v[50:65], v[74:77], v[78:81], v[50:65]
	v_xor_b32_e32 v86, 0x20, v226
	v_add_u32_e32 v82, v86, v224
	v_add_u32_e32 v86, v86, v225
	v_mfma_f32_32x32x16_bf16 v[34:49], v[70:73], v[78:81], v[34:49]
	ds_read_b128 v[78:81], v82
	ds_read_b128 v[82:85], v82 offset:4096
	v_mfma_f32_32x32x16_bf16 v[18:33], v[74:77], v[66:69], v[18:33]
	ds_read_b128 v[74:77], v86 offset:16384
	ds_read_b128 v[86:89], v86 offset:20480
	v_mfma_f32_32x32x16_bf16 v[2:17], v[70:73], v[66:69], v[2:17]
	s_waitcnt lgkmcnt(0)
	v_mfma_f32_32x32x16_bf16 v[50:65], v[74:77], v[78:81], v[50:65]
	v_xor_b32_e32 v70, 0x40, v226
	v_add_u32_e32 v66, v70, v224
	v_add_u32_e32 v70, v70, v225
	v_mfma_f32_32x32x16_bf16 v[34:49], v[86:89], v[78:81], v[34:49]
	ds_read_b128 v[78:81], v66
	ds_read_b128 v[66:69], v66 offset:4096
	v_mfma_f32_32x32x16_bf16 v[18:33], v[74:77], v[82:85], v[18:33]
	ds_read_b128 v[74:77], v70 offset:16384
	ds_read_b128 v[70:73], v70 offset:20480
	v_mfma_f32_32x32x16_bf16 v[2:17], v[86:89], v[82:85], v[2:17]
	s_waitcnt lgkmcnt(0)
	v_mfma_f32_32x32x16_bf16 v[50:65], v[74:77], v[78:81], v[50:65]
	v_xor_b32_e32 v86, 0x60, v226
	v_add_u32_e32 v82, v86, v224
	v_add_u32_e32 v86, v86, v225
	v_mfma_f32_32x32x16_bf16 v[34:49], v[70:73], v[78:81], v[34:49]
	ds_read_b128 v[78:81], v82
	ds_read_b128 v[82:85], v82 offset:4096
	v_mfma_f32_32x32x16_bf16 v[18:33], v[74:77], v[66:69], v[18:33]
	ds_read_b128 v[74:77], v86 offset:16384
	ds_read_b128 v[86:89], v86 offset:20480
	v_mfma_f32_32x32x16_bf16 v[2:17], v[70:73], v[66:69], v[2:17]
	s_waitcnt vmcnt(0) lgkmcnt(0)
	s_barrier
	s_waitcnt lgkmcnt(0)
	v_mfma_f32_32x32x16_bf16 v[50:65], v[74:77], v[78:81], v[50:65]
	v_mov_b32_e32 v70, v226
	v_add_u32_e32 v66, v70, v224
	v_add_u32_e32 v70, v70, v225
	v_mfma_f32_32x32x16_bf16 v[34:49], v[86:89], v[78:81], v[34:49]
	ds_read_b128 v[78:81], v66 offset:32768
	ds_read_b128 v[66:69], v66 offset:36864
	v_mfma_f32_32x32x16_bf16 v[18:33], v[74:77], v[82:85], v[18:33]
	ds_read_b128 v[74:77], v70 offset:49152
	ds_read_b128 v[70:73], v70 offset:53248
	v_mfma_f32_32x32x16_bf16 v[2:17], v[86:89], v[82:85], v[2:17]
	s_waitcnt lgkmcnt(0)
	v_mfma_f32_32x32x16_bf16 v[50:65], v[74:77], v[78:81], v[50:65]
	v_xor_b32_e32 v86, 0x20, v226
	v_add_u32_e32 v82, v86, v224
	v_add_u32_e32 v86, v86, v225
	v_mfma_f32_32x32x16_bf16 v[34:49], v[70:73], v[78:81], v[34:49]
	ds_read_b128 v[78:81], v82 offset:32768
	ds_read_b128 v[82:85], v82 offset:36864
	v_mfma_f32_32x32x16_bf16 v[18:33], v[74:77], v[66:69], v[18:33]
	ds_read_b128 v[74:77], v86 offset:49152
	ds_read_b128 v[86:89], v86 offset:53248
	v_mfma_f32_32x32x16_bf16 v[2:17], v[70:73], v[66:69], v[2:17]
	s_waitcnt lgkmcnt(0)
	v_mfma_f32_32x32x16_bf16 v[50:65], v[74:77], v[78:81], v[50:65]
	v_xor_b32_e32 v70, 0x40, v226
	v_add_u32_e32 v66, v70, v224
	v_add_u32_e32 v70, v70, v225
	v_mfma_f32_32x32x16_bf16 v[34:49], v[86:89], v[78:81], v[34:49]
	ds_read_b128 v[78:81], v66 offset:32768
	ds_read_b128 v[66:69], v66 offset:36864
	v_mfma_f32_32x32x16_bf16 v[18:33], v[74:77], v[82:85], v[18:33]
	ds_read_b128 v[74:77], v70 offset:49152
	ds_read_b128 v[70:73], v70 offset:53248
	v_mfma_f32_32x32x16_bf16 v[2:17], v[86:89], v[82:85], v[2:17]
	s_waitcnt lgkmcnt(0)
	v_mfma_f32_32x32x16_bf16 v[50:65], v[74:77], v[78:81], v[50:65]
	v_xor_b32_e32 v86, 0x60, v226
	v_add_u32_e32 v82, v86, v224
	v_add_u32_e32 v86, v86, v225
	v_mfma_f32_32x32x16_bf16 v[34:49], v[70:73], v[78:81], v[34:49]
	ds_read_b128 v[78:81], v82 offset:32768
	ds_read_b128 v[82:85], v82 offset:36864
	v_mfma_f32_32x32x16_bf16 v[18:33], v[74:77], v[66:69], v[18:33]
	ds_read_b128 v[74:77], v86 offset:49152
	ds_read_b128 v[86:89], v86 offset:53248
	v_mfma_f32_32x32x16_bf16 v[2:17], v[70:73], v[66:69], v[2:17]
	s_waitcnt lgkmcnt(0)
	v_mfma_f32_32x32x16_bf16 v[50:65], v[74:77], v[78:81], v[50:65]
	v_mfma_f32_32x32x16_bf16 v[34:49], v[86:89], v[78:81], v[34:49]
	v_mfma_f32_32x32x16_bf16 v[18:33], v[74:77], v[82:85], v[18:33]
	v_mfma_f32_32x32x16_bf16 v[2:17], v[86:89], v[82:85], v[2:17]
	s_nop 15
	v_lshlrev_b32_e32 v66, 16, v162
	v_and_b32_e32 v67, 0xffff0000, v162
	v_fma_f32 v2, v2, v66, v227
	v_fma_f32 v3, v3, v67, v228
	v_lshlrev_b32_e32 v66, 16, v163
	v_and_b32_e32 v67, 0xffff0000, v163
	v_fma_f32 v4, v4, v66, v229
	v_fma_f32 v5, v5, v67, v230
	v_lshlrev_b32_e32 v66, 16, v164
	v_and_b32_e32 v67, 0xffff0000, v164
	v_fma_f32 v6, v6, v66, v231
	v_fma_f32 v7, v7, v67, v232
	v_lshlrev_b32_e32 v66, 16, v165
	v_and_b32_e32 v67, 0xffff0000, v165
	v_fma_f32 v8, v8, v66, v233
	v_fma_f32 v9, v9, v67, v234
	v_lshlrev_b32_e32 v66, 16, v166
	v_and_b32_e32 v67, 0xffff0000, v166
	v_fma_f32 v10, v10, v66, v235
	v_fma_f32 v11, v11, v67, v236
	v_lshlrev_b32_e32 v66, 16, v167
	v_and_b32_e32 v67, 0xffff0000, v167
	v_fma_f32 v12, v12, v66, v237
	v_fma_f32 v13, v13, v67, v238
	v_lshlrev_b32_e32 v66, 16, v168
	v_and_b32_e32 v67, 0xffff0000, v168
	v_fma_f32 v14, v14, v66, v239
	v_fma_f32 v15, v15, v67, v240
	v_lshlrev_b32_e32 v66, 16, v169
	v_and_b32_e32 v67, 0xffff0000, v169
	v_fma_f32 v16, v16, v66, v241
	v_fma_f32 v17, v17, v67, v242
	v_lshlrev_b32_e32 v66, 16, v170
	v_and_b32_e32 v67, 0xffff0000, v170
	v_fma_f32 v18, v18, v66, v243
	v_fma_f32 v19, v19, v67, v244
	v_lshlrev_b32_e32 v66, 16, v171
	v_and_b32_e32 v67, 0xffff0000, v171
	v_fma_f32 v20, v20, v66, v245
	v_fma_f32 v21, v21, v67, v246
	v_lshlrev_b32_e32 v66, 16, v172
	v_and_b32_e32 v67, 0xffff0000, v172
	v_fma_f32 v22, v22, v66, v247
	v_fma_f32 v23, v23, v67, v248
	v_lshlrev_b32_e32 v66, 16, v173
	v_and_b32_e32 v67, 0xffff0000, v173
	v_fma_f32 v24, v24, v66, v249
	v_fma_f32 v25, v25, v67, v250
	v_lshlrev_b32_e32 v66, 16, v174
	v_and_b32_e32 v67, 0xffff0000, v174
	v_fma_f32 v26, v26, v66, v251
	v_fma_f32 v27, v27, v67, v90
	v_lshlrev_b32_e32 v66, 16, v175
	v_and_b32_e32 v67, 0xffff0000, v175
	v_fma_f32 v28, v28, v66, v91
	v_fma_f32 v29, v29, v67, v92
	v_lshlrev_b32_e32 v66, 16, v176
	v_and_b32_e32 v67, 0xffff0000, v176
	v_fma_f32 v30, v30, v66, v93
	v_fma_f32 v31, v31, v67, v94
	v_lshlrev_b32_e32 v66, 16, v177
	v_and_b32_e32 v67, 0xffff0000, v177
	v_fma_f32 v32, v32, v66, v95
	v_fma_f32 v33, v33, v67, v96
	v_lshlrev_b32_e32 v66, 16, v178
	v_and_b32_e32 v67, 0xffff0000, v178
	v_fma_f32 v34, v34, v66, v98
	v_fma_f32 v35, v35, v67, v99
	v_lshlrev_b32_e32 v66, 16, v179
	v_and_b32_e32 v67, 0xffff0000, v179
	v_fma_f32 v36, v36, v66, v100
	v_fma_f32 v37, v37, v67, v101
	v_lshlrev_b32_e32 v66, 16, v180
	v_and_b32_e32 v67, 0xffff0000, v180
	v_fma_f32 v38, v38, v66, v102
	v_fma_f32 v39, v39, v67, v103
	v_lshlrev_b32_e32 v66, 16, v181
	v_and_b32_e32 v67, 0xffff0000, v181
	v_fma_f32 v40, v40, v66, v104
	v_fma_f32 v41, v41, v67, v105
	v_lshlrev_b32_e32 v66, 16, v182
	v_and_b32_e32 v67, 0xffff0000, v182
	v_fma_f32 v42, v42, v66, v106
	v_fma_f32 v43, v43, v67, v107
	v_lshlrev_b32_e32 v66, 16, v183
	v_and_b32_e32 v67, 0xffff0000, v183
	v_fma_f32 v44, v44, v66, v108
	v_fma_f32 v45, v45, v67, v109
	v_lshlrev_b32_e32 v66, 16, v184
	v_and_b32_e32 v67, 0xffff0000, v184
	v_fma_f32 v46, v46, v66, v110
	v_fma_f32 v47, v47, v67, v111
	v_lshlrev_b32_e32 v66, 16, v185
	v_and_b32_e32 v67, 0xffff0000, v185
	v_fma_f32 v48, v48, v66, v112
	v_fma_f32 v49, v49, v67, v113
	v_lshlrev_b32_e32 v66, 16, v186
	v_and_b32_e32 v67, 0xffff0000, v186
	v_fma_f32 v50, v50, v66, v114
	v_fma_f32 v51, v51, v67, v115
	v_lshlrev_b32_e32 v66, 16, v187
	v_and_b32_e32 v67, 0xffff0000, v187
	v_fma_f32 v52, v52, v66, v116
	v_fma_f32 v53, v53, v67, v117
	v_lshlrev_b32_e32 v66, 16, v188
	v_and_b32_e32 v67, 0xffff0000, v188
	v_fma_f32 v54, v54, v66, v118
	v_fma_f32 v55, v55, v67, v119
	v_lshlrev_b32_e32 v66, 16, v189
	v_and_b32_e32 v67, 0xffff0000, v189
	v_fma_f32 v56, v56, v66, v120
	v_fma_f32 v57, v57, v67, v121
	v_lshlrev_b32_e32 v66, 16, v190
	v_and_b32_e32 v67, 0xffff0000, v190
	v_fma_f32 v58, v58, v66, v122
	v_fma_f32 v59, v59, v67, v123
	v_lshlrev_b32_e32 v66, 16, v191
	v_and_b32_e32 v67, 0xffff0000, v191
	v_fma_f32 v60, v60, v66, v124
	v_fma_f32 v61, v61, v67, v125
	v_lshlrev_b32_e32 v66, 16, v192
	v_and_b32_e32 v67, 0xffff0000, v192
	v_fma_f32 v62, v62, v66, v126
	v_fma_f32 v63, v63, v67, v127
	v_lshlrev_b32_e32 v66, 16, v193
	v_and_b32_e32 v67, 0xffff0000, v193
	v_fma_f32 v64, v64, v66, v128
	v_fma_f32 v65, v65, v67, v129
	v_mov_b32_e32 v114, v2
	v_mov_b32_e32 v112, v3
	v_mov_b32_e32 v115, v4
	v_mov_b32_e32 v113, v5
	v_mov_b32_e32 v110, v6
	v_mov_b32_e32 v108, v7
	v_mov_b32_e32 v111, v8
	v_mov_b32_e32 v109, v9
	v_mov_b32_e32 v104, v10
	v_mov_b32_e32 v102, v11
	v_mov_b32_e32 v105, v12
	v_mov_b32_e32 v103, v13
	v_mov_b32_e32 v98, v14
	v_mov_b32_e32 v100, v15
	v_mov_b32_e32 v99, v16
	v_mov_b32_e32 v101, v17
	v_mov_b32_e32 v130, v18
	v_mov_b32_e32 v128, v19
	v_mov_b32_e32 v131, v20
	v_mov_b32_e32 v129, v21
	v_mov_b32_e32 v126, v22
	v_mov_b32_e32 v124, v23
	v_mov_b32_e32 v127, v24
	v_mov_b32_e32 v125, v25
	v_mov_b32_e32 v120, v26
	v_mov_b32_e32 v118, v27
	v_mov_b32_e32 v121, v28
	v_mov_b32_e32 v119, v29
	v_mov_b32_e32 v106, v30
	v_mov_b32_e32 v116, v31
	v_mov_b32_e32 v107, v32
	v_mov_b32_e32 v117, v33
	v_mov_b32_e32 v146, v34
	v_mov_b32_e32 v144, v35
	v_mov_b32_e32 v147, v36
	v_mov_b32_e32 v145, v37
	v_mov_b32_e32 v142, v38
	v_mov_b32_e32 v140, v39
	v_mov_b32_e32 v143, v40
	v_mov_b32_e32 v141, v41
	v_mov_b32_e32 v136, v42
	v_mov_b32_e32 v134, v43
	v_mov_b32_e32 v137, v44
	v_mov_b32_e32 v135, v45
	v_mov_b32_e32 v122, v46
	v_mov_b32_e32 v132, v47
	v_mov_b32_e32 v123, v48
	v_mov_b32_e32 v133, v49
	v_mov_b32_e32 v160, v50
	v_mov_b32_e32 v158, v51
	v_mov_b32_e32 v161, v52
	v_mov_b32_e32 v159, v53
	v_mov_b32_e32 v156, v54
	v_mov_b32_e32 v154, v55
	v_mov_b32_e32 v157, v56
	v_mov_b32_e32 v155, v57
	v_mov_b32_e32 v152, v58
	v_mov_b32_e32 v150, v59
	v_mov_b32_e32 v153, v60
	v_mov_b32_e32 v151, v61
	v_mov_b32_e32 v138, v62
	v_mov_b32_e32 v148, v63
	v_mov_b32_e32 v139, v64
	v_mov_b32_e32 v149, v65
	s_branch .LBB0_915
